# compress: block-row loads use the default cache policy instead of nt (the two 16-byte halves of each 32-byte sector were fetched twice)
# speedup vs baseline: 1.0056x; 1.0033x over previous
.LBB0_561:
	s_andn2_saveexec_b64 s[0:1], s[0:1]
	v_lshlrev_b32_e32 v2, 6, v1
	v_lshl_or_b32 v6, v177, 13, v2
	v_ashrrev_i32_e32 v7, 31, v6
	v_lshlrev_b64 v[6:7], 12, v[6:7]
	v_lshl_add_u64 v[6:7], s[8:9], 0, v[6:7]
	s_mov_b64 s[8:9], 0x4020000
	v_lshl_add_u64 v[68:69], v[6:7], 0, s[8:9]
	s_or_b64 exec, exec, s[0:1]
	v_ashrrev_i32_e32 v2, 31, v4
	v_lshrrev_b32_e32 v2, 26, v2
	v_add_u32_e32 v76, v4, v2
	v_bfe_i32 v2, v4, 27, 1
	v_lshlrev_b32_e32 v6, 4, v4
	v_lshrrev_b32_e32 v2, 22, v2
	v_add_u32_e32 v2, v6, v2
	v_and_b32_e32 v2, 0xfffffc00, v2
	v_sub_u32_e32 v2, v6, v2
	v_lshrrev_b32_e32 v7, 4, v2
	v_bitop3_b32 v2, v7, v2, 32 bitop3:0x6c
	v_ashrrev_i32_e32 v8, 31, v2
	v_lshrrev_b32_e32 v8, 26, v8
	v_add_u32_e32 v8, v2, v8
	v_ashrrev_i32_e32 v78, 6, v8
	v_and_b32_e32 v8, 0xc0, v8
	v_ashrrev_i32_e32 v77, 6, v76
	v_sub_u32_e32 v2, v2, v8
	v_lshlrev_b32_e32 v7, 3, v77
	v_lshlrev_b32_e32 v9, 5, v77
	v_ashrrev_i16_sdwa v2, v227, sext(v2) dst_sel:DWORD dst_unused:UNUSED_PAD src0_sel:DWORD src1_sel:BYTE_0
	v_and_b32_e32 v7, 0x7fff0, v7
	v_and_b32_e32 v9, 32, v9
	v_bfe_i32 v79, v2, 0, 16
	v_add_u32_e32 v2, v9, v79
	v_add_lshl_u32 v7, v78, v7, 13
	v_add_u32_e32 v6, 0x2000, v6
	v_lshl_add_u32 v2, v2, 1, v7
	v_ashrrev_i32_e32 v7, 31, v6
	v_lshrrev_b32_e32 v7, 22, v7
	v_add_u32_e32 v7, v6, v7
	v_ashrrev_i32_e32 v80, 10, v7
	v_mul_i32_i24_e32 v7, 0x400, v80
	v_sub_u32_e32 v6, v6, v7
	v_lshrrev_b32_e32 v7, 4, v6
	v_bitop3_b32 v6, v7, v6, 32 bitop3:0x6c
	v_ashrrev_i32_e32 v8, 31, v6
	v_lshrrev_b32_e32 v8, 26, v8
	v_add_u32_e32 v8, v6, v8
	v_and_b32_e32 v5, 15, v4
	v_ashrrev_i32_e32 v81, 6, v8
	v_and_b32_e32 v8, 0xc0, v8
	v_sub_u32_e32 v6, v6, v8
	v_lshlrev_b32_e32 v178, 2, v5
	v_and_b32_e32 v204, 3, v4
	v_bfe_u32 v205, v4, 4, 2
	v_lshlrev_b32_e32 v7, 3, v80
	v_lshlrev_b32_e32 v9, 5, v80
	v_ashrrev_i16_sdwa v6, v227, sext(v6) dst_sel:DWORD dst_unused:UNUSED_PAD src0_sel:DWORD src1_sel:BYTE_0
	v_lshlrev_b32_e32 v8, 6, v5
	v_and_b32_e32 v4, 48, v4
	v_and_b32_e32 v5, 32, v178
	v_and_b32_e32 v7, 0x7fff0, v7
	v_and_b32_e32 v9, 32, v9
	v_bfe_i32 v82, v6, 0, 16
	v_bitop3_b32 v181, v8, v5, v4 bitop3:0x36
	s_lshl_b32 s12, s10, 10
	v_mov_b64_e32 v[4:5], 0x9300000
	v_add_u32_e32 v6, v9, v82
	v_add_lshl_u32 v7, v81, v7, 13
	s_add_i32 s11, s12, 0
	v_lshl_add_u64 v[4:5], s[6:7], 0, v[4:5]
	v_lshl_add_u32 v184, v6, 1, v7
	v_lshl_add_u64 v[8:9], v[4:5], 0, v[2:3]
	s_mov_b32 m0, s11
	v_mov_b32_e32 v185, v3
	s_add_i32 s9, s11, 0x2000
	s_barrier
	global_load_lds_dwordx4 v[8:9], off
	v_lshl_add_u64 v[4:5], v[4:5], 0, v[184:185]
	s_mov_b32 m0, s9
	s_add_i32 s8, s11, 0x4000
	global_load_lds_dwordx4 v[4:5], off
	v_mov_b64_e32 v[4:5], 0x9400000
	v_lshl_add_u64 v[4:5], s[6:7], 0, v[4:5]
	v_lshl_add_u64 v[8:9], v[4:5], 0, v[2:3]
	s_mov_b32 m0, s8
	s_add_i32 s10, s11, 0x6000
	global_load_lds_dwordx4 v[8:9], off
	v_lshl_add_u64 v[4:5], v[4:5], 0, v[184:185]
	s_mov_b32 m0, s10
	v_lshlrev_b32_e32 v70, 8, v204
	v_mov_b32_e32 v71, v3
	global_load_lds_dwordx4 v[4:5], off
	v_mov_b64_e32 v[4:5], 0x9300080
	v_lshl_add_u64 v[6:7], v[68:69], 0, v[70:71]
	v_lshlrev_b32_e32 v72, 5, v205
	v_mov_b32_e32 v73, v3
	s_add_i32 s13, s11, 0x8000
	v_lshl_add_u64 v[4:5], s[6:7], 0, v[4:5]
	v_lshl_add_u64 v[182:183], v[6:7], 0, v[72:73]
	v_lshl_add_u64 v[6:7], v[4:5], 0, v[2:3]
	s_mov_b32 m0, s13
	s_add_i32 s14, s11, 0xa000
	global_load_dwordx4 v[44:47], v[182:183], off offset:16
	global_load_dwordx4 v[60:63], v[182:183], off
	global_load_dwordx4 v[56:59], v[182:183], off offset:144
	global_load_dwordx4 v[64:67], v[182:183], off offset:128
	global_load_dwordx4 v[52:55], v[182:183], off offset:1040
	global_load_dwordx4 v[48:51], v[182:183], off offset:1024
	global_load_dwordx4 v[36:39], v[182:183], off offset:1168
	global_load_dwordx4 v[40:43], v[182:183], off offset:1152
	v_lshl_add_u64 v[4:5], v[4:5], 0, v[184:185]
	global_load_lds_dwordx4 v[6:7], off
	s_mov_b32 m0, s14
	s_add_i32 s15, s11, 0xc000
	global_load_lds_dwordx4 v[4:5], off
	v_mov_b64_e32 v[4:5], 0x9400080
	v_lshl_add_u64 v[4:5], s[6:7], 0, v[4:5]
	v_lshl_add_u64 v[6:7], v[4:5], 0, v[2:3]
	s_mov_b32 m0, s15
	s_add_i32 s16, s11, 0xe000
	global_load_lds_dwordx4 v[6:7], off
	v_lshl_add_u64 v[4:5], v[4:5], 0, v[184:185]
	s_mov_b32 m0, s16
	s_mov_b64 s[0:1], 0x1000
	global_load_lds_dwordx4 v[4:5], off
	v_lshl_add_u64 v[4:5], v[182:183], 0, s[0:1]
	s_movk_i32 s0, 0x1000
	v_add_co_u32_e32 v6, vcc, s0, v182
	s_mov_b64 s[0:1], 0x1080
	s_nop 0
	v_addc_co_u32_e32 v7, vcc, 0, v183, vcc
	global_load_dwordx4 v[24:27], v[6:7], off
	global_load_dwordx4 v[12:15], v[4:5], off offset:16
	v_lshl_add_u64 v[4:5], v[182:183], 0, s[0:1]
	s_mov_b64 s[0:1], 0x1400
	v_lshl_add_u64 v[20:21], v[182:183], 0, s[0:1]
	s_mov_b64 s[0:1], 0x1480
	global_load_dwordx4 v[28:31], v[6:7], off offset:128
	global_load_dwordx4 v[16:19], v[6:7], off offset:1024
	v_lshl_add_u64 v[74:75], v[182:183], 0, s[0:1]
	global_load_dwordx4 v[32:35], v[4:5], off offset:16
	global_load_dwordx4 v[8:11], v[6:7], off offset:1152
	s_nop 0
	global_load_dwordx4 v[20:23], v[20:21], off offset:16
	s_nop 0
	global_load_dwordx4 v[4:7], v[74:75], off offset:16
	v_or_b32_e32 v70, v70, v72
	v_lshl_add_u64 v[68:69], v[68:69], 0, v[70:71]
	s_mov_b64 s[0:1], 0xd490
	v_lshl_add_u64 v[186:187], v[68:69], 0, s[0:1]
	v_lshlrev_b32_e32 v68, 16, v77
	v_and_b32_e32 v68, 0xfffe0000, v68
	v_lshl_add_u32 v68, v78, 13, v68
	v_and_or_b32 v68, v76, 64, v68
	v_lshl_add_u32 v188, v79, 1, v68
	v_lshlrev_b32_e32 v68, 16, v80
	v_and_b32_e32 v68, 0xfffe0000, v68
	v_lshl_add_u32 v68, v81, 13, v68
	v_lshlrev_b32_e32 v69, 6, v80
	v_and_or_b32 v68, v69, 64, v68
	v_mov_b32_e32 v100, 0
	v_lshlrev_b32_e32 v176, 6, v204
	v_lshlrev_b32_e32 v206, 3, v205
	v_mov_b32_e32 v189, v3
	v_lshl_add_u32 v190, v82, 1, v68
	v_mov_b32_e32 v191, v3
	s_mov_b32 s17, -12
	s_mov_b64 s[0:1], s[6:7]
	v_mov_b32_e32 v101, v100
	v_mov_b32_e32 v102, v100
	v_mov_b32_e32 v103, v100
	v_mov_b32_e32 v104, v100
	v_mov_b32_e32 v105, v100
	v_mov_b32_e32 v106, v100
	v_mov_b32_e32 v107, v100
	v_mov_b32_e32 v108, v100
	v_mov_b32_e32 v109, v100
	v_mov_b32_e32 v110, v100
	v_mov_b32_e32 v111, v100
	v_mov_b32_e32 v112, v100
	v_mov_b32_e32 v113, v100
	v_mov_b32_e32 v114, v100
	v_mov_b32_e32 v115, v100
	v_mov_b32_e32 v116, v100
	v_mov_b32_e32 v117, v100
	v_mov_b32_e32 v118, v100
	v_mov_b32_e32 v119, v100
	v_mov_b32_e32 v120, v100
	v_mov_b32_e32 v121, v100
	v_mov_b32_e32 v122, v100
	v_mov_b32_e32 v123, v100
	v_mov_b32_e32 v124, v100
	v_mov_b32_e32 v125, v100
	v_mov_b32_e32 v126, v100
	v_mov_b32_e32 v127, v100
	v_mov_b32_e32 v128, v100
	v_mov_b32_e32 v129, v100
	v_mov_b32_e32 v130, v100
	v_mov_b32_e32 v131, v100
	v_mov_b32_e32 v96, v100
	v_mov_b32_e32 v97, v100
	v_mov_b32_e32 v98, v100
	v_mov_b32_e32 v99, v100
	v_mov_b32_e32 v92, v100
	v_mov_b32_e32 v93, v100
	v_mov_b32_e32 v94, v100
	v_mov_b32_e32 v95, v100
	v_mov_b32_e32 v88, v100
	v_mov_b32_e32 v89, v100
	v_mov_b32_e32 v90, v100
	v_mov_b32_e32 v91, v100
	v_mov_b32_e32 v84, v100
	v_mov_b32_e32 v85, v100
	v_mov_b32_e32 v86, v100
	v_mov_b32_e32 v87, v100
	v_mov_b32_e32 v80, v100
	v_mov_b32_e32 v81, v100
	v_mov_b32_e32 v82, v100
	v_mov_b32_e32 v83, v100
	v_mov_b32_e32 v76, v100
	v_mov_b32_e32 v77, v100
	v_mov_b32_e32 v78, v100
	v_mov_b32_e32 v79, v100
	v_mov_b32_e32 v72, v100
	v_mov_b32_e32 v73, v100
	v_mov_b32_e32 v74, v100
	v_mov_b32_e32 v75, v100
	v_mov_b32_e32 v68, v100
	v_mov_b32_e32 v69, v100
	v_mov_b32_e32 v70, v100
	v_mov_b32_e32 v71, v100
	s_mov_b64 s[26:27], 0x9400400
	s_mov_b64 s[28:29], 0x9300480
	s_mov_b64 s[30:31], 0x9400480
	s_mov_b64 s[34:35], 0x9300500
	s_mov_b64 s[36:37], 0x9400500
	s_mov_b64 s[38:39], 0x9300580
	s_mov_b64 s[40:41], 0x9400580
	s_mov_b64 s[44:45], 0x9300600
	s_mov_b64 s[46:47], 0x9400600
	s_mov_b64 s[48:49], 0x9300680
	s_mov_b64 s[50:51], 0x9400680
.LBB0_564:
	s_mov_b32 s24, 0xffff4b70
	s_mov_b32 s25, -1
	v_lshl_add_u64 v[136:137], v[186:187], 0, s[24:25]
	s_mov_b32 s24, 0xffff5000
	s_add_i32 s23, 0, 0x10000
	v_add_co_u32_e32 v144, vcc, s24, v186
	s_mov_b32 s24, 0xffff4bf0
	v_lshl_add_u64 v[192:193], s[0:1], 0, v[188:189]
	s_add_i32 s21, s23, s12
	s_mov_b32 s25, -1
	s_waitcnt vmcnt(12)
	s_barrier
	v_lshl_add_u64 v[132:133], v[192:193], 0, s[84:85]
	s_mov_b32 m0, s21
	v_lshl_add_u64 v[194:195], s[0:1], 0, v[190:191]
	s_add_i32 s20, s21, 0x2000
	s_add_i32 s22, 0, 0x14000
	v_lshl_add_u64 v[146:147], v[186:187], 0, s[24:25]
	s_mov_b32 s24, 0xffff4f70
	global_load_lds_dwordx4 v[132:133], off
	v_lshl_add_u64 v[132:133], v[194:195], 0, s[84:85]
	s_mov_b32 m0, s20
	s_add_i32 s18, s22, s12
	s_mov_b32 s25, -1
	global_load_lds_dwordx4 v[132:133], off
	v_lshl_add_u64 v[132:133], v[192:193], 0, s[86:87]
	s_mov_b32 m0, s18
	s_add_i32 s19, s18, 0x2000
	v_lshl_add_u64 v[152:153], v[186:187], 0, s[24:25]
	s_mov_b32 s24, 0xffff4ff0
	global_load_lds_dwordx4 v[132:133], off
	v_lshl_add_u64 v[132:133], v[194:195], 0, s[86:87]
	s_mov_b32 m0, s19
	s_mov_b32 s25, -1
	global_load_lds_dwordx4 v[132:133], off
	v_addc_co_u32_e32 v145, vcc, -1, v187, vcc
	v_lshl_add_u64 v[154:155], v[186:187], 0, s[24:25]
	global_load_dwordx4 v[132:135], v[144:145], off offset:-1168
	s_nop 0
	global_load_dwordx4 v[136:139], v[136:137], off offset:16
	s_nop 0
	global_load_dwordx4 v[148:151], v[144:145], off offset:-1040
	global_load_dwordx4 v[140:143], v[144:145], off offset:-144
	global_load_dwordx4 v[160:163], v[146:147], off offset:16
	s_nop 0
	global_load_dwordx4 v[144:147], v[144:145], off offset:-16
	s_nop 0
	global_load_dwordx4 v[156:159], v[152:153], off offset:16
	s_nop 0
	global_load_dwordx4 v[152:155], v[154:155], off offset:16
	v_add_u32_e32 v179, 0, v181
	v_cvt_pk_bf16_f32 v60, v60, v61
	v_cvt_pk_bf16_f32 v61, v62, v63
	v_cvt_pk_bf16_f32 v62, v44, v45
	v_cvt_pk_bf16_f32 v63, v46, v47
	v_cvt_pk_bf16_f32 v44, v64, v65
	v_cvt_pk_bf16_f32 v45, v66, v67
	v_cvt_pk_bf16_f32 v46, v56, v57
	v_cvt_pk_bf16_f32 v47, v58, v59
	v_cvt_pk_bf16_f32 v48, v48, v49
	v_cvt_pk_bf16_f32 v49, v50, v51
	v_cvt_pk_bf16_f32 v50, v52, v53
	v_cvt_pk_bf16_f32 v51, v54, v55
	v_cvt_pk_bf16_f32 v40, v40, v41
	v_cvt_pk_bf16_f32 v41, v42, v43
	v_cvt_pk_bf16_f32 v42, v36, v37
	v_cvt_pk_bf16_f32 v43, v38, v39
	ds_read_b128 v[36:39], v179
	ds_read_b128 v[52:55], v179 offset:2048
	s_waitcnt lgkmcnt(0)
	v_mfma_f32_16x16x32_bf16 v[36:39], v[36:39], v[60:63], v[100:103]
	s_nop 2
	ds_read_b128 v[100:103], v179 offset:8192
	ds_read_b128 v[56:59], v179 offset:4096
	ds_read_b128 v[64:67], v179 offset:6144
	v_mfma_f32_16x16x32_bf16 v[52:55], v[52:55], v[60:63], v[104:107]
	s_nop 2
	ds_read_b128 v[104:107], v179 offset:10240
	s_waitcnt lgkmcnt(0)
	v_mfma_f32_16x16x32_bf16 v[116:119], v[100:103], v[60:63], v[116:119]
	ds_read_b128 v[100:103], v179 offset:12288
	v_mfma_f32_16x16x32_bf16 v[120:123], v[104:107], v[60:63], v[120:123]
	ds_read_b128 v[104:107], v179 offset:14336
	v_mfma_f32_16x16x32_bf16 v[56:59], v[56:59], v[60:63], v[108:111]
	v_mfma_f32_16x16x32_bf16 v[64:67], v[64:67], v[60:63], v[112:115]
	s_waitcnt lgkmcnt(0)
	v_mfma_f32_16x16x32_bf16 v[124:127], v[100:103], v[60:63], v[124:127]
	v_mfma_f32_16x16x32_bf16 v[60:63], v[104:107], v[60:63], v[128:131]
	ds_read_b128 v[100:103], v179 offset:1024
	s_waitcnt lgkmcnt(0)
	v_mfma_f32_16x16x32_bf16 v[100:103], v[100:103], v[44:47], v[36:39]
	s_nop 2
	ds_read_b128 v[36:39], v179 offset:3072
	s_waitcnt lgkmcnt(0)
	v_mfma_f32_16x16x32_bf16 v[104:107], v[36:39], v[44:47], v[52:55]
	ds_read_b128 v[36:39], v179 offset:5120
	s_waitcnt lgkmcnt(0)
	v_mfma_f32_16x16x32_bf16 v[108:111], v[36:39], v[44:47], v[56:59]
	ds_read_b128 v[36:39], v179 offset:7168
	s_waitcnt lgkmcnt(0)
	v_mfma_f32_16x16x32_bf16 v[112:115], v[36:39], v[44:47], v[64:67]
	ds_read_b128 v[36:39], v179 offset:9216
	s_waitcnt lgkmcnt(0)
	v_mfma_f32_16x16x32_bf16 v[116:119], v[36:39], v[44:47], v[116:119]
	ds_read_b128 v[36:39], v179 offset:11264
	s_waitcnt lgkmcnt(0)
	v_mfma_f32_16x16x32_bf16 v[120:123], v[36:39], v[44:47], v[120:123]
	ds_read_b128 v[36:39], v179 offset:13312
	s_waitcnt lgkmcnt(0)
	v_mfma_f32_16x16x32_bf16 v[124:127], v[36:39], v[44:47], v[124:127]
	ds_read_b128 v[36:39], v179 offset:15360
	s_waitcnt lgkmcnt(0)
	v_mfma_f32_16x16x32_bf16 v[128:131], v[36:39], v[44:47], v[60:63]
	s_nop 2
	ds_read_b128 v[60:63], v179 offset:24576
	ds_read_b128 v[64:67], v179 offset:26624
	ds_read_b128 v[36:39], v179 offset:16384
	ds_read_b128 v[44:47], v179 offset:18432
	ds_read_b128 v[52:55], v179 offset:20480
	ds_read_b128 v[56:59], v179 offset:22528
	s_waitcnt lgkmcnt(0)
	v_mfma_f32_16x16x32_bf16 v[64:67], v[64:67], v[48:51], v[76:79]
	s_nop 2
	ds_read_b128 v[76:79], v179 offset:28672
	v_mfma_f32_16x16x32_bf16 v[44:47], v[44:47], v[48:51], v[92:95]
	s_waitcnt lgkmcnt(0)
	v_mfma_f32_16x16x32_bf16 v[92:95], v[76:79], v[48:51], v[72:75]
	s_nop 2
	ds_read_b128 v[72:75], v179 offset:30720
	v_mfma_f32_16x16x32_bf16 v[36:39], v[36:39], v[48:51], v[96:99]
	v_mfma_f32_16x16x32_bf16 v[52:55], v[52:55], v[48:51], v[88:91]
	v_mfma_f32_16x16x32_bf16 v[56:59], v[56:59], v[48:51], v[84:87]
	v_mfma_f32_16x16x32_bf16 v[60:63], v[60:63], v[48:51], v[80:83]
	s_waitcnt lgkmcnt(0)
	v_mfma_f32_16x16x32_bf16 v[48:51], v[72:75], v[48:51], v[68:71]
	s_nop 2
	ds_read_b128 v[68:71], v179 offset:17408
	s_waitcnt lgkmcnt(0)
	v_mfma_f32_16x16x32_bf16 v[68:71], v[68:71], v[40:43], v[36:39]
	s_nop 2
	ds_read_b128 v[36:39], v179 offset:19456
	s_waitcnt lgkmcnt(0)
	v_mfma_f32_16x16x32_bf16 v[72:75], v[36:39], v[40:43], v[44:47]
	ds_read_b128 v[36:39], v179 offset:21504
	s_waitcnt lgkmcnt(0)
	v_mfma_f32_16x16x32_bf16 v[76:79], v[36:39], v[40:43], v[52:55]
	ds_read_b128 v[36:39], v179 offset:23552
	s_waitcnt lgkmcnt(0)
	v_mfma_f32_16x16x32_bf16 v[80:83], v[36:39], v[40:43], v[56:59]
	ds_read_b128 v[36:39], v179 offset:25600
	s_waitcnt lgkmcnt(0)
	v_mfma_f32_16x16x32_bf16 v[84:87], v[36:39], v[40:43], v[60:63]
	ds_read_b128 v[36:39], v179 offset:27648
	s_waitcnt lgkmcnt(0)
	v_mfma_f32_16x16x32_bf16 v[88:91], v[36:39], v[40:43], v[64:67]
	ds_read_b128 v[36:39], v179 offset:29696
	s_waitcnt lgkmcnt(0)
	v_mfma_f32_16x16x32_bf16 v[92:95], v[36:39], v[40:43], v[92:95]
	ds_read_b128 v[36:39], v179 offset:31744
	s_waitcnt lgkmcnt(0)
	v_mfma_f32_16x16x32_bf16 v[96:99], v[36:39], v[40:43], v[48:51]
	s_mov_b32 s24, 0xffff5b70
	s_mov_b32 s25, -1
	v_lshl_add_u64 v[40:41], v[186:187], 0, s[24:25]
	s_mov_b32 s24, 0xffff6000
	v_add_co_u32_e32 v48, vcc, s24, v186
	s_mov_b32 s24, 0xffff5bf0
	s_mov_b32 s25, -1
	s_mov_b32 m0, s11
	s_waitcnt vmcnt(12)
	s_barrier
	v_lshl_add_u64 v[36:37], v[192:193], 0, s[88:89]
	v_lshl_add_u64 v[50:51], v[186:187], 0, s[24:25]
	s_mov_b32 s24, 0xffff5f70
	global_load_lds_dwordx4 v[36:37], off
	v_lshl_add_u64 v[36:37], v[194:195], 0, s[88:89]
	s_mov_b32 m0, s9
	s_mov_b32 s25, -1
	global_load_lds_dwordx4 v[36:37], off
	v_lshl_add_u64 v[36:37], v[192:193], 0, s[90:91]
	s_mov_b32 m0, s8
	v_lshl_add_u64 v[56:57], v[186:187], 0, s[24:25]
	s_mov_b32 s24, 0xffff5ff0
	global_load_lds_dwordx4 v[36:37], off
	v_lshl_add_u64 v[36:37], v[194:195], 0, s[90:91]
	s_mov_b32 m0, s10
	s_mov_b32 s25, -1
	global_load_lds_dwordx4 v[36:37], off
	v_addc_co_u32_e32 v49, vcc, -1, v187, vcc
	v_lshl_add_u64 v[58:59], v[186:187], 0, s[24:25]
	global_load_dwordx4 v[36:39], v[48:49], off offset:-1168
	s_nop 0
	global_load_dwordx4 v[40:43], v[40:41], off offset:16
	s_nop 0
	global_load_dwordx4 v[52:55], v[48:49], off offset:-1040
	global_load_dwordx4 v[44:47], v[48:49], off offset:-144
	global_load_dwordx4 v[64:67], v[50:51], off offset:16
	s_nop 0
	global_load_dwordx4 v[48:51], v[48:49], off offset:-16
	s_nop 0
	global_load_dwordx4 v[60:63], v[56:57], off offset:16
	s_nop 0
	global_load_dwordx4 v[56:59], v[58:59], off offset:16
	v_cvt_pk_bf16_f32 v24, v24, v25
	v_cvt_pk_bf16_f32 v25, v26, v27
	v_cvt_pk_bf16_f32 v26, v12, v13
	v_cvt_pk_bf16_f32 v27, v14, v15
	v_cvt_pk_bf16_f32 v28, v28, v29
	v_cvt_pk_bf16_f32 v29, v30, v31
	v_cvt_pk_bf16_f32 v30, v32, v33
	v_cvt_pk_bf16_f32 v31, v34, v35
	v_cvt_pk_bf16_f32 v16, v16, v17
	v_cvt_pk_bf16_f32 v17, v18, v19
	v_cvt_pk_bf16_f32 v18, v20, v21
	v_cvt_pk_bf16_f32 v19, v22, v23
	v_cvt_pk_bf16_f32 v172, v8, v9
	v_cvt_pk_bf16_f32 v173, v10, v11
	v_cvt_pk_bf16_f32 v174, v4, v5
	v_cvt_pk_bf16_f32 v175, v6, v7
	ds_read_b128 v[4:7], v179 offset:32768
	ds_read_b128 v[8:11], v179 offset:34816
	ds_read_b128 v[12:15], v179 offset:36864
	s_waitcnt lgkmcnt(0)
	v_mfma_f32_16x16x32_bf16 v[20:23], v[8:11], v[24:27], v[104:107]
	ds_read_b128 v[8:11], v179 offset:38912
	v_mfma_f32_16x16x32_bf16 v[4:7], v[4:7], v[24:27], v[100:103]
	v_mfma_f32_16x16x32_bf16 v[32:35], v[12:15], v[24:27], v[108:111]
	ds_read_b128 v[12:15], v179 offset:40960
	s_waitcnt lgkmcnt(0)
	v_mfma_f32_16x16x32_bf16 v[100:103], v[8:11], v[24:27], v[112:115]
	ds_read_b128 v[8:11], v179 offset:43008
	v_mfma_f32_16x16x32_bf16 v[104:107], v[12:15], v[24:27], v[116:119]
	ds_read_b128 v[12:15], v179 offset:45056
	s_waitcnt lgkmcnt(0)
	v_mfma_f32_16x16x32_bf16 v[108:111], v[8:11], v[24:27], v[120:123]
	ds_read_b128 v[8:11], v179 offset:47104
	v_mfma_f32_16x16x32_bf16 v[112:115], v[12:15], v[24:27], v[124:127]
	s_waitcnt lgkmcnt(0)
	v_mfma_f32_16x16x32_bf16 v[116:119], v[8:11], v[24:27], v[128:131]
	ds_read_b128 v[8:11], v179 offset:33792
	s_waitcnt lgkmcnt(0)
	v_mfma_f32_16x16x32_bf16 v[8:11], v[8:11], v[28:31], v[4:7]
	s_nop 2
	ds_read_b128 v[4:7], v179 offset:35840
	s_waitcnt lgkmcnt(0)
	v_mfma_f32_16x16x32_bf16 v[12:15], v[4:7], v[28:31], v[20:23]
	ds_read_b128 v[4:7], v179 offset:37888
	s_waitcnt lgkmcnt(0)
	v_mfma_f32_16x16x32_bf16 v[20:23], v[4:7], v[28:31], v[32:35]
	ds_read_b128 v[4:7], v179 offset:39936
	s_waitcnt lgkmcnt(0)
	v_mfma_f32_16x16x32_bf16 v[24:27], v[4:7], v[28:31], v[100:103]
	ds_read_b128 v[4:7], v179 offset:41984
	s_waitcnt lgkmcnt(0)
	v_mfma_f32_16x16x32_bf16 v[32:35], v[4:7], v[28:31], v[104:107]
	ds_read_b128 v[4:7], v179 offset:44032
	s_waitcnt lgkmcnt(0)
	v_mfma_f32_16x16x32_bf16 v[100:103], v[4:7], v[28:31], v[108:111]
	ds_read_b128 v[4:7], v179 offset:46080
	s_waitcnt lgkmcnt(0)
	v_mfma_f32_16x16x32_bf16 v[104:107], v[4:7], v[28:31], v[112:115]
	ds_read_b128 v[4:7], v179 offset:48128
	s_waitcnt lgkmcnt(0)
	v_mfma_f32_16x16x32_bf16 v[116:119], v[4:7], v[28:31], v[116:119]
	ds_read_b128 v[4:7], v179 offset:49152
	ds_read_b128 v[28:31], v179 offset:51200
	s_waitcnt lgkmcnt(0)
	v_mfma_f32_16x16x32_bf16 v[4:7], v[4:7], v[16:19], v[68:71]
	s_nop 2
	ds_read_b128 v[68:71], v179 offset:53248
	v_mfma_f32_16x16x32_bf16 v[28:31], v[28:31], v[16:19], v[72:75]
	s_nop 2
	ds_read_b128 v[72:75], v179 offset:55296
	s_waitcnt lgkmcnt(0)
	v_mfma_f32_16x16x32_bf16 v[68:71], v[68:71], v[16:19], v[76:79]
	s_nop 2
	ds_read_b128 v[76:79], v179 offset:57344
	v_mfma_f32_16x16x32_bf16 v[72:75], v[72:75], v[16:19], v[80:83]
	s_waitcnt lgkmcnt(0)
	v_mfma_f32_16x16x32_bf16 v[80:83], v[76:79], v[16:19], v[84:87]
	ds_read_b128 v[76:79], v179 offset:59392
	s_waitcnt lgkmcnt(0)
	v_mfma_f32_16x16x32_bf16 v[108:111], v[76:79], v[16:19], v[88:91]
	ds_read_b128 v[76:79], v179 offset:61440
	s_waitcnt lgkmcnt(0)
	v_mfma_f32_16x16x32_bf16 v[92:95], v[76:79], v[16:19], v[92:95]
	ds_read_b128 v[76:79], v179 offset:63488
	s_waitcnt lgkmcnt(0)
	v_mfma_f32_16x16x32_bf16 v[16:19], v[76:79], v[16:19], v[96:99]
	ds_read_b128 v[76:79], v179 offset:50176
	s_waitcnt lgkmcnt(0)
	v_mfma_f32_16x16x32_bf16 v[76:79], v[76:79], v[172:175], v[4:7]
	s_nop 2
	ds_read_b128 v[4:7], v179 offset:52224
	s_waitcnt lgkmcnt(0)
	v_mfma_f32_16x16x32_bf16 v[84:87], v[4:7], v[172:175], v[28:31]
	ds_read_b128 v[4:7], v179 offset:54272
	s_waitcnt lgkmcnt(0)
	v_mfma_f32_16x16x32_bf16 v[88:91], v[4:7], v[172:175], v[68:71]
	ds_read_b128 v[4:7], v179 offset:56320
	s_waitcnt lgkmcnt(0)
	v_mfma_f32_16x16x32_bf16 v[112:115], v[4:7], v[172:175], v[72:75]
	ds_read_b128 v[4:7], v179 offset:58368
	s_waitcnt lgkmcnt(0)
	v_mfma_f32_16x16x32_bf16 v[128:131], v[4:7], v[172:175], v[80:83]
	ds_read_b128 v[4:7], v179 offset:60416
	s_waitcnt lgkmcnt(0)
	v_mfma_f32_16x16x32_bf16 v[164:167], v[4:7], v[172:175], v[108:111]
	ds_read_b128 v[4:7], v179 offset:62464
	s_waitcnt lgkmcnt(0)
	v_mfma_f32_16x16x32_bf16 v[168:171], v[4:7], v[172:175], v[92:95]
	ds_read_b128 v[4:7], v179 offset:64512
	s_waitcnt lgkmcnt(0)
	v_mfma_f32_16x16x32_bf16 v[172:175], v[4:7], v[172:175], v[16:19]
	s_mov_b32 s24, 0xffff6b70
	s_mov_b32 s25, -1
	s_nop 0
	v_lshl_add_u64 v[16:17], v[186:187], 0, s[24:25]
	s_mov_b32 s24, 0xffff7000
	v_add_co_u32_e32 v68, vcc, s24, v186
	s_mov_b32 s24, 0xffff6bf0
	s_mov_b32 s25, -1
	s_mov_b32 m0, s13
	s_waitcnt vmcnt(12)
	s_barrier
	v_lshl_add_u64 v[4:5], v[192:193], 0, s[92:93]
	v_lshl_add_u64 v[70:71], v[186:187], 0, s[24:25]
	s_mov_b32 s24, 0xffff6f70
	global_load_lds_dwordx4 v[4:5], off
	v_lshl_add_u64 v[4:5], v[194:195], 0, s[92:93]
	s_mov_b32 m0, s14
	s_mov_b32 s25, -1
	global_load_lds_dwordx4 v[4:5], off
	v_lshl_add_u64 v[4:5], v[192:193], 0, s[82:83]
	s_mov_b32 m0, s15
	v_lshl_add_u64 v[80:81], v[186:187], 0, s[24:25]
	s_mov_b32 s24, 0xffff6ff0
	global_load_lds_dwordx4 v[4:5], off
	v_lshl_add_u64 v[4:5], v[194:195], 0, s[82:83]
	s_mov_b32 m0, s16
	s_mov_b32 s25, -1
	global_load_lds_dwordx4 v[4:5], off
	v_addc_co_u32_e32 v69, vcc, -1, v187, vcc
	v_lshl_add_u64 v[82:83], v[186:187], 0, s[24:25]
	global_load_dwordx4 v[4:7], v[68:69], off offset:-1168
	s_nop 0
	global_load_dwordx4 v[16:19], v[16:17], off offset:16
	s_nop 0
	global_load_dwordx4 v[72:75], v[68:69], off offset:-1040
	global_load_dwordx4 v[28:31], v[68:69], off offset:-144
	global_load_dwordx4 v[108:111], v[70:71], off offset:16
	s_nop 0
	global_load_dwordx4 v[68:71], v[68:69], off offset:-16
	s_nop 0
	global_load_dwordx4 v[96:99], v[80:81], off offset:16
	s_nop 0
	global_load_dwordx4 v[80:83], v[82:83], off offset:16
	v_add_u32_e32 v208, s23, v181
	v_cvt_pk_bf16_f32 v92, v132, v133
	v_cvt_pk_bf16_f32 v93, v134, v135
	v_cvt_pk_bf16_f32 v94, v136, v137
	v_cvt_pk_bf16_f32 v95, v138, v139
	v_cvt_pk_bf16_f32 v132, v148, v149
	v_cvt_pk_bf16_f32 v133, v150, v151
	v_cvt_pk_bf16_f32 v134, v160, v161
	v_cvt_pk_bf16_f32 v135, v162, v163
	v_cvt_pk_bf16_f32 v136, v140, v141
	v_cvt_pk_bf16_f32 v137, v142, v143
	v_cvt_pk_bf16_f32 v138, v156, v157
	v_cvt_pk_bf16_f32 v139, v158, v159
	v_cvt_pk_bf16_f32 v160, v144, v145
	v_cvt_pk_bf16_f32 v161, v146, v147
	v_cvt_pk_bf16_f32 v162, v152, v153
	v_cvt_pk_bf16_f32 v163, v154, v155
	ds_read_b128 v[120:123], v208
	ds_read_b128 v[124:127], v208 offset:2048
	s_waitcnt lgkmcnt(0)
	v_mfma_f32_16x16x32_bf16 v[8:11], v[120:123], v[92:95], v[8:11]
	ds_read_b128 v[120:123], v208 offset:4096
	v_mfma_f32_16x16x32_bf16 v[124:127], v[124:127], v[92:95], v[12:15]
	s_nop 2
	ds_read_b128 v[12:15], v208 offset:6144
	s_waitcnt lgkmcnt(0)
	v_mfma_f32_16x16x32_bf16 v[20:23], v[120:123], v[92:95], v[20:23]
	ds_read_b128 v[120:123], v208 offset:8192
	v_mfma_f32_16x16x32_bf16 v[140:143], v[12:15], v[92:95], v[24:27]
	ds_read_b128 v[12:15], v208 offset:10240
	s_nop 1
	ds_read_b128 v[24:27], v208 offset:12288
	s_waitcnt lgkmcnt(0)
	v_mfma_f32_16x16x32_bf16 v[100:103], v[12:15], v[92:95], v[100:103]
	ds_read_b128 v[12:15], v208 offset:14336
	v_mfma_f32_16x16x32_bf16 v[32:35], v[120:123], v[92:95], v[32:35]
	v_mfma_f32_16x16x32_bf16 v[144:147], v[24:27], v[92:95], v[104:107]
	s_waitcnt lgkmcnt(0)
	v_mfma_f32_16x16x32_bf16 v[148:151], v[12:15], v[92:95], v[116:119]
	ds_read_b128 v[12:15], v208 offset:1024
	s_waitcnt lgkmcnt(0)
	v_mfma_f32_16x16x32_bf16 v[12:15], v[12:15], v[132:135], v[8:11]
	s_nop 2
	ds_read_b128 v[8:11], v208 offset:3072
	s_waitcnt lgkmcnt(0)
	v_mfma_f32_16x16x32_bf16 v[24:27], v[8:11], v[132:135], v[124:127]
	ds_read_b128 v[8:11], v208 offset:5120
	s_waitcnt lgkmcnt(0)
	v_mfma_f32_16x16x32_bf16 v[92:95], v[8:11], v[132:135], v[20:23]
	ds_read_b128 v[8:11], v208 offset:7168
	s_waitcnt lgkmcnt(0)
	v_mfma_f32_16x16x32_bf16 v[104:107], v[8:11], v[132:135], v[140:143]
	ds_read_b128 v[8:11], v208 offset:9216
	s_waitcnt lgkmcnt(0)
	v_mfma_f32_16x16x32_bf16 v[116:119], v[8:11], v[132:135], v[32:35]
	ds_read_b128 v[8:11], v208 offset:11264
	s_waitcnt lgkmcnt(0)
	v_mfma_f32_16x16x32_bf16 v[120:123], v[8:11], v[132:135], v[100:103]
	ds_read_b128 v[8:11], v208 offset:13312
	s_waitcnt lgkmcnt(0)
	v_mfma_f32_16x16x32_bf16 v[124:127], v[8:11], v[132:135], v[144:147]
	ds_read_b128 v[8:11], v208 offset:15360
	s_waitcnt lgkmcnt(0)
	v_mfma_f32_16x16x32_bf16 v[132:135], v[8:11], v[132:135], v[148:151]
	v_add_u32_e32 v207, s22, v181
	ds_read_b128 v[8:11], v207
	ds_read_b128 v[20:23], v207 offset:2048
	ds_read_b128 v[32:35], v207 offset:4096
	ds_read_b128 v[100:103], v207 offset:12288
	s_waitcnt lgkmcnt(0)
	v_mfma_f32_16x16x32_bf16 v[8:11], v[8:11], v[136:139], v[76:79]
	s_nop 2
	ds_read_b128 v[76:79], v207 offset:6144
	v_mfma_f32_16x16x32_bf16 v[20:23], v[20:23], v[136:139], v[84:87]
	v_mfma_f32_16x16x32_bf16 v[32:35], v[32:35], v[136:139], v[88:91]
	s_nop 1
	ds_read_b128 v[84:87], v207 offset:8192
	ds_read_b128 v[88:91], v207 offset:10240
	s_waitcnt lgkmcnt(0)
	v_mfma_f32_16x16x32_bf16 v[76:79], v[76:79], v[136:139], v[112:115]
	s_nop 2
	ds_read_b128 v[112:115], v207 offset:14336
	v_mfma_f32_16x16x32_bf16 v[84:87], v[84:87], v[136:139], v[128:131]
	v_mfma_f32_16x16x32_bf16 v[88:91], v[88:91], v[136:139], v[164:167]
	v_mfma_f32_16x16x32_bf16 v[100:103], v[100:103], v[136:139], v[168:171]
	s_waitcnt lgkmcnt(0)
	v_mfma_f32_16x16x32_bf16 v[112:115], v[112:115], v[136:139], v[172:175]
	ds_read_b128 v[128:131], v207 offset:1024
	s_waitcnt lgkmcnt(0)
	v_mfma_f32_16x16x32_bf16 v[128:131], v[128:131], v[160:163], v[8:11]
	s_nop 2
	ds_read_b128 v[8:11], v207 offset:3072
	s_waitcnt lgkmcnt(0)
	v_mfma_f32_16x16x32_bf16 v[136:139], v[8:11], v[160:163], v[20:23]
	ds_read_b128 v[8:11], v207 offset:5120
	s_waitcnt lgkmcnt(0)
	v_mfma_f32_16x16x32_bf16 v[140:143], v[8:11], v[160:163], v[32:35]
	ds_read_b128 v[8:11], v207 offset:7168
	s_waitcnt lgkmcnt(0)
	v_mfma_f32_16x16x32_bf16 v[144:147], v[8:11], v[160:163], v[76:79]
	ds_read_b128 v[8:11], v207 offset:9216
	s_waitcnt lgkmcnt(0)
	v_mfma_f32_16x16x32_bf16 v[148:151], v[8:11], v[160:163], v[84:87]
	ds_read_b128 v[8:11], v207 offset:11264
	s_waitcnt lgkmcnt(0)
	v_mfma_f32_16x16x32_bf16 v[152:155], v[8:11], v[160:163], v[88:91]
	ds_read_b128 v[8:11], v207 offset:13312
	s_waitcnt lgkmcnt(0)
	v_mfma_f32_16x16x32_bf16 v[156:159], v[8:11], v[160:163], v[100:103]
	ds_read_b128 v[8:11], v207 offset:15360
	s_waitcnt lgkmcnt(0)
	v_mfma_f32_16x16x32_bf16 v[160:163], v[8:11], v[160:163], v[112:115]
	s_mov_b32 s22, 0xffff7b70
	s_mov_b32 s23, -1
	v_lshl_add_u64 v[20:21], v[186:187], 0, s[22:23]
	s_movk_i32 s22, 0x8000
	v_add_co_u32_e32 v76, vcc, s22, v186
	s_mov_b32 s22, 0xffff7bf0
	s_mov_b32 s23, -1
	s_mov_b32 m0, s21
	s_waitcnt vmcnt(12)
	s_barrier
	v_lshl_add_u64 v[8:9], v[192:193], 0, s[72:73]
	v_lshl_add_u64 v[78:79], v[186:187], 0, s[22:23]
	s_mov_b32 s22, 0xffff7f70
	global_load_lds_dwordx4 v[8:9], off
	v_lshl_add_u64 v[8:9], v[194:195], 0, s[72:73]
	s_mov_b32 m0, s20
	s_mov_b32 s23, -1
	global_load_lds_dwordx4 v[8:9], off
	v_lshl_add_u64 v[8:9], v[192:193], 0, s[74:75]
	s_mov_b32 m0, s18
	v_lshl_add_u64 v[88:89], v[186:187], 0, s[22:23]
	s_mov_b32 s22, 0xffff7ff0
	global_load_lds_dwordx4 v[8:9], off
	v_lshl_add_u64 v[8:9], v[194:195], 0, s[74:75]
	s_mov_b32 m0, s19
	s_mov_b32 s23, -1
	global_load_lds_dwordx4 v[8:9], off
	v_addc_co_u32_e32 v77, vcc, -1, v187, vcc
	v_lshl_add_u64 v[90:91], v[186:187], 0, s[22:23]
	global_load_dwordx4 v[8:11], v[76:77], off offset:-1168
	s_nop 0
	global_load_dwordx4 v[20:23], v[20:21], off offset:16
	s_nop 0
	global_load_dwordx4 v[84:87], v[76:77], off offset:-1040
	global_load_dwordx4 v[32:35], v[76:77], off offset:-144
	global_load_dwordx4 v[112:115], v[78:79], off offset:16
	s_nop 0
	global_load_dwordx4 v[76:79], v[76:77], off offset:-16
	s_nop 0
	global_load_dwordx4 v[100:103], v[88:89], off offset:16
	s_nop 0
	global_load_dwordx4 v[88:91], v[90:91], off offset:16
	v_cvt_pk_bf16_f32 v36, v36, v37
	v_cvt_pk_bf16_f32 v37, v38, v39
	v_cvt_pk_bf16_f32 v38, v40, v41
	v_cvt_pk_bf16_f32 v39, v42, v43
	v_cvt_pk_bf16_f32 v164, v52, v53
	v_cvt_pk_bf16_f32 v165, v54, v55
	v_cvt_pk_bf16_f32 v166, v64, v65
	v_cvt_pk_bf16_f32 v167, v66, v67
	v_cvt_pk_bf16_f32 v168, v44, v45
	v_cvt_pk_bf16_f32 v169, v46, v47
	v_cvt_pk_bf16_f32 v170, v60, v61
	v_cvt_pk_bf16_f32 v171, v62, v63
	v_cvt_pk_bf16_f32 v48, v48, v49
	v_cvt_pk_bf16_f32 v49, v50, v51
	v_cvt_pk_bf16_f32 v50, v56, v57
	v_cvt_pk_bf16_f32 v51, v58, v59
	ds_read_b128 v[40:43], v179
	ds_read_b128 v[44:47], v179 offset:2048
	s_waitcnt lgkmcnt(0)
	v_mfma_f32_16x16x32_bf16 v[12:15], v[40:43], v[36:39], v[12:15]
	ds_read_b128 v[40:43], v179 offset:4096
	v_mfma_f32_16x16x32_bf16 v[24:27], v[44:47], v[36:39], v[24:27]
	ds_read_b128 v[44:47], v179 offset:6144
	s_waitcnt lgkmcnt(0)
	v_mfma_f32_16x16x32_bf16 v[52:55], v[40:43], v[36:39], v[92:95]
	ds_read_b128 v[40:43], v179 offset:8192
	v_mfma_f32_16x16x32_bf16 v[56:59], v[44:47], v[36:39], v[104:107]
	ds_read_b128 v[44:47], v179 offset:10240
	s_waitcnt lgkmcnt(0)
	v_mfma_f32_16x16x32_bf16 v[60:63], v[40:43], v[36:39], v[116:119]
	ds_read_b128 v[40:43], v179 offset:12288
	v_mfma_f32_16x16x32_bf16 v[92:95], v[44:47], v[36:39], v[120:123]
	ds_read_b128 v[44:47], v179 offset:14336
	s_waitcnt lgkmcnt(0)
	v_mfma_f32_16x16x32_bf16 v[104:107], v[40:43], v[36:39], v[124:127]
	v_mfma_f32_16x16x32_bf16 v[36:39], v[44:47], v[36:39], v[132:135]
	ds_read_b128 v[40:43], v179 offset:1024
	s_waitcnt lgkmcnt(0)
	v_mfma_f32_16x16x32_bf16 v[40:43], v[40:43], v[164:167], v[12:15]
	s_nop 2
	ds_read_b128 v[12:15], v179 offset:3072
	s_waitcnt lgkmcnt(0)
	v_mfma_f32_16x16x32_bf16 v[44:47], v[12:15], v[164:167], v[24:27]
	ds_read_b128 v[12:15], v179 offset:5120
	s_waitcnt lgkmcnt(0)
	v_mfma_f32_16x16x32_bf16 v[52:55], v[12:15], v[164:167], v[52:55]
	ds_read_b128 v[12:15], v179 offset:7168
	s_waitcnt lgkmcnt(0)
	v_mfma_f32_16x16x32_bf16 v[56:59], v[12:15], v[164:167], v[56:59]
	ds_read_b128 v[12:15], v179 offset:9216
	s_waitcnt lgkmcnt(0)
	v_mfma_f32_16x16x32_bf16 v[64:67], v[12:15], v[164:167], v[60:63]
	ds_read_b128 v[12:15], v179 offset:11264
	s_waitcnt lgkmcnt(0)
	v_mfma_f32_16x16x32_bf16 v[120:123], v[12:15], v[164:167], v[92:95]
	ds_read_b128 v[12:15], v179 offset:13312
	s_waitcnt lgkmcnt(0)
	v_mfma_f32_16x16x32_bf16 v[124:127], v[12:15], v[164:167], v[104:107]
	ds_read_b128 v[12:15], v179 offset:15360
	s_waitcnt lgkmcnt(0)
	v_mfma_f32_16x16x32_bf16 v[132:135], v[12:15], v[164:167], v[36:39]
	ds_read_b128 v[12:15], v179 offset:16384
	ds_read_b128 v[24:27], v179 offset:18432
	s_nop 0
	ds_read_b128 v[36:39], v179 offset:20480
	ds_read_b128 v[60:63], v179 offset:22528
	ds_read_b128 v[92:95], v179 offset:24576
	ds_read_b128 v[104:107], v179 offset:26624
	ds_read_b128 v[116:119], v179 offset:28672
	s_waitcnt lgkmcnt(0)
	v_mfma_f32_16x16x32_bf16 v[12:15], v[12:15], v[168:171], v[128:131]
	s_nop 2
	ds_read_b128 v[128:131], v179 offset:30720
	v_mfma_f32_16x16x32_bf16 v[24:27], v[24:27], v[168:171], v[136:139]
	v_mfma_f32_16x16x32_bf16 v[36:39], v[36:39], v[168:171], v[140:143]
	v_mfma_f32_16x16x32_bf16 v[60:63], v[60:63], v[168:171], v[144:147]
	v_mfma_f32_16x16x32_bf16 v[92:95], v[92:95], v[168:171], v[148:151]
	v_mfma_f32_16x16x32_bf16 v[104:107], v[104:107], v[168:171], v[152:155]
	v_mfma_f32_16x16x32_bf16 v[116:119], v[116:119], v[168:171], v[156:159]
	s_waitcnt lgkmcnt(0)
	v_mfma_f32_16x16x32_bf16 v[160:163], v[128:131], v[168:171], v[160:163]
	ds_read_b128 v[128:131], v179 offset:17408
	s_waitcnt lgkmcnt(0)
	v_mfma_f32_16x16x32_bf16 v[128:131], v[128:131], v[48:51], v[12:15]
	s_nop 2
	ds_read_b128 v[12:15], v179 offset:19456
	s_waitcnt lgkmcnt(0)
	v_mfma_f32_16x16x32_bf16 v[136:139], v[12:15], v[48:51], v[24:27]
	ds_read_b128 v[12:15], v179 offset:21504
	s_waitcnt lgkmcnt(0)
	v_mfma_f32_16x16x32_bf16 v[140:143], v[12:15], v[48:51], v[36:39]
	ds_read_b128 v[12:15], v179 offset:23552
	s_waitcnt lgkmcnt(0)
	v_mfma_f32_16x16x32_bf16 v[144:147], v[12:15], v[48:51], v[60:63]
	ds_read_b128 v[12:15], v179 offset:25600
	s_waitcnt lgkmcnt(0)
	v_mfma_f32_16x16x32_bf16 v[148:151], v[12:15], v[48:51], v[92:95]
	ds_read_b128 v[12:15], v179 offset:27648
	s_waitcnt lgkmcnt(0)
	v_mfma_f32_16x16x32_bf16 v[152:155], v[12:15], v[48:51], v[104:107]
	ds_read_b128 v[12:15], v179 offset:29696
	s_waitcnt lgkmcnt(0)
	v_mfma_f32_16x16x32_bf16 v[156:159], v[12:15], v[48:51], v[116:119]
	ds_read_b128 v[12:15], v179 offset:31744
	s_waitcnt lgkmcnt(0)
	v_mfma_f32_16x16x32_bf16 v[160:163], v[12:15], v[48:51], v[160:163]
	s_movk_i32 s22, 0x8b70
	s_mov_b32 s23, -1
	v_lshl_add_u64 v[24:25], v[186:187], 0, s[22:23]
	s_movk_i32 s22, 0x9000
	v_add_co_u32_e32 v48, vcc, s22, v186
	s_movk_i32 s22, 0x8bf0
	s_mov_b32 s23, -1
	s_mov_b32 m0, s11
	s_waitcnt vmcnt(12)
	s_barrier
	v_lshl_add_u64 v[12:13], v[192:193], 0, s[76:77]
	v_lshl_add_u64 v[50:51], v[186:187], 0, s[22:23]
	s_movk_i32 s22, 0x8f70
	global_load_lds_dwordx4 v[12:13], off
	v_lshl_add_u64 v[12:13], v[194:195], 0, s[76:77]
	s_mov_b32 m0, s9
	s_mov_b32 s23, -1
	global_load_lds_dwordx4 v[12:13], off
	v_lshl_add_u64 v[12:13], v[192:193], 0, s[60:61]
	s_mov_b32 m0, s8
	v_lshl_add_u64 v[92:93], v[186:187], 0, s[22:23]
	s_movk_i32 s22, 0x8ff0
	global_load_lds_dwordx4 v[12:13], off
	v_lshl_add_u64 v[12:13], v[194:195], 0, s[60:61]
	s_mov_b32 m0, s10
	s_mov_b32 s23, -1
	global_load_lds_dwordx4 v[12:13], off
	v_addc_co_u32_e32 v49, vcc, -1, v187, vcc
	v_lshl_add_u64 v[94:95], v[186:187], 0, s[22:23]
	global_load_dwordx4 v[12:15], v[48:49], off offset:-1168
	s_nop 0
	global_load_dwordx4 v[24:27], v[24:25], off offset:16
	s_nop 0
	global_load_dwordx4 v[60:63], v[48:49], off offset:-1040
	global_load_dwordx4 v[36:39], v[48:49], off offset:-144
	global_load_dwordx4 v[116:119], v[50:51], off offset:16
	s_nop 0
	global_load_dwordx4 v[48:51], v[48:49], off offset:-16
	s_nop 0
	global_load_dwordx4 v[104:107], v[92:93], off offset:16
	s_nop 0
	global_load_dwordx4 v[92:95], v[94:95], off offset:16
	v_cvt_pk_bf16_f32 v4, v4, v5
	v_cvt_pk_bf16_f32 v5, v6, v7
	v_cvt_pk_bf16_f32 v6, v16, v17
	v_cvt_pk_bf16_f32 v7, v18, v19
	v_cvt_pk_bf16_f32 v72, v72, v73
	v_cvt_pk_bf16_f32 v73, v74, v75
	v_cvt_pk_bf16_f32 v74, v108, v109
	v_cvt_pk_bf16_f32 v75, v110, v111
	v_cvt_pk_bf16_f32 v28, v28, v29
	v_cvt_pk_bf16_f32 v29, v30, v31
	v_cvt_pk_bf16_f32 v30, v96, v97
	v_cvt_pk_bf16_f32 v31, v98, v99
	v_cvt_pk_bf16_f32 v108, v68, v69
	v_cvt_pk_bf16_f32 v109, v70, v71
	v_cvt_pk_bf16_f32 v110, v80, v81
	v_cvt_pk_bf16_f32 v111, v82, v83
	ds_read_b128 v[16:19], v179 offset:32768
	ds_read_b128 v[68:71], v179 offset:34816
	s_waitcnt lgkmcnt(0)
	v_mfma_f32_16x16x32_bf16 v[16:19], v[16:19], v[4:7], v[40:43]
	s_nop 2
	ds_read_b128 v[40:43], v179 offset:36864
	v_mfma_f32_16x16x32_bf16 v[44:47], v[68:71], v[4:7], v[44:47]
	ds_read_b128 v[68:71], v179 offset:38912
	s_waitcnt lgkmcnt(0)
	v_mfma_f32_16x16x32_bf16 v[40:43], v[40:43], v[4:7], v[52:55]
	s_nop 2
	ds_read_b128 v[52:55], v179 offset:40960
	v_mfma_f32_16x16x32_bf16 v[68:71], v[68:71], v[4:7], v[56:59]
	s_nop 2
	ds_read_b128 v[56:59], v179 offset:43008
	s_waitcnt lgkmcnt(0)
	v_mfma_f32_16x16x32_bf16 v[52:55], v[52:55], v[4:7], v[64:67]
	s_nop 2
	ds_read_b128 v[64:67], v179 offset:45056
	v_mfma_f32_16x16x32_bf16 v[96:99], v[56:59], v[4:7], v[120:123]
	ds_read_b128 v[56:59], v179 offset:47104
	s_waitcnt lgkmcnt(0)
	v_mfma_f32_16x16x32_bf16 v[64:67], v[64:67], v[4:7], v[124:127]
	v_mfma_f32_16x16x32_bf16 v[4:7], v[56:59], v[4:7], v[132:135]
	ds_read_b128 v[56:59], v179 offset:33792
	s_waitcnt lgkmcnt(0)
	v_mfma_f32_16x16x32_bf16 v[16:19], v[56:59], v[72:75], v[16:19]
	ds_read_b128 v[56:59], v179 offset:35840
	s_waitcnt lgkmcnt(0)
	v_mfma_f32_16x16x32_bf16 v[44:47], v[56:59], v[72:75], v[44:47]
	ds_read_b128 v[56:59], v179 offset:37888
	s_waitcnt lgkmcnt(0)
	v_mfma_f32_16x16x32_bf16 v[56:59], v[56:59], v[72:75], v[40:43]
	s_nop 2
	ds_read_b128 v[40:43], v179 offset:39936
	s_waitcnt lgkmcnt(0)
	v_mfma_f32_16x16x32_bf16 v[68:71], v[40:43], v[72:75], v[68:71]
	ds_read_b128 v[40:43], v179 offset:41984
	s_waitcnt lgkmcnt(0)
	v_mfma_f32_16x16x32_bf16 v[80:83], v[40:43], v[72:75], v[52:55]
	ds_read_b128 v[40:43], v179 offset:44032
	s_waitcnt lgkmcnt(0)
	v_mfma_f32_16x16x32_bf16 v[96:99], v[40:43], v[72:75], v[96:99]
	ds_read_b128 v[40:43], v179 offset:46080
	s_waitcnt lgkmcnt(0)
	v_mfma_f32_16x16x32_bf16 v[124:127], v[40:43], v[72:75], v[64:67]
	ds_read_b128 v[40:43], v179 offset:48128
	s_waitcnt lgkmcnt(0)
	v_mfma_f32_16x16x32_bf16 v[132:135], v[40:43], v[72:75], v[4:7]
	s_nop 2
	ds_read_b128 v[4:7], v179 offset:49152
	ds_read_b128 v[40:43], v179 offset:51200
	ds_read_b128 v[52:55], v179 offset:53248
	ds_read_b128 v[64:67], v179 offset:55296
	ds_read_b128 v[72:75], v179 offset:57344
	ds_read_b128 v[120:123], v179 offset:59392
	s_waitcnt lgkmcnt(0)
	v_mfma_f32_16x16x32_bf16 v[4:7], v[4:7], v[28:31], v[128:131]
	s_nop 2
	ds_read_b128 v[128:131], v179 offset:61440
	v_mfma_f32_16x16x32_bf16 v[40:43], v[40:43], v[28:31], v[136:139]
	v_mfma_f32_16x16x32_bf16 v[52:55], v[52:55], v[28:31], v[140:143]
	s_waitcnt lgkmcnt(0)
	v_mfma_f32_16x16x32_bf16 v[156:159], v[128:131], v[28:31], v[156:159]
	ds_read_b128 v[128:131], v179 offset:63488
	v_mfma_f32_16x16x32_bf16 v[64:67], v[64:67], v[28:31], v[144:147]
	v_mfma_f32_16x16x32_bf16 v[72:75], v[72:75], v[28:31], v[148:151]
	v_mfma_f32_16x16x32_bf16 v[120:123], v[120:123], v[28:31], v[152:155]
	s_waitcnt lgkmcnt(0)
	v_mfma_f32_16x16x32_bf16 v[28:31], v[128:131], v[28:31], v[160:163]
	ds_read_b128 v[128:131], v179 offset:50176
	s_waitcnt lgkmcnt(0)
	v_mfma_f32_16x16x32_bf16 v[128:131], v[128:131], v[108:111], v[4:7]
	s_nop 2
	ds_read_b128 v[4:7], v179 offset:52224
	s_waitcnt lgkmcnt(0)
	v_mfma_f32_16x16x32_bf16 v[136:139], v[4:7], v[108:111], v[40:43]
	ds_read_b128 v[4:7], v179 offset:54272
	s_waitcnt lgkmcnt(0)
	v_mfma_f32_16x16x32_bf16 v[140:143], v[4:7], v[108:111], v[52:55]
	ds_read_b128 v[4:7], v179 offset:56320
	s_waitcnt lgkmcnt(0)
	v_mfma_f32_16x16x32_bf16 v[144:147], v[4:7], v[108:111], v[64:67]
	ds_read_b128 v[4:7], v179 offset:58368
	s_waitcnt lgkmcnt(0)
	v_mfma_f32_16x16x32_bf16 v[148:151], v[4:7], v[108:111], v[72:75]
	ds_read_b128 v[4:7], v179 offset:60416
	s_waitcnt lgkmcnt(0)
	v_mfma_f32_16x16x32_bf16 v[152:155], v[4:7], v[108:111], v[120:123]
	ds_read_b128 v[4:7], v179 offset:62464
	s_waitcnt lgkmcnt(0)
	v_mfma_f32_16x16x32_bf16 v[156:159], v[4:7], v[108:111], v[156:159]
	ds_read_b128 v[4:7], v179 offset:64512
	s_waitcnt lgkmcnt(0)
	v_mfma_f32_16x16x32_bf16 v[160:163], v[4:7], v[108:111], v[28:31]
	s_movk_i32 s22, 0x9b70
	s_mov_b32 s23, -1
	s_nop 0
	v_lshl_add_u64 v[28:29], v[186:187], 0, s[22:23]
	s_movk_i32 s22, 0xa000
	v_add_co_u32_e32 v52, vcc, s22, v186
	s_movk_i32 s22, 0x9bf0
	s_mov_b32 s23, -1
	s_mov_b32 m0, s13
	s_waitcnt vmcnt(12)
	s_barrier
	v_lshl_add_u64 v[4:5], v[192:193], 0, s[58:59]
	v_lshl_add_u64 v[54:55], v[186:187], 0, s[22:23]
	s_movk_i32 s22, 0x9f70
	global_load_lds_dwordx4 v[4:5], off
	v_lshl_add_u64 v[4:5], v[194:195], 0, s[58:59]
	s_mov_b32 m0, s14
	s_mov_b32 s23, -1
	global_load_lds_dwordx4 v[4:5], off
	v_lshl_add_u64 v[4:5], v[192:193], 0, s[54:55]
	s_mov_b32 m0, s15
	v_lshl_add_u64 v[72:73], v[186:187], 0, s[22:23]
	s_movk_i32 s22, 0x9ff0
	global_load_lds_dwordx4 v[4:5], off
	v_lshl_add_u64 v[4:5], v[194:195], 0, s[54:55]
	s_mov_b32 m0, s16
	s_mov_b32 s23, -1
	global_load_lds_dwordx4 v[4:5], off
	v_addc_co_u32_e32 v53, vcc, -1, v187, vcc
	v_lshl_add_u64 v[74:75], v[186:187], 0, s[22:23]
	global_load_dwordx4 v[4:7], v[52:53], off offset:-1168
	s_nop 0
	global_load_dwordx4 v[28:31], v[28:29], off offset:16
	s_nop 0
	global_load_dwordx4 v[64:67], v[52:53], off offset:-1040
	global_load_dwordx4 v[40:43], v[52:53], off offset:-144
	global_load_dwordx4 v[120:123], v[54:55], off offset:16
	s_nop 0
	global_load_dwordx4 v[52:55], v[52:53], off offset:-16
	s_nop 0
	global_load_dwordx4 v[108:111], v[72:73], off offset:16
	s_nop 0
	global_load_dwordx4 v[72:75], v[74:75], off offset:16
	v_cvt_pk_bf16_f32 v8, v8, v9
	v_cvt_pk_bf16_f32 v9, v10, v11
	v_cvt_pk_bf16_f32 v10, v20, v21
	v_cvt_pk_bf16_f32 v11, v22, v23
	v_cvt_pk_bf16_f32 v20, v84, v85
	v_cvt_pk_bf16_f32 v21, v86, v87
	v_cvt_pk_bf16_f32 v22, v112, v113
	v_cvt_pk_bf16_f32 v23, v114, v115
	v_cvt_pk_bf16_f32 v164, v32, v33
	v_cvt_pk_bf16_f32 v165, v34, v35
	v_cvt_pk_bf16_f32 v166, v100, v101
	v_cvt_pk_bf16_f32 v167, v102, v103
	v_cvt_pk_bf16_f32 v100, v76, v77
	v_cvt_pk_bf16_f32 v101, v78, v79
	v_cvt_pk_bf16_f32 v102, v88, v89
	v_cvt_pk_bf16_f32 v103, v90, v91
	ds_read_b128 v[32:35], v208
	ds_read_b128 v[76:79], v208 offset:2048
	s_waitcnt lgkmcnt(0)
	v_mfma_f32_16x16x32_bf16 v[16:19], v[32:35], v[8:11], v[16:19]
	ds_read_b128 v[32:35], v208 offset:4096
	v_mfma_f32_16x16x32_bf16 v[44:47], v[76:79], v[8:11], v[44:47]
	ds_read_b128 v[76:79], v208 offset:6144
	s_waitcnt lgkmcnt(0)
	v_mfma_f32_16x16x32_bf16 v[56:59], v[32:35], v[8:11], v[56:59]
	ds_read_b128 v[32:35], v208 offset:8192
	v_mfma_f32_16x16x32_bf16 v[68:71], v[76:79], v[8:11], v[68:71]
	ds_read_b128 v[76:79], v208 offset:10240
	s_waitcnt lgkmcnt(0)
	v_mfma_f32_16x16x32_bf16 v[80:83], v[32:35], v[8:11], v[80:83]
	ds_read_b128 v[32:35], v208 offset:12288
	v_mfma_f32_16x16x32_bf16 v[96:99], v[76:79], v[8:11], v[96:99]
	ds_read_b128 v[76:79], v208 offset:14336
	s_waitcnt lgkmcnt(0)
	v_mfma_f32_16x16x32_bf16 v[112:115], v[32:35], v[8:11], v[124:127]
	v_mfma_f32_16x16x32_bf16 v[124:127], v[76:79], v[8:11], v[132:135]
	ds_read_b128 v[8:11], v208 offset:1024
	s_waitcnt lgkmcnt(0)
	v_mfma_f32_16x16x32_bf16 v[8:11], v[8:11], v[20:23], v[16:19]
	s_nop 2
	ds_read_b128 v[16:19], v208 offset:3072
	s_waitcnt lgkmcnt(0)
	v_mfma_f32_16x16x32_bf16 v[32:35], v[16:19], v[20:23], v[44:47]
	ds_read_b128 v[16:19], v208 offset:5120
	s_waitcnt lgkmcnt(0)
	v_mfma_f32_16x16x32_bf16 v[76:79], v[16:19], v[20:23], v[56:59]
	ds_read_b128 v[16:19], v208 offset:7168
	s_waitcnt lgkmcnt(0)
	v_mfma_f32_16x16x32_bf16 v[84:87], v[16:19], v[20:23], v[68:71]
	ds_read_b128 v[16:19], v208 offset:9216
	s_waitcnt lgkmcnt(0)
	v_mfma_f32_16x16x32_bf16 v[88:91], v[16:19], v[20:23], v[80:83]
	ds_read_b128 v[16:19], v208 offset:11264
	s_waitcnt lgkmcnt(0)
	v_mfma_f32_16x16x32_bf16 v[96:99], v[16:19], v[20:23], v[96:99]
	ds_read_b128 v[16:19], v208 offset:13312
	s_waitcnt lgkmcnt(0)
	v_mfma_f32_16x16x32_bf16 v[112:115], v[16:19], v[20:23], v[112:115]
	ds_read_b128 v[16:19], v208 offset:15360
	s_waitcnt lgkmcnt(0)
	v_mfma_f32_16x16x32_bf16 v[132:135], v[16:19], v[20:23], v[124:127]
	ds_read_b128 v[16:19], v207
	ds_read_b128 v[20:23], v207 offset:2048
	ds_read_b128 v[44:47], v207 offset:4096
	ds_read_b128 v[56:59], v207 offset:6144
	ds_read_b128 v[68:71], v207 offset:8192
	ds_read_b128 v[80:83], v207 offset:10240
	ds_read_b128 v[124:127], v207 offset:12288
	s_waitcnt lgkmcnt(0)
	v_mfma_f32_16x16x32_bf16 v[16:19], v[16:19], v[164:167], v[128:131]
	s_nop 2
	ds_read_b128 v[128:131], v207 offset:14336
	v_mfma_f32_16x16x32_bf16 v[20:23], v[20:23], v[164:167], v[136:139]
	v_mfma_f32_16x16x32_bf16 v[44:47], v[44:47], v[164:167], v[140:143]
	v_mfma_f32_16x16x32_bf16 v[56:59], v[56:59], v[164:167], v[144:147]
	v_mfma_f32_16x16x32_bf16 v[68:71], v[68:71], v[164:167], v[148:151]
	v_mfma_f32_16x16x32_bf16 v[80:83], v[80:83], v[164:167], v[152:155]
	v_mfma_f32_16x16x32_bf16 v[124:127], v[124:127], v[164:167], v[156:159]
	s_waitcnt lgkmcnt(0)
	v_mfma_f32_16x16x32_bf16 v[160:163], v[128:131], v[164:167], v[160:163]
	ds_read_b128 v[128:131], v207 offset:1024
	s_waitcnt lgkmcnt(0)
	v_mfma_f32_16x16x32_bf16 v[128:131], v[128:131], v[100:103], v[16:19]
	s_nop 2
	ds_read_b128 v[16:19], v207 offset:3072
	s_waitcnt lgkmcnt(0)
	v_mfma_f32_16x16x32_bf16 v[136:139], v[16:19], v[100:103], v[20:23]
	ds_read_b128 v[16:19], v207 offset:5120
	s_waitcnt lgkmcnt(0)
	v_mfma_f32_16x16x32_bf16 v[140:143], v[16:19], v[100:103], v[44:47]
	ds_read_b128 v[16:19], v207 offset:7168
	s_waitcnt lgkmcnt(0)
	v_mfma_f32_16x16x32_bf16 v[144:147], v[16:19], v[100:103], v[56:59]
	ds_read_b128 v[16:19], v207 offset:9216
	s_waitcnt lgkmcnt(0)
	v_mfma_f32_16x16x32_bf16 v[148:151], v[16:19], v[100:103], v[68:71]
	ds_read_b128 v[16:19], v207 offset:11264
	s_waitcnt lgkmcnt(0)
	v_mfma_f32_16x16x32_bf16 v[152:155], v[16:19], v[100:103], v[80:83]
	ds_read_b128 v[16:19], v207 offset:13312
	s_waitcnt lgkmcnt(0)
	v_mfma_f32_16x16x32_bf16 v[156:159], v[16:19], v[100:103], v[124:127]
	ds_read_b128 v[16:19], v207 offset:15360
	s_waitcnt lgkmcnt(0)
	v_mfma_f32_16x16x32_bf16 v[160:163], v[16:19], v[100:103], v[160:163]
	s_movk_i32 s22, 0xab70
	s_mov_b32 s23, -1
	v_lshl_add_u64 v[20:21], v[186:187], 0, s[22:23]
	s_movk_i32 s22, 0xb000
	v_add_co_u32_e32 v56, vcc, s22, v186
	s_movk_i32 s22, 0xabf0
	s_mov_b32 s23, -1
	s_mov_b32 m0, s21
	s_waitcnt vmcnt(12)
	s_barrier
	v_lshl_add_u64 v[16:17], v[192:193], 0, s[42:43]
	v_lshl_add_u64 v[58:59], v[186:187], 0, s[22:23]
	s_movk_i32 s22, 0xaf70
	global_load_lds_dwordx4 v[16:17], off
	v_lshl_add_u64 v[16:17], v[194:195], 0, s[42:43]
	s_mov_b32 m0, s20
	s_mov_b32 s23, -1
	global_load_lds_dwordx4 v[16:17], off
	v_lshl_add_u64 v[16:17], v[192:193], 0, s[26:27]
	s_mov_b32 m0, s18
	v_lshl_add_u64 v[80:81], v[186:187], 0, s[22:23]
	s_movk_i32 s22, 0xaff0
	global_load_lds_dwordx4 v[16:17], off
	v_lshl_add_u64 v[16:17], v[194:195], 0, s[26:27]
	s_mov_b32 m0, s19
	s_mov_b32 s23, -1
	global_load_lds_dwordx4 v[16:17], off
	v_addc_co_u32_e32 v57, vcc, -1, v187, vcc
	v_lshl_add_u64 v[82:83], v[186:187], 0, s[22:23]
	global_load_dwordx4 v[16:19], v[56:57], off offset:-1168
	s_nop 0
	global_load_dwordx4 v[20:23], v[20:21], off offset:16
	s_nop 0
	global_load_dwordx4 v[68:71], v[56:57], off offset:-1040
	global_load_dwordx4 v[44:47], v[56:57], off offset:-144
	global_load_dwordx4 v[124:127], v[58:59], off offset:16
	s_nop 0
	global_load_dwordx4 v[56:59], v[56:57], off offset:-16
	s_nop 0
	global_load_dwordx4 v[100:103], v[80:81], off offset:16
	s_nop 0
	global_load_dwordx4 v[80:83], v[82:83], off offset:16
	v_cvt_pk_bf16_f32 v12, v12, v13
	v_cvt_pk_bf16_f32 v13, v14, v15
	v_cvt_pk_bf16_f32 v14, v24, v25
	v_cvt_pk_bf16_f32 v15, v26, v27
	v_cvt_pk_bf16_f32 v24, v60, v61
	v_cvt_pk_bf16_f32 v25, v62, v63
	v_cvt_pk_bf16_f32 v26, v116, v117
	v_cvt_pk_bf16_f32 v27, v118, v119
	v_cvt_pk_bf16_f32 v36, v36, v37
	v_cvt_pk_bf16_f32 v37, v38, v39
	v_cvt_pk_bf16_f32 v38, v104, v105
	v_cvt_pk_bf16_f32 v39, v106, v107
	v_cvt_pk_bf16_f32 v48, v48, v49
	v_cvt_pk_bf16_f32 v49, v50, v51
	v_cvt_pk_bf16_f32 v50, v92, v93
	v_cvt_pk_bf16_f32 v51, v94, v95
	ds_read_b128 v[60:63], v179
	ds_read_b128 v[92:95], v179 offset:2048
	s_waitcnt lgkmcnt(0)
	v_mfma_f32_16x16x32_bf16 v[8:11], v[60:63], v[12:15], v[8:11]
	ds_read_b128 v[60:63], v179 offset:4096
	v_mfma_f32_16x16x32_bf16 v[32:35], v[92:95], v[12:15], v[32:35]
	ds_read_b128 v[92:95], v179 offset:6144
	s_waitcnt lgkmcnt(0)
	v_mfma_f32_16x16x32_bf16 v[60:63], v[60:63], v[12:15], v[76:79]
	s_nop 2
	ds_read_b128 v[76:79], v179 offset:8192
	v_mfma_f32_16x16x32_bf16 v[84:87], v[92:95], v[12:15], v[84:87]
	ds_read_b128 v[92:95], v179 offset:10240
	s_waitcnt lgkmcnt(0)
	v_mfma_f32_16x16x32_bf16 v[88:91], v[76:79], v[12:15], v[88:91]
	ds_read_b128 v[76:79], v179 offset:12288
	v_mfma_f32_16x16x32_bf16 v[92:95], v[92:95], v[12:15], v[96:99]
	s_nop 2
	ds_read_b128 v[96:99], v179 offset:14336
	s_waitcnt lgkmcnt(0)
	v_mfma_f32_16x16x32_bf16 v[104:107], v[76:79], v[12:15], v[112:115]
	v_mfma_f32_16x16x32_bf16 v[12:15], v[96:99], v[12:15], v[132:135]
	ds_read_b128 v[76:79], v179 offset:1024
	s_waitcnt lgkmcnt(0)
	v_mfma_f32_16x16x32_bf16 v[8:11], v[76:79], v[24:27], v[8:11]
	ds_read_b128 v[76:79], v179 offset:3072
	s_waitcnt lgkmcnt(0)
	v_mfma_f32_16x16x32_bf16 v[32:35], v[76:79], v[24:27], v[32:35]
	ds_read_b128 v[76:79], v179 offset:5120
	s_waitcnt lgkmcnt(0)
	v_mfma_f32_16x16x32_bf16 v[76:79], v[76:79], v[24:27], v[60:63]
	s_nop 2
	ds_read_b128 v[60:63], v179 offset:7168
	s_waitcnt lgkmcnt(0)
	v_mfma_f32_16x16x32_bf16 v[84:87], v[60:63], v[24:27], v[84:87]
	ds_read_b128 v[60:63], v179 offset:9216
	s_waitcnt lgkmcnt(0)
	v_mfma_f32_16x16x32_bf16 v[88:91], v[60:63], v[24:27], v[88:91]
	ds_read_b128 v[60:63], v179 offset:11264
	s_waitcnt lgkmcnt(0)
	v_mfma_f32_16x16x32_bf16 v[92:95], v[60:63], v[24:27], v[92:95]
	ds_read_b128 v[60:63], v179 offset:13312
	s_waitcnt lgkmcnt(0)
	v_mfma_f32_16x16x32_bf16 v[104:107], v[60:63], v[24:27], v[104:107]
	ds_read_b128 v[60:63], v179 offset:15360
	s_waitcnt lgkmcnt(0)
	v_mfma_f32_16x16x32_bf16 v[116:119], v[60:63], v[24:27], v[12:15]
	s_nop 2
	ds_read_b128 v[12:15], v179 offset:16384
	ds_read_b128 v[24:27], v179 offset:18432
	ds_read_b128 v[132:135], v179 offset:28672
	ds_read_b128 v[60:63], v179 offset:20480
	ds_read_b128 v[96:99], v179 offset:22528
	ds_read_b128 v[112:115], v179 offset:24576
	s_waitcnt lgkmcnt(0)
	v_mfma_f32_16x16x32_bf16 v[12:15], v[12:15], v[36:39], v[128:131]
	s_nop 2
	ds_read_b128 v[128:131], v179 offset:26624
	v_mfma_f32_16x16x32_bf16 v[156:159], v[132:135], v[36:39], v[156:159]
	ds_read_b128 v[132:135], v179 offset:30720
	v_mfma_f32_16x16x32_bf16 v[24:27], v[24:27], v[36:39], v[136:139]
	v_mfma_f32_16x16x32_bf16 v[60:63], v[60:63], v[36:39], v[140:143]
	v_mfma_f32_16x16x32_bf16 v[96:99], v[96:99], v[36:39], v[144:147]
	v_mfma_f32_16x16x32_bf16 v[112:115], v[112:115], v[36:39], v[148:151]
	s_waitcnt lgkmcnt(0)
	v_mfma_f32_16x16x32_bf16 v[128:131], v[128:131], v[36:39], v[152:155]
	v_mfma_f32_16x16x32_bf16 v[36:39], v[132:135], v[36:39], v[160:163]
	ds_read_b128 v[132:135], v179 offset:17408
	s_waitcnt lgkmcnt(0)
	v_mfma_f32_16x16x32_bf16 v[132:135], v[132:135], v[48:51], v[12:15]
	s_nop 2
	ds_read_b128 v[12:15], v179 offset:19456
	s_waitcnt lgkmcnt(0)
	v_mfma_f32_16x16x32_bf16 v[136:139], v[12:15], v[48:51], v[24:27]
	ds_read_b128 v[12:15], v179 offset:21504
	s_waitcnt lgkmcnt(0)
	v_mfma_f32_16x16x32_bf16 v[140:143], v[12:15], v[48:51], v[60:63]
	ds_read_b128 v[12:15], v179 offset:23552
	s_waitcnt lgkmcnt(0)
	v_mfma_f32_16x16x32_bf16 v[144:147], v[12:15], v[48:51], v[96:99]
	ds_read_b128 v[12:15], v179 offset:25600
	s_waitcnt lgkmcnt(0)
	v_mfma_f32_16x16x32_bf16 v[148:151], v[12:15], v[48:51], v[112:115]
	ds_read_b128 v[12:15], v179 offset:27648
	s_waitcnt lgkmcnt(0)
	v_mfma_f32_16x16x32_bf16 v[152:155], v[12:15], v[48:51], v[128:131]
	ds_read_b128 v[12:15], v179 offset:29696
	s_waitcnt lgkmcnt(0)
	v_mfma_f32_16x16x32_bf16 v[156:159], v[12:15], v[48:51], v[156:159]
	ds_read_b128 v[12:15], v179 offset:31744
	s_waitcnt lgkmcnt(0)
	v_mfma_f32_16x16x32_bf16 v[160:163], v[12:15], v[48:51], v[36:39]
	s_movk_i32 s22, 0xbb70
	s_mov_b32 s23, -1
	v_lshl_add_u64 v[24:25], v[186:187], 0, s[22:23]
	s_movk_i32 s22, 0xc000
	v_add_co_u32_e32 v48, vcc, s22, v186
	s_movk_i32 s22, 0xbbf0
	s_mov_b32 s23, -1
	s_mov_b32 m0, s11
	s_waitcnt vmcnt(12)
	s_barrier
	v_lshl_add_u64 v[12:13], v[192:193], 0, s[28:29]
	v_lshl_add_u64 v[50:51], v[186:187], 0, s[22:23]
	s_movk_i32 s22, 0xbf70
	global_load_lds_dwordx4 v[12:13], off
	v_lshl_add_u64 v[12:13], v[194:195], 0, s[28:29]
	s_mov_b32 m0, s9
	s_mov_b32 s23, -1
	global_load_lds_dwordx4 v[12:13], off
	v_lshl_add_u64 v[12:13], v[192:193], 0, s[30:31]
	s_mov_b32 m0, s8
	v_lshl_add_u64 v[96:97], v[186:187], 0, s[22:23]
	s_movk_i32 s22, 0xbff0
	global_load_lds_dwordx4 v[12:13], off
	v_lshl_add_u64 v[12:13], v[194:195], 0, s[30:31]
	s_mov_b32 m0, s10
	s_mov_b32 s23, -1
	global_load_lds_dwordx4 v[12:13], off
	v_addc_co_u32_e32 v49, vcc, -1, v187, vcc
	v_lshl_add_u64 v[98:99], v[186:187], 0, s[22:23]
	global_load_dwordx4 v[12:15], v[48:49], off offset:-1168
	s_nop 0
	global_load_dwordx4 v[24:27], v[24:25], off offset:16
	s_nop 0
	global_load_dwordx4 v[60:63], v[48:49], off offset:-1040
	global_load_dwordx4 v[36:39], v[48:49], off offset:-144
	global_load_dwordx4 v[128:131], v[50:51], off offset:16
	s_nop 0
	global_load_dwordx4 v[48:51], v[48:49], off offset:-16
	s_nop 0
	global_load_dwordx4 v[112:115], v[96:97], off offset:16
	s_nop 0
	global_load_dwordx4 v[96:99], v[98:99], off offset:16
	v_cvt_pk_bf16_f32 v4, v4, v5
	v_cvt_pk_bf16_f32 v5, v6, v7
	v_cvt_pk_bf16_f32 v6, v28, v29
	v_cvt_pk_bf16_f32 v7, v30, v31
	v_cvt_pk_bf16_f32 v28, v64, v65
	v_cvt_pk_bf16_f32 v29, v66, v67
	v_cvt_pk_bf16_f32 v30, v120, v121
	v_cvt_pk_bf16_f32 v31, v122, v123
	v_cvt_pk_bf16_f32 v164, v40, v41
	v_cvt_pk_bf16_f32 v165, v42, v43
	v_cvt_pk_bf16_f32 v166, v108, v109
	v_cvt_pk_bf16_f32 v167, v110, v111
	v_cvt_pk_bf16_f32 v108, v52, v53
	v_cvt_pk_bf16_f32 v109, v54, v55
	v_cvt_pk_bf16_f32 v110, v72, v73
	v_cvt_pk_bf16_f32 v111, v74, v75
	ds_read_b128 v[40:43], v179 offset:32768
	ds_read_b128 v[52:55], v179 offset:34816
	s_waitcnt lgkmcnt(0)
	v_mfma_f32_16x16x32_bf16 v[8:11], v[40:43], v[4:7], v[8:11]
	ds_read_b128 v[40:43], v179 offset:36864
	v_mfma_f32_16x16x32_bf16 v[32:35], v[52:55], v[4:7], v[32:35]
	ds_read_b128 v[52:55], v179 offset:38912
	s_waitcnt lgkmcnt(0)
	v_mfma_f32_16x16x32_bf16 v[64:67], v[40:43], v[4:7], v[76:79]
	ds_read_b128 v[40:43], v179 offset:40960
	v_mfma_f32_16x16x32_bf16 v[72:75], v[52:55], v[4:7], v[84:87]
	ds_read_b128 v[52:55], v179 offset:43008
	s_waitcnt lgkmcnt(0)
	v_mfma_f32_16x16x32_bf16 v[76:79], v[40:43], v[4:7], v[88:91]
	ds_read_b128 v[40:43], v179 offset:45056
	v_mfma_f32_16x16x32_bf16 v[84:87], v[52:55], v[4:7], v[92:95]
	ds_read_b128 v[52:55], v179 offset:47104
	s_waitcnt lgkmcnt(0)
	v_mfma_f32_16x16x32_bf16 v[88:91], v[40:43], v[4:7], v[104:107]
	v_mfma_f32_16x16x32_bf16 v[4:7], v[52:55], v[4:7], v[116:119]
	ds_read_b128 v[40:43], v179 offset:33792
	s_waitcnt lgkmcnt(0)
	v_mfma_f32_16x16x32_bf16 v[40:43], v[40:43], v[28:31], v[8:11]
	s_nop 2
	ds_read_b128 v[8:11], v179 offset:35840
	s_waitcnt lgkmcnt(0)
	v_mfma_f32_16x16x32_bf16 v[52:55], v[8:11], v[28:31], v[32:35]
	ds_read_b128 v[8:11], v179 offset:37888
	s_waitcnt lgkmcnt(0)
	v_mfma_f32_16x16x32_bf16 v[64:67], v[8:11], v[28:31], v[64:67]
	ds_read_b128 v[8:11], v179 offset:39936
	s_waitcnt lgkmcnt(0)
	v_mfma_f32_16x16x32_bf16 v[72:75], v[8:11], v[28:31], v[72:75]
	ds_read_b128 v[8:11], v179 offset:41984
	s_waitcnt lgkmcnt(0)
	v_mfma_f32_16x16x32_bf16 v[92:95], v[8:11], v[28:31], v[76:79]
	ds_read_b128 v[8:11], v179 offset:44032
	s_waitcnt lgkmcnt(0)
	v_mfma_f32_16x16x32_bf16 v[104:107], v[8:11], v[28:31], v[84:87]
	ds_read_b128 v[8:11], v179 offset:46080
	s_waitcnt lgkmcnt(0)
	v_mfma_f32_16x16x32_bf16 v[116:119], v[8:11], v[28:31], v[88:91]
	ds_read_b128 v[8:11], v179 offset:48128
	s_waitcnt lgkmcnt(0)
	v_mfma_f32_16x16x32_bf16 v[120:123], v[8:11], v[28:31], v[4:7]
	s_nop 2
	ds_read_b128 v[4:7], v179 offset:49152
	ds_read_b128 v[8:11], v179 offset:51200
	ds_read_b128 v[28:31], v179 offset:53248
	ds_read_b128 v[32:35], v179 offset:55296
	ds_read_b128 v[76:79], v179 offset:57344
	ds_read_b128 v[84:87], v179 offset:59392
	ds_read_b128 v[88:91], v179 offset:61440
	s_waitcnt lgkmcnt(0)
	v_mfma_f32_16x16x32_bf16 v[4:7], v[4:7], v[164:167], v[132:135]
	s_nop 2
	ds_read_b128 v[132:135], v179 offset:63488
	v_mfma_f32_16x16x32_bf16 v[8:11], v[8:11], v[164:167], v[136:139]
	v_mfma_f32_16x16x32_bf16 v[28:31], v[28:31], v[164:167], v[140:143]
	v_mfma_f32_16x16x32_bf16 v[32:35], v[32:35], v[164:167], v[144:147]
	v_mfma_f32_16x16x32_bf16 v[76:79], v[76:79], v[164:167], v[148:151]
	v_mfma_f32_16x16x32_bf16 v[84:87], v[84:87], v[164:167], v[152:155]
	v_mfma_f32_16x16x32_bf16 v[88:91], v[88:91], v[164:167], v[156:159]
	s_waitcnt lgkmcnt(0)
	v_mfma_f32_16x16x32_bf16 v[160:163], v[132:135], v[164:167], v[160:163]
	ds_read_b128 v[132:135], v179 offset:50176
	s_waitcnt lgkmcnt(0)
	v_mfma_f32_16x16x32_bf16 v[132:135], v[132:135], v[108:111], v[4:7]
	s_nop 2
	ds_read_b128 v[4:7], v179 offset:52224
	s_waitcnt lgkmcnt(0)
	v_mfma_f32_16x16x32_bf16 v[136:139], v[4:7], v[108:111], v[8:11]
	ds_read_b128 v[4:7], v179 offset:54272
	s_waitcnt lgkmcnt(0)
	v_mfma_f32_16x16x32_bf16 v[140:143], v[4:7], v[108:111], v[28:31]
	ds_read_b128 v[4:7], v179 offset:56320
	s_waitcnt lgkmcnt(0)
	v_mfma_f32_16x16x32_bf16 v[144:147], v[4:7], v[108:111], v[32:35]
	ds_read_b128 v[4:7], v179 offset:58368
	s_waitcnt lgkmcnt(0)
	v_mfma_f32_16x16x32_bf16 v[148:151], v[4:7], v[108:111], v[76:79]
	ds_read_b128 v[4:7], v179 offset:60416
	s_waitcnt lgkmcnt(0)
	v_mfma_f32_16x16x32_bf16 v[152:155], v[4:7], v[108:111], v[84:87]
	ds_read_b128 v[4:7], v179 offset:62464
	s_waitcnt lgkmcnt(0)
	v_mfma_f32_16x16x32_bf16 v[156:159], v[4:7], v[108:111], v[88:91]
	ds_read_b128 v[4:7], v179 offset:64512
	s_waitcnt lgkmcnt(0)
	v_mfma_f32_16x16x32_bf16 v[160:163], v[4:7], v[108:111], v[160:163]
	s_movk_i32 s22, 0xcb70
	s_mov_b32 s23, -1
	v_lshl_add_u64 v[8:9], v[186:187], 0, s[22:23]
	s_movk_i32 s22, 0xd000
	v_add_co_u32_e32 v32, vcc, s22, v186
	s_movk_i32 s22, 0xcbf0
	s_mov_b32 s23, -1
	s_mov_b32 m0, s13
	s_waitcnt vmcnt(12)
	s_barrier
	v_lshl_add_u64 v[4:5], v[192:193], 0, s[34:35]
	v_lshl_add_u64 v[34:35], v[186:187], 0, s[22:23]
	s_movk_i32 s22, 0xcf70
	global_load_lds_dwordx4 v[4:5], off
	v_lshl_add_u64 v[4:5], v[194:195], 0, s[34:35]
	s_mov_b32 m0, s14
	s_mov_b32 s23, -1
	global_load_lds_dwordx4 v[4:5], off
	v_lshl_add_u64 v[4:5], v[192:193], 0, s[36:37]
	s_mov_b32 m0, s15
	v_lshl_add_u64 v[84:85], v[186:187], 0, s[22:23]
	s_movk_i32 s22, 0xcff0
	global_load_lds_dwordx4 v[4:5], off
	v_lshl_add_u64 v[4:5], v[194:195], 0, s[36:37]
	s_mov_b32 m0, s16
	s_mov_b32 s23, -1
	global_load_lds_dwordx4 v[4:5], off
	v_addc_co_u32_e32 v33, vcc, -1, v187, vcc
	v_lshl_add_u64 v[86:87], v[186:187], 0, s[22:23]
	global_load_dwordx4 v[4:7], v[32:33], off offset:-1168
	s_nop 0
	global_load_dwordx4 v[8:11], v[8:9], off offset:16
	s_nop 0
	global_load_dwordx4 v[76:79], v[32:33], off offset:-1040
	global_load_dwordx4 v[28:31], v[32:33], off offset:-144
	global_load_dwordx4 v[108:111], v[34:35], off offset:16
	s_nop 0
	global_load_dwordx4 v[32:35], v[32:33], off offset:-16
	s_nop 0
	global_load_dwordx4 v[88:91], v[84:85], off offset:16
	s_nop 0
	global_load_dwordx4 v[84:87], v[86:87], off offset:16
	v_cvt_pk_bf16_f32 v16, v16, v17
	v_cvt_pk_bf16_f32 v17, v18, v19
	v_cvt_pk_bf16_f32 v18, v20, v21
	v_cvt_pk_bf16_f32 v19, v22, v23
	v_cvt_pk_bf16_f32 v68, v68, v69
	v_cvt_pk_bf16_f32 v69, v70, v71
	v_cvt_pk_bf16_f32 v70, v124, v125
	v_cvt_pk_bf16_f32 v71, v126, v127
	v_cvt_pk_bf16_f32 v164, v44, v45
	v_cvt_pk_bf16_f32 v165, v46, v47
	v_cvt_pk_bf16_f32 v166, v100, v101
	v_cvt_pk_bf16_f32 v167, v102, v103
	v_cvt_pk_bf16_f32 v100, v56, v57
	v_cvt_pk_bf16_f32 v101, v58, v59
	v_cvt_pk_bf16_f32 v102, v80, v81
	v_cvt_pk_bf16_f32 v103, v82, v83
	ds_read_b128 v[20:23], v208
	ds_read_b128 v[44:47], v208 offset:2048
	s_waitcnt lgkmcnt(0)
	v_mfma_f32_16x16x32_bf16 v[20:23], v[20:23], v[16:19], v[40:43]
	s_nop 2
	ds_read_b128 v[40:43], v208 offset:4096
	ds_read_b128 v[56:59], v208 offset:8192
	ds_read_b128 v[80:83], v208 offset:14336
	v_mfma_f32_16x16x32_bf16 v[44:47], v[44:47], v[16:19], v[52:55]
	s_nop 2
	ds_read_b128 v[52:55], v208 offset:6144
	s_waitcnt lgkmcnt(0)
	v_mfma_f32_16x16x32_bf16 v[40:43], v[40:43], v[16:19], v[64:67]
	s_nop 2
	ds_read_b128 v[64:67], v208 offset:10240
	v_mfma_f32_16x16x32_bf16 v[52:55], v[52:55], v[16:19], v[72:75]
	s_nop 2
	ds_read_b128 v[72:75], v208 offset:12288
	v_mfma_f32_16x16x32_bf16 v[56:59], v[56:59], v[16:19], v[92:95]
	s_waitcnt lgkmcnt(0)
	v_mfma_f32_16x16x32_bf16 v[64:67], v[64:67], v[16:19], v[104:107]
	v_mfma_f32_16x16x32_bf16 v[72:75], v[72:75], v[16:19], v[116:119]
	v_mfma_f32_16x16x32_bf16 v[80:83], v[80:83], v[16:19], v[120:123]
	ds_read_b128 v[16:19], v208 offset:1024
	s_waitcnt lgkmcnt(0)
	v_mfma_f32_16x16x32_bf16 v[16:19], v[16:19], v[68:71], v[20:23]
	s_nop 2
	ds_read_b128 v[20:23], v208 offset:3072
	s_waitcnt lgkmcnt(0)
	v_mfma_f32_16x16x32_bf16 v[20:23], v[20:23], v[68:71], v[44:47]
	s_nop 2
	ds_read_b128 v[44:47], v208 offset:5120
	s_waitcnt lgkmcnt(0)
	v_mfma_f32_16x16x32_bf16 v[40:43], v[44:47], v[68:71], v[40:43]
	ds_read_b128 v[44:47], v208 offset:7168
	s_waitcnt lgkmcnt(0)
	v_mfma_f32_16x16x32_bf16 v[44:47], v[44:47], v[68:71], v[52:55]
	s_nop 2
	ds_read_b128 v[52:55], v208 offset:9216
	s_waitcnt lgkmcnt(0)
	v_mfma_f32_16x16x32_bf16 v[52:55], v[52:55], v[68:71], v[56:59]
	s_nop 2
	ds_read_b128 v[56:59], v208 offset:11264
	s_waitcnt lgkmcnt(0)
	v_mfma_f32_16x16x32_bf16 v[56:59], v[56:59], v[68:71], v[64:67]
	s_nop 2
	ds_read_b128 v[64:67], v208 offset:13312
	s_waitcnt lgkmcnt(0)
	v_mfma_f32_16x16x32_bf16 v[64:67], v[64:67], v[68:71], v[72:75]
	s_nop 2
	ds_read_b128 v[72:75], v208 offset:15360
	s_waitcnt lgkmcnt(0)
	v_mfma_f32_16x16x32_bf16 v[124:127], v[72:75], v[68:71], v[80:83]
	ds_read_b128 v[68:71], v207
	ds_read_b128 v[72:75], v207 offset:2048
	s_nop 0
	ds_read_b128 v[80:83], v207 offset:4096
	ds_read_b128 v[92:95], v207 offset:6144
	ds_read_b128 v[104:107], v207 offset:8192
	ds_read_b128 v[116:119], v207 offset:10240
	ds_read_b128 v[120:123], v207 offset:12288
	s_waitcnt lgkmcnt(0)
	v_mfma_f32_16x16x32_bf16 v[68:71], v[68:71], v[164:167], v[132:135]
	s_nop 2
	ds_read_b128 v[132:135], v207 offset:14336
	v_mfma_f32_16x16x32_bf16 v[72:75], v[72:75], v[164:167], v[136:139]
	v_mfma_f32_16x16x32_bf16 v[80:83], v[80:83], v[164:167], v[140:143]
	v_mfma_f32_16x16x32_bf16 v[92:95], v[92:95], v[164:167], v[144:147]
	v_mfma_f32_16x16x32_bf16 v[104:107], v[104:107], v[164:167], v[148:151]
	v_mfma_f32_16x16x32_bf16 v[116:119], v[116:119], v[164:167], v[152:155]
	v_mfma_f32_16x16x32_bf16 v[120:123], v[120:123], v[164:167], v[156:159]
	s_waitcnt lgkmcnt(0)
	v_mfma_f32_16x16x32_bf16 v[160:163], v[132:135], v[164:167], v[160:163]
	ds_read_b128 v[132:135], v207 offset:1024
	s_waitcnt lgkmcnt(0)
	v_mfma_f32_16x16x32_bf16 v[132:135], v[132:135], v[100:103], v[68:71]
	s_nop 2
	ds_read_b128 v[68:71], v207 offset:3072
	s_waitcnt lgkmcnt(0)
	v_mfma_f32_16x16x32_bf16 v[136:139], v[68:71], v[100:103], v[72:75]
	ds_read_b128 v[68:71], v207 offset:5120
	s_waitcnt lgkmcnt(0)
	v_mfma_f32_16x16x32_bf16 v[140:143], v[68:71], v[100:103], v[80:83]
	ds_read_b128 v[68:71], v207 offset:7168
	s_waitcnt lgkmcnt(0)
	v_mfma_f32_16x16x32_bf16 v[144:147], v[68:71], v[100:103], v[92:95]
	ds_read_b128 v[68:71], v207 offset:9216
	s_waitcnt lgkmcnt(0)
	v_mfma_f32_16x16x32_bf16 v[148:151], v[68:71], v[100:103], v[104:107]
	ds_read_b128 v[68:71], v207 offset:11264
	s_waitcnt lgkmcnt(0)
	v_mfma_f32_16x16x32_bf16 v[152:155], v[68:71], v[100:103], v[116:119]
	ds_read_b128 v[68:71], v207 offset:13312
	s_waitcnt lgkmcnt(0)
	v_mfma_f32_16x16x32_bf16 v[156:159], v[68:71], v[100:103], v[120:123]
	ds_read_b128 v[68:71], v207 offset:15360
	s_waitcnt lgkmcnt(0)
	v_mfma_f32_16x16x32_bf16 v[160:163], v[68:71], v[100:103], v[160:163]
	s_movk_i32 s22, 0xdb70
	s_mov_b32 s23, -1
	v_lshl_add_u64 v[72:73], v[186:187], 0, s[22:23]
	s_movk_i32 s22, 0xe000
	v_add_co_u32_e32 v92, vcc, s22, v186
	s_movk_i32 s22, 0xdbf0
	s_mov_b32 s23, -1
	s_mov_b32 m0, s21
	s_waitcnt vmcnt(12)
	s_barrier
	v_lshl_add_u64 v[68:69], v[192:193], 0, s[38:39]
	v_lshl_add_u64 v[94:95], v[186:187], 0, s[22:23]
	s_movk_i32 s22, 0xdf70
	global_load_lds_dwordx4 v[68:69], off
	v_lshl_add_u64 v[68:69], v[194:195], 0, s[38:39]
	s_mov_b32 m0, s20
	s_mov_b32 s23, -1
	global_load_lds_dwordx4 v[68:69], off
	v_lshl_add_u64 v[68:69], v[192:193], 0, s[40:41]
	s_mov_b32 m0, s18
	v_lshl_add_u64 v[104:105], v[186:187], 0, s[22:23]
	s_movk_i32 s22, 0xdff0
	global_load_lds_dwordx4 v[68:69], off
	v_lshl_add_u64 v[68:69], v[194:195], 0, s[40:41]
	s_mov_b32 m0, s19
	s_mov_b32 s23, -1
	global_load_lds_dwordx4 v[68:69], off
	v_addc_co_u32_e32 v93, vcc, -1, v187, vcc
	v_lshl_add_u64 v[106:107], v[186:187], 0, s[22:23]
	global_load_dwordx4 v[68:71], v[92:93], off offset:-1168
	s_nop 0
	global_load_dwordx4 v[72:75], v[72:73], off offset:16
	s_nop 0
	global_load_dwordx4 v[100:103], v[92:93], off offset:-1040
	global_load_dwordx4 v[80:83], v[92:93], off offset:-144
	global_load_dwordx4 v[120:123], v[94:95], off offset:16
	s_nop 0
	global_load_dwordx4 v[92:95], v[92:93], off offset:-16
	s_nop 0
	global_load_dwordx4 v[116:119], v[104:105], off offset:16
	s_nop 0
	global_load_dwordx4 v[104:107], v[106:107], off offset:16
	v_cvt_pk_bf16_f32 v12, v12, v13
	v_cvt_pk_bf16_f32 v13, v14, v15
	v_cvt_pk_bf16_f32 v14, v24, v25
	v_cvt_pk_bf16_f32 v15, v26, v27
	v_cvt_pk_bf16_f32 v60, v60, v61
	v_cvt_pk_bf16_f32 v61, v62, v63
	v_cvt_pk_bf16_f32 v62, v128, v129
	v_cvt_pk_bf16_f32 v63, v130, v131
	v_cvt_pk_bf16_f32 v36, v36, v37
	v_cvt_pk_bf16_f32 v37, v38, v39
	v_cvt_pk_bf16_f32 v38, v112, v113
	v_cvt_pk_bf16_f32 v39, v114, v115
	v_cvt_pk_bf16_f32 v48, v48, v49
	v_cvt_pk_bf16_f32 v49, v50, v51
	v_cvt_pk_bf16_f32 v50, v96, v97
	v_cvt_pk_bf16_f32 v51, v98, v99
	ds_read_b128 v[24:27], v179
	ds_read_b128 v[96:99], v179 offset:2048
	s_waitcnt lgkmcnt(0)
	v_mfma_f32_16x16x32_bf16 v[16:19], v[24:27], v[12:15], v[16:19]
	ds_read_b128 v[24:27], v179 offset:4096
	v_mfma_f32_16x16x32_bf16 v[20:23], v[96:99], v[12:15], v[20:23]
	ds_read_b128 v[96:99], v179 offset:6144
	s_waitcnt lgkmcnt(0)
	v_mfma_f32_16x16x32_bf16 v[24:27], v[24:27], v[12:15], v[40:43]
	s_nop 2
	ds_read_b128 v[40:43], v179 offset:8192
	v_mfma_f32_16x16x32_bf16 v[44:47], v[96:99], v[12:15], v[44:47]
	ds_read_b128 v[96:99], v179 offset:10240
	s_waitcnt lgkmcnt(0)
	v_mfma_f32_16x16x32_bf16 v[40:43], v[40:43], v[12:15], v[52:55]
	s_nop 2
	ds_read_b128 v[52:55], v179 offset:12288
	v_mfma_f32_16x16x32_bf16 v[56:59], v[96:99], v[12:15], v[56:59]
	ds_read_b128 v[96:99], v179 offset:14336
	s_waitcnt lgkmcnt(0)
	v_mfma_f32_16x16x32_bf16 v[52:55], v[52:55], v[12:15], v[64:67]
	v_mfma_f32_16x16x32_bf16 v[64:67], v[96:99], v[12:15], v[124:127]
	ds_read_b128 v[12:15], v179 offset:1024
	s_waitcnt lgkmcnt(0)
	v_mfma_f32_16x16x32_bf16 v[12:15], v[12:15], v[60:63], v[16:19]
	s_nop 2
	ds_read_b128 v[16:19], v179 offset:3072
	s_waitcnt lgkmcnt(0)
	v_mfma_f32_16x16x32_bf16 v[16:19], v[16:19], v[60:63], v[20:23]
	s_nop 2
	ds_read_b128 v[20:23], v179 offset:5120
	s_waitcnt lgkmcnt(0)
	v_mfma_f32_16x16x32_bf16 v[20:23], v[20:23], v[60:63], v[24:27]
	s_nop 2
	ds_read_b128 v[24:27], v179 offset:7168
	s_waitcnt lgkmcnt(0)
	v_mfma_f32_16x16x32_bf16 v[24:27], v[24:27], v[60:63], v[44:47]
	s_nop 2
	ds_read_b128 v[44:47], v179 offset:9216
	s_waitcnt lgkmcnt(0)
	v_mfma_f32_16x16x32_bf16 v[96:99], v[44:47], v[60:63], v[40:43]
	s_nop 2
	ds_read_b128 v[40:43], v179 offset:11264
	s_waitcnt lgkmcnt(0)
	v_mfma_f32_16x16x32_bf16 v[112:115], v[40:43], v[60:63], v[56:59]
	ds_read_b128 v[40:43], v179 offset:13312
	s_waitcnt lgkmcnt(0)
	v_mfma_f32_16x16x32_bf16 v[124:127], v[40:43], v[60:63], v[52:55]
	ds_read_b128 v[40:43], v179 offset:15360
	s_waitcnt lgkmcnt(0)
	v_mfma_f32_16x16x32_bf16 v[128:131], v[40:43], v[60:63], v[64:67]
	ds_read_b128 v[40:43], v179 offset:16384
	ds_read_b128 v[44:47], v179 offset:18432
	ds_read_b128 v[52:55], v179 offset:20480
	ds_read_b128 v[56:59], v179 offset:22528
	ds_read_b128 v[60:63], v179 offset:24576
	ds_read_b128 v[64:67], v179 offset:26624
	s_waitcnt lgkmcnt(0)
	v_mfma_f32_16x16x32_bf16 v[40:43], v[40:43], v[36:39], v[132:135]
	s_nop 2
	ds_read_b128 v[132:135], v179 offset:28672
	v_mfma_f32_16x16x32_bf16 v[44:47], v[44:47], v[36:39], v[136:139]
	v_mfma_f32_16x16x32_bf16 v[52:55], v[52:55], v[36:39], v[140:143]
	s_waitcnt lgkmcnt(0)
	v_mfma_f32_16x16x32_bf16 v[156:159], v[132:135], v[36:39], v[156:159]
	ds_read_b128 v[132:135], v179 offset:30720
	v_mfma_f32_16x16x32_bf16 v[56:59], v[56:59], v[36:39], v[144:147]
	v_mfma_f32_16x16x32_bf16 v[60:63], v[60:63], v[36:39], v[148:151]
	v_mfma_f32_16x16x32_bf16 v[64:67], v[64:67], v[36:39], v[152:155]
	s_waitcnt lgkmcnt(0)
	v_mfma_f32_16x16x32_bf16 v[36:39], v[132:135], v[36:39], v[160:163]
	ds_read_b128 v[132:135], v179 offset:17408
	s_waitcnt lgkmcnt(0)
	v_mfma_f32_16x16x32_bf16 v[132:135], v[132:135], v[48:51], v[40:43]
	s_nop 2
	ds_read_b128 v[40:43], v179 offset:19456
	s_waitcnt lgkmcnt(0)
	v_mfma_f32_16x16x32_bf16 v[136:139], v[40:43], v[48:51], v[44:47]
	ds_read_b128 v[40:43], v179 offset:21504
	s_waitcnt lgkmcnt(0)
	v_mfma_f32_16x16x32_bf16 v[140:143], v[40:43], v[48:51], v[52:55]
	ds_read_b128 v[40:43], v179 offset:23552
	s_waitcnt lgkmcnt(0)
	v_mfma_f32_16x16x32_bf16 v[144:147], v[40:43], v[48:51], v[56:59]
	ds_read_b128 v[40:43], v179 offset:25600
	s_waitcnt lgkmcnt(0)
	v_mfma_f32_16x16x32_bf16 v[148:151], v[40:43], v[48:51], v[60:63]
	ds_read_b128 v[40:43], v179 offset:27648
	s_waitcnt lgkmcnt(0)
	v_mfma_f32_16x16x32_bf16 v[152:155], v[40:43], v[48:51], v[64:67]
	ds_read_b128 v[40:43], v179 offset:29696
	s_waitcnt lgkmcnt(0)
	v_mfma_f32_16x16x32_bf16 v[156:159], v[40:43], v[48:51], v[156:159]
	ds_read_b128 v[40:43], v179 offset:31744
	s_waitcnt lgkmcnt(0)
	v_mfma_f32_16x16x32_bf16 v[160:163], v[40:43], v[48:51], v[36:39]
	s_mov_b32 m0, s11
	s_waitcnt vmcnt(12)
	s_barrier
	v_lshl_add_u64 v[36:37], v[192:193], 0, s[44:45]
	global_load_lds_dwordx4 v[36:37], off
	v_lshl_add_u64 v[36:37], v[194:195], 0, s[44:45]
	s_mov_b32 m0, s9
	s_movk_i32 s22, 0xeb70
	global_load_lds_dwordx4 v[36:37], off
	v_lshl_add_u64 v[36:37], v[192:193], 0, s[46:47]
	s_mov_b32 m0, s8
	s_mov_b32 s23, -1
	global_load_lds_dwordx4 v[36:37], off
	v_lshl_add_u64 v[36:37], v[194:195], 0, s[46:47]
	s_mov_b32 m0, s10
	s_nop 0
	global_load_lds_dwordx4 v[36:37], off
	v_lshl_add_u64 v[36:37], v[186:187], 0, s[22:23]
	s_movk_i32 s22, 0xf000
	v_add_co_u32_e32 v38, vcc, s22, v186
	s_movk_i32 s22, 0xebf0
	s_nop 0
	v_addc_co_u32_e32 v39, vcc, -1, v187, vcc
	s_mov_b32 s23, -1
	global_load_dwordx4 v[60:63], v[38:39], off offset:-1168
	global_load_dwordx4 v[44:47], v[36:37], off offset:16
	v_lshl_add_u64 v[36:37], v[186:187], 0, s[22:23]
	s_movk_i32 s22, 0xef70
	s_mov_b32 s23, -1
	v_lshl_add_u64 v[52:53], v[186:187], 0, s[22:23]
	global_load_dwordx4 v[64:67], v[38:39], off offset:-1040
	global_load_dwordx4 v[48:51], v[38:39], off offset:-144
	global_load_dwordx4 v[56:59], v[36:37], off offset:16
	global_load_dwordx4 v[40:43], v[38:39], off offset:-16
	s_nop 0
	global_load_dwordx4 v[52:55], v[52:53], off offset:16
	s_nop 0
	global_load_dwordx4 v[36:39], v[186:187], off offset:-4096
	v_cvt_pk_bf16_f32 v4, v4, v5
	v_cvt_pk_bf16_f32 v5, v6, v7
	v_cvt_pk_bf16_f32 v6, v8, v9
	v_cvt_pk_bf16_f32 v7, v10, v11
	v_cvt_pk_bf16_f32 v8, v76, v77
	v_cvt_pk_bf16_f32 v9, v78, v79
	v_cvt_pk_bf16_f32 v10, v108, v109
	v_cvt_pk_bf16_f32 v11, v110, v111
	v_cvt_pk_bf16_f32 v28, v28, v29
	v_cvt_pk_bf16_f32 v29, v30, v31
	v_cvt_pk_bf16_f32 v30, v88, v89
	v_cvt_pk_bf16_f32 v31, v90, v91
	v_cvt_pk_bf16_f32 v32, v32, v33
	v_cvt_pk_bf16_f32 v33, v34, v35
	v_cvt_pk_bf16_f32 v34, v84, v85
	v_cvt_pk_bf16_f32 v35, v86, v87
	ds_read_b128 v[76:79], v179 offset:32768
	ds_read_b128 v[84:87], v179 offset:34816
	s_waitcnt lgkmcnt(0)
	v_mfma_f32_16x16x32_bf16 v[12:15], v[76:79], v[4:7], v[12:15]
	ds_read_b128 v[76:79], v179 offset:36864
	v_mfma_f32_16x16x32_bf16 v[16:19], v[84:87], v[4:7], v[16:19]
	ds_read_b128 v[84:87], v179 offset:38912
	s_waitcnt lgkmcnt(0)
	v_mfma_f32_16x16x32_bf16 v[20:23], v[76:79], v[4:7], v[20:23]
	ds_read_b128 v[76:79], v179 offset:40960
	v_mfma_f32_16x16x32_bf16 v[24:27], v[84:87], v[4:7], v[24:27]
	ds_read_b128 v[84:87], v179 offset:43008
	s_waitcnt lgkmcnt(0)
	v_mfma_f32_16x16x32_bf16 v[108:111], v[76:79], v[4:7], v[96:99]
	ds_read_b128 v[76:79], v179 offset:45056
	v_mfma_f32_16x16x32_bf16 v[112:115], v[84:87], v[4:7], v[112:115]
	ds_read_b128 v[84:87], v179 offset:47104
	s_waitcnt lgkmcnt(0)
	v_mfma_f32_16x16x32_bf16 v[124:127], v[76:79], v[4:7], v[124:127]
	v_mfma_f32_16x16x32_bf16 v[4:7], v[84:87], v[4:7], v[128:131]
	ds_read_b128 v[76:79], v179 offset:33792
	s_waitcnt lgkmcnt(0)
	v_mfma_f32_16x16x32_bf16 v[76:79], v[76:79], v[8:11], v[12:15]
	s_nop 2
	ds_read_b128 v[12:15], v179 offset:35840
	s_waitcnt lgkmcnt(0)
	v_mfma_f32_16x16x32_bf16 v[84:87], v[12:15], v[8:11], v[16:19]
	ds_read_b128 v[12:15], v179 offset:37888
	s_waitcnt lgkmcnt(0)
	v_mfma_f32_16x16x32_bf16 v[88:91], v[12:15], v[8:11], v[20:23]
	ds_read_b128 v[12:15], v179 offset:39936
	s_waitcnt lgkmcnt(0)
	v_mfma_f32_16x16x32_bf16 v[96:99], v[12:15], v[8:11], v[24:27]
	ds_read_b128 v[12:15], v179 offset:41984
	s_waitcnt lgkmcnt(0)
	v_mfma_f32_16x16x32_bf16 v[108:111], v[12:15], v[8:11], v[108:111]
	ds_read_b128 v[12:15], v179 offset:44032
	s_waitcnt lgkmcnt(0)
	v_mfma_f32_16x16x32_bf16 v[112:115], v[12:15], v[8:11], v[112:115]
	ds_read_b128 v[12:15], v179 offset:46080
	s_waitcnt lgkmcnt(0)
	v_mfma_f32_16x16x32_bf16 v[124:127], v[12:15], v[8:11], v[124:127]
	ds_read_b128 v[12:15], v179 offset:48128
	s_waitcnt lgkmcnt(0)
	v_mfma_f32_16x16x32_bf16 v[128:131], v[12:15], v[8:11], v[4:7]
	s_nop 2
	ds_read_b128 v[4:7], v179 offset:49152
	ds_read_b128 v[8:11], v179 offset:51200
	ds_read_b128 v[12:15], v179 offset:53248
	ds_read_b128 v[16:19], v179 offset:55296
	ds_read_b128 v[20:23], v179 offset:57344
	ds_read_b128 v[24:27], v179 offset:59392
	s_waitcnt lgkmcnt(0)
	v_mfma_f32_16x16x32_bf16 v[4:7], v[4:7], v[28:31], v[132:135]
	s_nop 2
	ds_read_b128 v[132:135], v179 offset:61440
	v_mfma_f32_16x16x32_bf16 v[8:11], v[8:11], v[28:31], v[136:139]
	s_nop 2
	ds_read_b128 v[136:139], v179 offset:63488
	v_mfma_f32_16x16x32_bf16 v[12:15], v[12:15], v[28:31], v[140:143]
	v_mfma_f32_16x16x32_bf16 v[16:19], v[16:19], v[28:31], v[144:147]
	v_mfma_f32_16x16x32_bf16 v[20:23], v[20:23], v[28:31], v[148:151]
	v_mfma_f32_16x16x32_bf16 v[24:27], v[24:27], v[28:31], v[152:155]
	s_waitcnt lgkmcnt(0)
	v_mfma_f32_16x16x32_bf16 v[132:135], v[132:135], v[28:31], v[156:159]
	v_mfma_f32_16x16x32_bf16 v[28:31], v[136:139], v[28:31], v[160:163]
	ds_read_b128 v[136:139], v179 offset:50176
	s_waitcnt lgkmcnt(0)
	v_mfma_f32_16x16x32_bf16 v[136:139], v[136:139], v[32:35], v[4:7]
	s_nop 2
	ds_read_b128 v[4:7], v179 offset:52224
	s_waitcnt lgkmcnt(0)
	v_mfma_f32_16x16x32_bf16 v[140:143], v[4:7], v[32:35], v[8:11]
	ds_read_b128 v[4:7], v179 offset:54272
	s_waitcnt lgkmcnt(0)
	v_mfma_f32_16x16x32_bf16 v[144:147], v[4:7], v[32:35], v[12:15]
	ds_read_b128 v[4:7], v179 offset:56320
	s_waitcnt lgkmcnt(0)
	v_mfma_f32_16x16x32_bf16 v[148:151], v[4:7], v[32:35], v[16:19]
	ds_read_b128 v[4:7], v179 offset:58368
	s_waitcnt lgkmcnt(0)
	v_mfma_f32_16x16x32_bf16 v[152:155], v[4:7], v[32:35], v[20:23]
	ds_read_b128 v[4:7], v179 offset:60416
	s_waitcnt lgkmcnt(0)
	v_mfma_f32_16x16x32_bf16 v[156:159], v[4:7], v[32:35], v[24:27]
	ds_read_b128 v[4:7], v179 offset:62464
	s_waitcnt lgkmcnt(0)
	v_mfma_f32_16x16x32_bf16 v[132:135], v[4:7], v[32:35], v[132:135]
	ds_read_b128 v[4:7], v179 offset:64512
	s_waitcnt lgkmcnt(0)
	v_mfma_f32_16x16x32_bf16 v[160:163], v[4:7], v[32:35], v[28:31]
	s_mov_b32 m0, s13
	s_waitcnt vmcnt(12)
	s_barrier
	v_lshl_add_u64 v[4:5], v[192:193], 0, s[48:49]
	global_load_lds_dwordx4 v[4:5], off
	v_lshl_add_u64 v[4:5], v[194:195], 0, s[48:49]
	s_mov_b32 m0, s14
	s_nop 0
	global_load_lds_dwordx4 v[4:5], off
	v_lshl_add_u64 v[4:5], v[192:193], 0, s[50:51]
	s_mov_b32 m0, s15
	s_nop 0
	global_load_lds_dwordx4 v[4:5], off
	v_lshl_add_u64 v[4:5], v[194:195], 0, s[50:51]
	s_mov_b32 m0, s16
	s_nop 0
	global_load_lds_dwordx4 v[4:5], off
	global_load_dwordx4 v[12:15], v[186:187], off offset:-1152
	global_load_dwordx4 v[24:27], v[186:187], off offset:-1168
	global_load_dwordx4 v[32:35], v[186:187], off offset:-1024
	global_load_dwordx4 v[28:31], v[186:187], off offset:-1040
	global_load_dwordx4 v[20:23], v[186:187], off offset:-128
	global_load_dwordx4 v[16:19], v[186:187], off offset:-144
	global_load_dwordx4 v[4:7], v[186:187], off
	global_load_dwordx4 v[8:11], v[186:187], off offset:-16
	v_cvt_pk_bf16_f32 v68, v68, v69
	v_cvt_pk_bf16_f32 v69, v70, v71
	v_cvt_pk_bf16_f32 v70, v72, v73
	v_cvt_pk_bf16_f32 v71, v74, v75
	v_cvt_pk_bf16_f32 v72, v100, v101
	v_cvt_pk_bf16_f32 v73, v102, v103
	v_cvt_pk_bf16_f32 v74, v120, v121
	v_cvt_pk_bf16_f32 v75, v122, v123
	v_cvt_pk_bf16_f32 v80, v80, v81
	v_cvt_pk_bf16_f32 v81, v82, v83
	v_cvt_pk_bf16_f32 v82, v116, v117
	v_cvt_pk_bf16_f32 v83, v118, v119
	v_cvt_pk_bf16_f32 v164, v92, v93
	v_cvt_pk_bf16_f32 v165, v94, v95
	v_cvt_pk_bf16_f32 v166, v104, v105
	v_cvt_pk_bf16_f32 v167, v106, v107
	ds_read_b128 v[92:95], v208
	ds_read_b128 v[100:103], v208 offset:2048
	s_waitcnt lgkmcnt(0)
	v_mfma_f32_16x16x32_bf16 v[76:79], v[92:95], v[68:71], v[76:79]
	ds_read_b128 v[92:95], v208 offset:4096
	ds_read_b128 v[104:107], v208 offset:12288
	v_mfma_f32_16x16x32_bf16 v[84:87], v[100:103], v[68:71], v[84:87]
	ds_read_b128 v[100:103], v208 offset:6144
	s_waitcnt lgkmcnt(0)
	v_mfma_f32_16x16x32_bf16 v[88:91], v[92:95], v[68:71], v[88:91]
	ds_read_b128 v[92:95], v208 offset:8192
	v_mfma_f32_16x16x32_bf16 v[96:99], v[100:103], v[68:71], v[96:99]
	ds_read_b128 v[100:103], v208 offset:10240
	s_waitcnt lgkmcnt(0)
	v_mfma_f32_16x16x32_bf16 v[120:123], v[100:103], v[68:71], v[112:115]
	ds_read_b128 v[100:103], v208 offset:14336
	v_mfma_f32_16x16x32_bf16 v[92:95], v[92:95], v[68:71], v[108:111]
	v_mfma_f32_16x16x32_bf16 v[124:127], v[104:107], v[68:71], v[124:127]
	s_waitcnt lgkmcnt(0)
	v_mfma_f32_16x16x32_bf16 v[68:71], v[100:103], v[68:71], v[128:131]
	ds_read_b128 v[100:103], v208 offset:1024
	s_waitcnt lgkmcnt(0)
	v_mfma_f32_16x16x32_bf16 v[100:103], v[100:103], v[72:75], v[76:79]
	s_nop 2
	ds_read_b128 v[76:79], v208 offset:3072
	s_waitcnt lgkmcnt(0)
	v_mfma_f32_16x16x32_bf16 v[104:107], v[76:79], v[72:75], v[84:87]
	ds_read_b128 v[76:79], v208 offset:5120
	s_waitcnt lgkmcnt(0)
	v_mfma_f32_16x16x32_bf16 v[108:111], v[76:79], v[72:75], v[88:91]
	ds_read_b128 v[76:79], v208 offset:7168
	s_waitcnt lgkmcnt(0)
	v_mfma_f32_16x16x32_bf16 v[112:115], v[76:79], v[72:75], v[96:99]
	ds_read_b128 v[76:79], v208 offset:9216
	s_waitcnt lgkmcnt(0)
	v_mfma_f32_16x16x32_bf16 v[116:119], v[76:79], v[72:75], v[92:95]
	ds_read_b128 v[76:79], v208 offset:11264
	s_waitcnt lgkmcnt(0)
	v_mfma_f32_16x16x32_bf16 v[120:123], v[76:79], v[72:75], v[120:123]
	ds_read_b128 v[76:79], v208 offset:13312
	s_waitcnt lgkmcnt(0)
	v_mfma_f32_16x16x32_bf16 v[124:127], v[76:79], v[72:75], v[124:127]
	ds_read_b128 v[76:79], v208 offset:15360
	s_waitcnt lgkmcnt(0)
	v_mfma_f32_16x16x32_bf16 v[128:131], v[76:79], v[72:75], v[68:71]
	s_nop 2
	ds_read_b128 v[68:71], v207
	ds_read_b128 v[72:75], v207 offset:2048
	ds_read_b128 v[88:91], v207 offset:8192
	ds_read_b128 v[76:79], v207 offset:4096
	ds_read_b128 v[84:87], v207 offset:6144
	s_waitcnt lgkmcnt(0)
	v_mfma_f32_16x16x32_bf16 v[68:71], v[68:71], v[80:83], v[136:139]
	v_mfma_f32_16x16x32_bf16 v[136:139], v[88:91], v[80:83], v[152:155]
	ds_read_b128 v[88:91], v207 offset:10240
	v_mfma_f32_16x16x32_bf16 v[72:75], v[72:75], v[80:83], v[140:143]
	s_waitcnt lgkmcnt(0)
	v_mfma_f32_16x16x32_bf16 v[140:143], v[88:91], v[80:83], v[156:159]
	ds_read_b128 v[88:91], v207 offset:12288
	s_waitcnt lgkmcnt(0)
	v_mfma_f32_16x16x32_bf16 v[132:135], v[88:91], v[80:83], v[132:135]
	ds_read_b128 v[88:91], v207 offset:14336
	v_mfma_f32_16x16x32_bf16 v[76:79], v[76:79], v[80:83], v[144:147]
	v_mfma_f32_16x16x32_bf16 v[84:87], v[84:87], v[80:83], v[148:151]
	s_waitcnt lgkmcnt(0)
	v_mfma_f32_16x16x32_bf16 v[144:147], v[88:91], v[80:83], v[160:163]
	ds_read_b128 v[80:83], v207 offset:1024
	s_waitcnt lgkmcnt(0)
	v_mfma_f32_16x16x32_bf16 v[96:99], v[80:83], v[164:167], v[68:71]
	s_nop 2
	ds_read_b128 v[68:71], v207 offset:3072
	s_waitcnt lgkmcnt(0)
	v_mfma_f32_16x16x32_bf16 v[92:95], v[68:71], v[164:167], v[72:75]
	ds_read_b128 v[68:71], v207 offset:5120
	s_waitcnt lgkmcnt(0)
	v_mfma_f32_16x16x32_bf16 v[88:91], v[68:71], v[164:167], v[76:79]
	ds_read_b128 v[68:71], v207 offset:7168
	s_waitcnt lgkmcnt(0)
	v_mfma_f32_16x16x32_bf16 v[84:87], v[68:71], v[164:167], v[84:87]
	ds_read_b128 v[68:71], v207 offset:9216
	s_waitcnt lgkmcnt(0)
	v_mfma_f32_16x16x32_bf16 v[80:83], v[68:71], v[164:167], v[136:139]
	ds_read_b128 v[68:71], v207 offset:11264
	s_waitcnt lgkmcnt(0)
	v_mfma_f32_16x16x32_bf16 v[76:79], v[68:71], v[164:167], v[140:143]
	ds_read_b128 v[68:71], v207 offset:13312
	s_waitcnt lgkmcnt(0)
	v_mfma_f32_16x16x32_bf16 v[72:75], v[68:71], v[164:167], v[132:135]
	ds_read_b128 v[68:71], v207 offset:15360
	s_waitcnt lgkmcnt(0)
	v_mfma_f32_16x16x32_bf16 v[68:71], v[68:71], v[164:167], v[144:147]
	s_add_i32 s17, s17, 12
	s_add_u32 s0, s0, 0x600
	s_addc_u32 s1, s1, 0
	s_mov_b64 s[22:23], 0xc000
	s_cmp_gt_u32 s17, 47
	v_lshl_add_u64 v[186:187], v[186:187], 0, s[22:23]
	s_cbranch_scc0 .LBB0_564
	s_add_u32 s0, s6, 0x9301f00
	s_addc_u32 s1, s7, 0
	s_mov_b32 m0, s21
	s_waitcnt vmcnt(12)
	s_barrier
	v_lshl_add_u64 v[132:133], s[0:1], 0, v[2:3]
	global_load_lds_dwordx4 v[132:133], off
	v_lshl_add_u64 v[132:133], s[0:1], 0, v[184:185]
	s_add_u32 s0, s6, 0x9401f00
	s_mov_b32 m0, s20
	s_addc_u32 s1, s7, 0
	global_load_lds_dwordx4 v[132:133], off
	v_lshl_add_u64 v[132:133], s[0:1], 0, v[2:3]
	s_mov_b32 m0, s18
	s_nop 0
	global_load_lds_dwordx4 v[132:133], off
	v_lshl_add_u64 v[132:133], s[0:1], 0, v[184:185]
	s_mov_b32 m0, s19
	s_mov_b64 s[0:1], 0x3e000
	global_load_lds_dwordx4 v[132:133], off
	v_lshl_add_u64 v[132:133], v[182:183], 0, s[0:1]
	s_mov_b32 s0, 0x3e000
	v_add_co_u32_e32 v148, vcc, s0, v182
	s_mov_b32 s0, 0x3f000
	s_nop 0
	v_addc_co_u32_e32 v149, vcc, 0, v183, vcc
	v_add_co_u32_e32 v164, vcc, s0, v182
	s_mov_b64 s[0:1], 0x3e080
	v_lshl_add_u64 v[140:141], v[182:183], 0, s[0:1]
	s_mov_b64 s[0:1], 0x3e400
	v_lshl_add_u64 v[142:143], v[182:183], 0, s[0:1]
	s_mov_b64 s[0:1], 0x3e480
	v_lshl_add_u64 v[152:153], v[182:183], 0, s[0:1]
	v_addc_co_u32_e32 v165, vcc, 0, v183, vcc
	global_load_dwordx4 v[136:139], v[132:133], off offset:16
	s_nop 0
	global_load_dwordx4 v[132:135], v[148:149], off offset:128
	global_load_dwordx4 v[144:147], v[140:141], off offset:16
	s_nop 0
	global_load_dwordx4 v[140:143], v[142:143], off offset:16
	s_nop 0
	global_load_dwordx4 v[156:159], v[148:149], off offset:1024
	s_nop 0
	global_load_dwordx4 v[148:151], v[148:149], off offset:1152
	s_nop 0
	global_load_dwordx4 v[160:163], v[164:165], off offset:-4096
	s_nop 0
	global_load_dwordx4 v[152:155], v[152:153], off offset:16
	v_cvt_pk_bf16_f32 v60, v60, v61
	v_cvt_pk_bf16_f32 v61, v62, v63
	v_cvt_pk_bf16_f32 v62, v44, v45
	v_cvt_pk_bf16_f32 v63, v46, v47
	v_cvt_pk_bf16_f32 v44, v64, v65
	v_cvt_pk_bf16_f32 v45, v66, v67
	v_cvt_pk_bf16_f32 v46, v56, v57
	v_cvt_pk_bf16_f32 v47, v58, v59
	v_cvt_pk_bf16_f32 v48, v48, v49
	v_cvt_pk_bf16_f32 v49, v50, v51
	v_cvt_pk_bf16_f32 v50, v52, v53
	v_cvt_pk_bf16_f32 v51, v54, v55
	v_cvt_pk_bf16_f32 v40, v40, v41
	v_cvt_pk_bf16_f32 v41, v42, v43
	v_cvt_pk_bf16_f32 v42, v36, v37
	v_cvt_pk_bf16_f32 v43, v38, v39
	ds_read_b128 v[36:39], v179
	ds_read_b128 v[52:55], v179 offset:2048
	s_waitcnt lgkmcnt(0)
	v_mfma_f32_16x16x32_bf16 v[36:39], v[36:39], v[60:63], v[100:103]
	s_nop 2
	ds_read_b128 v[100:103], v179 offset:8192
	ds_read_b128 v[56:59], v179 offset:4096
	ds_read_b128 v[64:67], v179 offset:6144
	v_mfma_f32_16x16x32_bf16 v[52:55], v[52:55], v[60:63], v[104:107]
	s_nop 2
	ds_read_b128 v[104:107], v179 offset:10240
	s_waitcnt lgkmcnt(0)
	v_mfma_f32_16x16x32_bf16 v[116:119], v[100:103], v[60:63], v[116:119]
	ds_read_b128 v[100:103], v179 offset:12288
	v_mfma_f32_16x16x32_bf16 v[120:123], v[104:107], v[60:63], v[120:123]
	ds_read_b128 v[104:107], v179 offset:14336
	v_mfma_f32_16x16x32_bf16 v[56:59], v[56:59], v[60:63], v[108:111]
	v_mfma_f32_16x16x32_bf16 v[64:67], v[64:67], v[60:63], v[112:115]
	s_waitcnt lgkmcnt(0)
	v_mfma_f32_16x16x32_bf16 v[124:127], v[100:103], v[60:63], v[124:127]
	v_mfma_f32_16x16x32_bf16 v[60:63], v[104:107], v[60:63], v[128:131]
	ds_read_b128 v[100:103], v179 offset:1024
	s_waitcnt lgkmcnt(0)
	v_mfma_f32_16x16x32_bf16 v[100:103], v[100:103], v[44:47], v[36:39]
	s_nop 2
	ds_read_b128 v[36:39], v179 offset:3072
	s_waitcnt lgkmcnt(0)
	v_mfma_f32_16x16x32_bf16 v[104:107], v[36:39], v[44:47], v[52:55]
	ds_read_b128 v[36:39], v179 offset:5120
	s_waitcnt lgkmcnt(0)
	v_mfma_f32_16x16x32_bf16 v[108:111], v[36:39], v[44:47], v[56:59]
	ds_read_b128 v[36:39], v179 offset:7168
	s_waitcnt lgkmcnt(0)
	v_mfma_f32_16x16x32_bf16 v[112:115], v[36:39], v[44:47], v[64:67]
	ds_read_b128 v[36:39], v179 offset:9216
	s_waitcnt lgkmcnt(0)
	v_mfma_f32_16x16x32_bf16 v[116:119], v[36:39], v[44:47], v[116:119]
	ds_read_b128 v[36:39], v179 offset:11264
	s_waitcnt lgkmcnt(0)
	v_mfma_f32_16x16x32_bf16 v[120:123], v[36:39], v[44:47], v[120:123]
	ds_read_b128 v[36:39], v179 offset:13312
	s_waitcnt lgkmcnt(0)
	v_mfma_f32_16x16x32_bf16 v[124:127], v[36:39], v[44:47], v[124:127]
	ds_read_b128 v[36:39], v179 offset:15360
	s_waitcnt lgkmcnt(0)
	v_mfma_f32_16x16x32_bf16 v[128:131], v[36:39], v[44:47], v[60:63]
	s_nop 2
	ds_read_b128 v[60:63], v179 offset:24576
	ds_read_b128 v[64:67], v179 offset:26624
	ds_read_b128 v[36:39], v179 offset:16384
	ds_read_b128 v[44:47], v179 offset:18432
	ds_read_b128 v[52:55], v179 offset:20480
	ds_read_b128 v[56:59], v179 offset:22528
	s_waitcnt lgkmcnt(0)
	v_mfma_f32_16x16x32_bf16 v[64:67], v[64:67], v[48:51], v[76:79]
	s_nop 2
	ds_read_b128 v[76:79], v179 offset:28672
	v_mfma_f32_16x16x32_bf16 v[44:47], v[44:47], v[48:51], v[92:95]
	s_waitcnt lgkmcnt(0)
	v_mfma_f32_16x16x32_bf16 v[92:95], v[76:79], v[48:51], v[72:75]
	s_nop 2
	ds_read_b128 v[72:75], v179 offset:30720
	v_mfma_f32_16x16x32_bf16 v[36:39], v[36:39], v[48:51], v[96:99]
	v_mfma_f32_16x16x32_bf16 v[52:55], v[52:55], v[48:51], v[88:91]
	v_mfma_f32_16x16x32_bf16 v[56:59], v[56:59], v[48:51], v[84:87]
	v_mfma_f32_16x16x32_bf16 v[60:63], v[60:63], v[48:51], v[80:83]
	s_waitcnt lgkmcnt(0)
	v_mfma_f32_16x16x32_bf16 v[48:51], v[72:75], v[48:51], v[68:71]
	s_nop 2
	ds_read_b128 v[68:71], v179 offset:17408
	s_waitcnt lgkmcnt(0)
	v_mfma_f32_16x16x32_bf16 v[68:71], v[68:71], v[40:43], v[36:39]
	s_nop 2
	ds_read_b128 v[36:39], v179 offset:19456
	s_waitcnt lgkmcnt(0)
	v_mfma_f32_16x16x32_bf16 v[72:75], v[36:39], v[40:43], v[44:47]
	ds_read_b128 v[36:39], v179 offset:21504
	s_waitcnt lgkmcnt(0)
	v_mfma_f32_16x16x32_bf16 v[76:79], v[36:39], v[40:43], v[52:55]
	ds_read_b128 v[36:39], v179 offset:23552
	s_waitcnt lgkmcnt(0)
	v_mfma_f32_16x16x32_bf16 v[80:83], v[36:39], v[40:43], v[56:59]
	ds_read_b128 v[36:39], v179 offset:25600
	s_waitcnt lgkmcnt(0)
	v_mfma_f32_16x16x32_bf16 v[84:87], v[36:39], v[40:43], v[60:63]
	ds_read_b128 v[36:39], v179 offset:27648
	s_waitcnt lgkmcnt(0)
	v_mfma_f32_16x16x32_bf16 v[88:91], v[36:39], v[40:43], v[64:67]
	ds_read_b128 v[36:39], v179 offset:29696
	s_waitcnt lgkmcnt(0)
	v_mfma_f32_16x16x32_bf16 v[92:95], v[36:39], v[40:43], v[92:95]
	ds_read_b128 v[36:39], v179 offset:31744
	s_waitcnt lgkmcnt(0)
	v_mfma_f32_16x16x32_bf16 v[96:99], v[36:39], v[40:43], v[48:51]
	s_add_u32 s0, s6, 0x9301f80
	s_addc_u32 s1, s7, 0
	s_mov_b32 m0, s11
	s_waitcnt vmcnt(12)
	s_barrier
	v_lshl_add_u64 v[36:37], s[0:1], 0, v[2:3]
	global_load_lds_dwordx4 v[36:37], off
	v_lshl_add_u64 v[36:37], s[0:1], 0, v[184:185]
	s_add_u32 s0, s6, 0x9401f80
	s_mov_b32 m0, s9
	s_addc_u32 s1, s7, 0
	global_load_lds_dwordx4 v[36:37], off
	v_lshl_add_u64 v[36:37], s[0:1], 0, v[2:3]
	s_mov_b32 m0, s8
	s_nop 0
	global_load_lds_dwordx4 v[36:37], off
	v_lshl_add_u64 v[36:37], s[0:1], 0, v[184:185]
	s_mov_b64 s[0:1], 0x3f000
	v_lshl_add_u64 v[40:41], v[182:183], 0, s[0:1]
	s_mov_b64 s[0:1], 0x3f080
	v_lshl_add_u64 v[42:43], v[182:183], 0, s[0:1]
	s_mov_b64 s[0:1], 0x3f400
	s_mov_b32 m0, s10
	v_lshl_add_u64 v[56:57], v[182:183], 0, s[0:1]
	s_mov_b64 s[0:1], 0x3f480
	global_load_lds_dwordx4 v[36:37], off
	v_lshl_add_u64 v[58:59], v[182:183], 0, s[0:1]
	global_load_dwordx4 v[44:47], v[164:165], off
	global_load_dwordx4 v[36:39], v[164:165], off offset:128
	global_load_dwordx4 v[48:51], v[40:41], off offset:16
	s_nop 0
	global_load_dwordx4 v[40:43], v[42:43], off offset:16
	s_nop 0
	global_load_dwordx4 v[60:63], v[164:165], off offset:1024
	global_load_dwordx4 v[52:55], v[164:165], off offset:1152
	global_load_dwordx4 v[64:67], v[56:57], off offset:16
	s_nop 0
	global_load_dwordx4 v[56:59], v[58:59], off offset:16
	v_cvt_pk_bf16_f32 v24, v24, v25
	v_cvt_pk_bf16_f32 v25, v26, v27
	v_cvt_pk_bf16_f32 v26, v12, v13
	v_cvt_pk_bf16_f32 v27, v14, v15
	v_cvt_pk_bf16_f32 v12, v28, v29
	v_cvt_pk_bf16_f32 v13, v30, v31
	v_cvt_pk_bf16_f32 v14, v32, v33
	v_cvt_pk_bf16_f32 v15, v34, v35
	v_cvt_pk_bf16_f32 v16, v16, v17
	v_cvt_pk_bf16_f32 v17, v18, v19
	v_cvt_pk_bf16_f32 v18, v20, v21
	v_cvt_pk_bf16_f32 v19, v22, v23
	v_cvt_pk_bf16_f32 v8, v8, v9
	v_cvt_pk_bf16_f32 v9, v10, v11
	v_cvt_pk_bf16_f32 v10, v4, v5
	v_cvt_pk_bf16_f32 v11, v6, v7
	ds_read_b128 v[4:7], v179 offset:32768
	ds_read_b128 v[20:23], v179 offset:34816
	ds_read_b128 v[28:31], v179 offset:36864
	ds_read_b128 v[32:35], v179 offset:38912
	s_waitcnt lgkmcnt(0)
	v_mfma_f32_16x16x32_bf16 v[4:7], v[4:7], v[24:27], v[100:103]
	s_nop 2
	ds_read_b128 v[100:103], v179 offset:40960
	v_mfma_f32_16x16x32_bf16 v[20:23], v[20:23], v[24:27], v[104:107]
	v_mfma_f32_16x16x32_bf16 v[28:31], v[28:31], v[24:27], v[108:111]
	s_nop 1
	ds_read_b128 v[104:107], v179 offset:43008
	v_mfma_f32_16x16x32_bf16 v[32:35], v[32:35], v[24:27], v[112:115]
	ds_read_b128 v[108:111], v179 offset:45056
	s_nop 1
	ds_read_b128 v[112:115], v179 offset:47104
	s_waitcnt lgkmcnt(0)
	v_mfma_f32_16x16x32_bf16 v[100:103], v[100:103], v[24:27], v[116:119]
	v_mfma_f32_16x16x32_bf16 v[104:107], v[104:107], v[24:27], v[120:123]
	v_mfma_f32_16x16x32_bf16 v[108:111], v[108:111], v[24:27], v[124:127]
	v_mfma_f32_16x16x32_bf16 v[24:27], v[112:115], v[24:27], v[128:131]
	ds_read_b128 v[112:115], v179 offset:33792
	s_waitcnt lgkmcnt(0)
	v_mfma_f32_16x16x32_bf16 v[4:7], v[112:115], v[12:15], v[4:7]
	ds_read_b128 v[112:115], v179 offset:35840
	s_waitcnt lgkmcnt(0)
	v_mfma_f32_16x16x32_bf16 v[20:23], v[112:115], v[12:15], v[20:23]
	ds_read_b128 v[112:115], v179 offset:37888
	s_waitcnt lgkmcnt(0)
	v_mfma_f32_16x16x32_bf16 v[28:31], v[112:115], v[12:15], v[28:31]
	ds_read_b128 v[112:115], v179 offset:39936
	s_waitcnt lgkmcnt(0)
	v_mfma_f32_16x16x32_bf16 v[32:35], v[112:115], v[12:15], v[32:35]
	ds_read_b128 v[112:115], v179 offset:41984
	s_waitcnt lgkmcnt(0)
	v_mfma_f32_16x16x32_bf16 v[100:103], v[112:115], v[12:15], v[100:103]
	ds_read_b128 v[112:115], v179 offset:44032
	s_waitcnt lgkmcnt(0)
	v_mfma_f32_16x16x32_bf16 v[104:107], v[112:115], v[12:15], v[104:107]
	ds_read_b128 v[112:115], v179 offset:46080
	s_waitcnt lgkmcnt(0)
	v_mfma_f32_16x16x32_bf16 v[108:111], v[112:115], v[12:15], v[108:111]
	ds_read_b128 v[112:115], v179 offset:48128
	s_waitcnt lgkmcnt(0)
	v_mfma_f32_16x16x32_bf16 v[12:15], v[112:115], v[12:15], v[24:27]
	s_nop 2
	ds_read_b128 v[24:27], v179 offset:49152
	s_waitcnt lgkmcnt(0)
	v_mfma_f32_16x16x32_bf16 v[24:27], v[24:27], v[16:19], v[68:71]
	s_nop 2
	ds_read_b128 v[68:71], v179 offset:51200
	s_waitcnt lgkmcnt(0)
	v_mfma_f32_16x16x32_bf16 v[68:71], v[68:71], v[16:19], v[72:75]
	s_nop 2
	ds_read_b128 v[72:75], v179 offset:53248
	s_waitcnt lgkmcnt(0)
	v_mfma_f32_16x16x32_bf16 v[72:75], v[72:75], v[16:19], v[76:79]
	s_nop 2
	ds_read_b128 v[76:79], v179 offset:55296
	s_waitcnt lgkmcnt(0)
	v_mfma_f32_16x16x32_bf16 v[76:79], v[76:79], v[16:19], v[80:83]
	s_nop 2
	ds_read_b128 v[80:83], v179 offset:57344
	s_waitcnt lgkmcnt(0)
	v_mfma_f32_16x16x32_bf16 v[80:83], v[80:83], v[16:19], v[84:87]
	s_nop 2
	ds_read_b128 v[84:87], v179 offset:59392
	s_waitcnt lgkmcnt(0)
	v_mfma_f32_16x16x32_bf16 v[84:87], v[84:87], v[16:19], v[88:91]
	s_nop 2
	ds_read_b128 v[88:91], v179 offset:61440
	s_waitcnt lgkmcnt(0)
	v_mfma_f32_16x16x32_bf16 v[88:91], v[88:91], v[16:19], v[92:95]
	s_nop 2
	ds_read_b128 v[92:95], v179 offset:63488
	s_waitcnt lgkmcnt(0)
	v_mfma_f32_16x16x32_bf16 v[16:19], v[92:95], v[16:19], v[96:99]
	ds_read_b128 v[92:95], v179 offset:50176
	s_waitcnt lgkmcnt(0)
	v_mfma_f32_16x16x32_bf16 v[24:27], v[92:95], v[8:11], v[24:27]
	ds_read_b128 v[92:95], v179 offset:52224
	s_waitcnt lgkmcnt(0)
	v_mfma_f32_16x16x32_bf16 v[68:71], v[92:95], v[8:11], v[68:71]
	ds_read_b128 v[92:95], v179 offset:54272
	s_waitcnt lgkmcnt(0)
	v_mfma_f32_16x16x32_bf16 v[72:75], v[92:95], v[8:11], v[72:75]
	ds_read_b128 v[92:95], v179 offset:56320
	s_waitcnt lgkmcnt(0)
	v_mfma_f32_16x16x32_bf16 v[76:79], v[92:95], v[8:11], v[76:79]
	ds_read_b128 v[92:95], v179 offset:58368
	s_waitcnt lgkmcnt(0)
	v_mfma_f32_16x16x32_bf16 v[80:83], v[92:95], v[8:11], v[80:83]
	ds_read_b128 v[92:95], v179 offset:60416
	s_waitcnt lgkmcnt(0)
	v_mfma_f32_16x16x32_bf16 v[84:87], v[92:95], v[8:11], v[84:87]
	ds_read_b128 v[92:95], v179 offset:62464
	s_waitcnt lgkmcnt(0)
	v_mfma_f32_16x16x32_bf16 v[88:91], v[92:95], v[8:11], v[88:91]
	ds_read_b128 v[92:95], v179 offset:64512
	s_waitcnt lgkmcnt(0)
	v_mfma_f32_16x16x32_bf16 v[8:11], v[92:95], v[8:11], v[16:19]
	s_waitcnt vmcnt(12)
	s_barrier
	v_cvt_pk_bf16_f32 v16, v160, v161
	v_cvt_pk_bf16_f32 v17, v162, v163
	v_cvt_pk_bf16_f32 v18, v136, v137
	v_cvt_pk_bf16_f32 v19, v138, v139
	v_cvt_pk_bf16_f32 v92, v132, v133
	v_cvt_pk_bf16_f32 v93, v134, v135
	v_cvt_pk_bf16_f32 v94, v144, v145
	v_cvt_pk_bf16_f32 v95, v146, v147
	v_cvt_pk_bf16_f32 v96, v156, v157
	v_cvt_pk_bf16_f32 v97, v158, v159
	v_cvt_pk_bf16_f32 v98, v140, v141
	v_cvt_pk_bf16_f32 v99, v142, v143
	v_cvt_pk_bf16_f32 v112, v148, v149
	v_cvt_pk_bf16_f32 v113, v150, v151
	v_cvt_pk_bf16_f32 v114, v152, v153
	v_cvt_pk_bf16_f32 v115, v154, v155
	ds_read_b128 v[116:119], v208
	ds_read_b128 v[120:123], v208 offset:2048
	s_waitcnt lgkmcnt(0)
	v_mfma_f32_16x16x32_bf16 v[4:7], v[116:119], v[16:19], v[4:7]
	ds_read_b128 v[116:119], v208 offset:4096
	v_mfma_f32_16x16x32_bf16 v[20:23], v[120:123], v[16:19], v[20:23]
	ds_read_b128 v[120:123], v208 offset:6144
	s_waitcnt lgkmcnt(0)
	v_mfma_f32_16x16x32_bf16 v[28:31], v[116:119], v[16:19], v[28:31]
	ds_read_b128 v[116:119], v208 offset:8192
	v_mfma_f32_16x16x32_bf16 v[32:35], v[120:123], v[16:19], v[32:35]
	ds_read_b128 v[120:123], v208 offset:10240
	s_waitcnt lgkmcnt(0)
	v_mfma_f32_16x16x32_bf16 v[100:103], v[116:119], v[16:19], v[100:103]
	ds_read_b128 v[116:119], v208 offset:12288
	v_mfma_f32_16x16x32_bf16 v[104:107], v[120:123], v[16:19], v[104:107]
	ds_read_b128 v[120:123], v208 offset:14336
	s_waitcnt lgkmcnt(0)
	v_mfma_f32_16x16x32_bf16 v[108:111], v[116:119], v[16:19], v[108:111]
	v_mfma_f32_16x16x32_bf16 v[12:15], v[120:123], v[16:19], v[12:15]
	ds_read_b128 v[16:19], v208 offset:1024
	s_waitcnt lgkmcnt(0)
	v_mfma_f32_16x16x32_bf16 v[4:7], v[16:19], v[92:95], v[4:7]
	ds_read_b128 v[16:19], v208 offset:3072
	s_waitcnt lgkmcnt(0)
	v_mfma_f32_16x16x32_bf16 v[16:19], v[16:19], v[92:95], v[20:23]
	s_nop 2
	ds_read_b128 v[20:23], v208 offset:5120
	s_waitcnt lgkmcnt(0)
	v_mfma_f32_16x16x32_bf16 v[20:23], v[20:23], v[92:95], v[28:31]
	s_nop 2
	ds_read_b128 v[28:31], v208 offset:7168
	s_waitcnt lgkmcnt(0)
	v_mfma_f32_16x16x32_bf16 v[28:31], v[28:31], v[92:95], v[32:35]
	s_nop 2
	ds_read_b128 v[32:35], v208 offset:9216
	s_waitcnt lgkmcnt(0)
	v_mfma_f32_16x16x32_bf16 v[32:35], v[32:35], v[92:95], v[100:103]
	s_nop 2
	ds_read_b128 v[100:103], v208 offset:11264
	s_waitcnt lgkmcnt(0)
	v_mfma_f32_16x16x32_bf16 v[100:103], v[100:103], v[92:95], v[104:107]
	s_nop 2
	ds_read_b128 v[104:107], v208 offset:13312
	s_waitcnt lgkmcnt(0)
	v_mfma_f32_16x16x32_bf16 v[104:107], v[104:107], v[92:95], v[108:111]
	s_nop 2
	ds_read_b128 v[108:111], v208 offset:15360
	s_waitcnt lgkmcnt(0)
	v_mfma_f32_16x16x32_bf16 v[12:15], v[108:111], v[92:95], v[12:15]
	ds_read_b128 v[92:95], v207
	s_waitcnt lgkmcnt(0)
	v_mfma_f32_16x16x32_bf16 v[24:27], v[92:95], v[96:99], v[24:27]
	ds_read_b128 v[92:95], v207 offset:2048
	s_waitcnt lgkmcnt(0)
	v_mfma_f32_16x16x32_bf16 v[68:71], v[92:95], v[96:99], v[68:71]
	ds_read_b128 v[92:95], v207 offset:4096
	s_waitcnt lgkmcnt(0)
	v_mfma_f32_16x16x32_bf16 v[72:75], v[92:95], v[96:99], v[72:75]
	ds_read_b128 v[92:95], v207 offset:6144
	s_waitcnt lgkmcnt(0)
	v_mfma_f32_16x16x32_bf16 v[76:79], v[92:95], v[96:99], v[76:79]
	ds_read_b128 v[92:95], v207 offset:8192
	s_waitcnt lgkmcnt(0)
	v_mfma_f32_16x16x32_bf16 v[80:83], v[92:95], v[96:99], v[80:83]
	ds_read_b128 v[92:95], v207 offset:10240
	s_waitcnt lgkmcnt(0)
	v_mfma_f32_16x16x32_bf16 v[84:87], v[92:95], v[96:99], v[84:87]
	ds_read_b128 v[92:95], v207 offset:12288
	s_waitcnt lgkmcnt(0)
	v_mfma_f32_16x16x32_bf16 v[88:91], v[92:95], v[96:99], v[88:91]
	ds_read_b128 v[92:95], v207 offset:14336
	s_waitcnt lgkmcnt(0)
	v_mfma_f32_16x16x32_bf16 v[8:11], v[92:95], v[96:99], v[8:11]
	ds_read_b128 v[92:95], v207 offset:1024
	s_waitcnt lgkmcnt(0)
	v_mfma_f32_16x16x32_bf16 v[24:27], v[92:95], v[112:115], v[24:27]
	ds_read_b128 v[92:95], v207 offset:3072
	s_waitcnt lgkmcnt(0)
	v_mfma_f32_16x16x32_bf16 v[68:71], v[92:95], v[112:115], v[68:71]
	ds_read_b128 v[92:95], v207 offset:5120
	s_waitcnt lgkmcnt(0)
	v_mfma_f32_16x16x32_bf16 v[72:75], v[92:95], v[112:115], v[72:75]
	ds_read_b128 v[92:95], v207 offset:7168
	s_waitcnt lgkmcnt(0)
	v_mfma_f32_16x16x32_bf16 v[76:79], v[92:95], v[112:115], v[76:79]
	ds_read_b128 v[92:95], v207 offset:9216
	s_waitcnt lgkmcnt(0)
	v_mfma_f32_16x16x32_bf16 v[80:83], v[92:95], v[112:115], v[80:83]
	ds_read_b128 v[92:95], v207 offset:11264
	s_waitcnt lgkmcnt(0)
	v_mfma_f32_16x16x32_bf16 v[84:87], v[92:95], v[112:115], v[84:87]
	ds_read_b128 v[92:95], v207 offset:13312
	s_waitcnt lgkmcnt(0)
	v_mfma_f32_16x16x32_bf16 v[88:91], v[92:95], v[112:115], v[88:91]
	ds_read_b128 v[92:95], v207 offset:15360
	s_waitcnt lgkmcnt(0)
	v_mfma_f32_16x16x32_bf16 v[8:11], v[92:95], v[112:115], v[8:11]
	s_waitcnt vmcnt(0)
	s_barrier
	v_cvt_pk_bf16_f32 v44, v44, v45
	v_cvt_pk_bf16_f32 v45, v46, v47
	v_cvt_pk_bf16_f32 v46, v48, v49
	v_cvt_pk_bf16_f32 v47, v50, v51
	v_cvt_pk_bf16_f32 v36, v36, v37
	v_cvt_pk_bf16_f32 v37, v38, v39
	v_cvt_pk_bf16_f32 v38, v40, v41
	v_cvt_pk_bf16_f32 v39, v42, v43
	v_cvt_pk_bf16_f32 v40, v60, v61
	v_cvt_pk_bf16_f32 v41, v62, v63
	v_cvt_pk_bf16_f32 v42, v64, v65
	v_cvt_pk_bf16_f32 v43, v66, v67
	v_cvt_pk_bf16_f32 v48, v52, v53
	v_cvt_pk_bf16_f32 v49, v54, v55
	v_cvt_pk_bf16_f32 v50, v56, v57
	v_cvt_pk_bf16_f32 v51, v58, v59
	ds_read_b128 v[52:55], v179
	ds_read_b128 v[56:59], v179 offset:2048
	s_waitcnt lgkmcnt(1)
	v_mfma_f32_16x16x32_bf16 v[4:7], v[52:55], v[44:47], v[4:7]
	ds_read_b128 v[52:55], v179 offset:4096
	ds_read_b128 v[60:63], v179 offset:14336
	s_waitcnt lgkmcnt(2)
	v_mfma_f32_16x16x32_bf16 v[16:19], v[56:59], v[44:47], v[16:19]
	ds_read_b128 v[56:59], v179 offset:6144
	s_waitcnt lgkmcnt(2)
	v_mfma_f32_16x16x32_bf16 v[20:23], v[52:55], v[44:47], v[20:23]
	ds_read_b128 v[52:55], v179 offset:8192
	s_waitcnt lgkmcnt(1)
	v_mfma_f32_16x16x32_bf16 v[28:31], v[56:59], v[44:47], v[28:31]
	ds_read_b128 v[56:59], v179 offset:10240
	s_waitcnt lgkmcnt(1)
	v_mfma_f32_16x16x32_bf16 v[32:35], v[52:55], v[44:47], v[32:35]
	ds_read_b128 v[52:55], v179 offset:12288
	s_waitcnt lgkmcnt(1)
	v_mfma_f32_16x16x32_bf16 v[56:59], v[56:59], v[44:47], v[100:103]
	s_waitcnt lgkmcnt(0)
	v_mfma_f32_16x16x32_bf16 v[52:55], v[52:55], v[44:47], v[104:107]
	v_mfma_f32_16x16x32_bf16 v[12:15], v[60:63], v[44:47], v[12:15]
	ds_read_b128 v[44:47], v179 offset:1024
	s_waitcnt lgkmcnt(0)
	v_mfma_f32_16x16x32_bf16 v[92:95], v[44:47], v[36:39], v[4:7]
	s_nop 2
	ds_read_b128 v[4:7], v179 offset:3072
	s_waitcnt lgkmcnt(0)
	v_mfma_f32_16x16x32_bf16 v[96:99], v[4:7], v[36:39], v[16:19]
	ds_read_b128 v[4:7], v179 offset:5120
	s_waitcnt lgkmcnt(0)
	v_mfma_f32_16x16x32_bf16 v[100:103], v[4:7], v[36:39], v[20:23]
	ds_read_b128 v[4:7], v179 offset:7168
	s_waitcnt lgkmcnt(0)
	v_mfma_f32_16x16x32_bf16 v[104:107], v[4:7], v[36:39], v[28:31]
	ds_read_b128 v[4:7], v179 offset:9216
	s_waitcnt lgkmcnt(0)
	v_mfma_f32_16x16x32_bf16 v[108:111], v[4:7], v[36:39], v[32:35]
	ds_read_b128 v[4:7], v179 offset:11264
	s_waitcnt lgkmcnt(0)
	v_mfma_f32_16x16x32_bf16 v[112:115], v[4:7], v[36:39], v[56:59]
	ds_read_b128 v[4:7], v179 offset:13312
	s_waitcnt lgkmcnt(0)
	v_mfma_f32_16x16x32_bf16 v[116:119], v[4:7], v[36:39], v[52:55]
	ds_read_b128 v[4:7], v179 offset:15360
	s_waitcnt lgkmcnt(0)
	v_mfma_f32_16x16x32_bf16 v[120:123], v[4:7], v[36:39], v[12:15]
	ds_read_b128 v[16:19], v179 offset:20480
	ds_read_b128 v[4:7], v179 offset:16384
	s_nop 0
	ds_read_b128 v[12:15], v179 offset:18432
	s_waitcnt lgkmcnt(2)
	v_mfma_f32_16x16x32_bf16 v[20:23], v[16:19], v[40:43], v[72:75]
	ds_read_b128 v[16:19], v179 offset:22528
	s_waitcnt lgkmcnt(2)
	v_mfma_f32_16x16x32_bf16 v[4:7], v[4:7], v[40:43], v[24:27]
	s_waitcnt lgkmcnt(1)
	v_mfma_f32_16x16x32_bf16 v[12:15], v[12:15], v[40:43], v[68:71]
	s_waitcnt lgkmcnt(0)
	v_mfma_f32_16x16x32_bf16 v[24:27], v[16:19], v[40:43], v[76:79]
	ds_read_b128 v[16:19], v179 offset:24576
	s_waitcnt lgkmcnt(0)
	v_mfma_f32_16x16x32_bf16 v[28:31], v[16:19], v[40:43], v[80:83]
	ds_read_b128 v[16:19], v179 offset:26624
	s_waitcnt lgkmcnt(0)
	v_mfma_f32_16x16x32_bf16 v[32:35], v[16:19], v[40:43], v[84:87]
	ds_read_b128 v[16:19], v179 offset:28672
	s_waitcnt lgkmcnt(0)
	v_mfma_f32_16x16x32_bf16 v[36:39], v[16:19], v[40:43], v[88:91]
	ds_read_b128 v[16:19], v179 offset:30720
	s_waitcnt lgkmcnt(0)
	v_mfma_f32_16x16x32_bf16 v[40:43], v[16:19], v[40:43], v[8:11]
	s_nop 2
	ds_read_b128 v[8:11], v179 offset:17408
	s_waitcnt lgkmcnt(0)
	v_mfma_f32_16x16x32_bf16 v[8:11], v[8:11], v[48:51], v[4:7]
	s_nop 2
	ds_read_b128 v[4:7], v179 offset:19456
	s_waitcnt lgkmcnt(0)
	v_mfma_f32_16x16x32_bf16 v[16:19], v[4:7], v[48:51], v[12:15]
	ds_read_b128 v[4:7], v179 offset:21504
	s_nop 1
	ds_read_b128 v[12:15], v179 offset:31744
	s_waitcnt lgkmcnt(1)
	v_mfma_f32_16x16x32_bf16 v[20:23], v[4:7], v[48:51], v[20:23]
	ds_read_b128 v[4:7], v179 offset:23552
	s_waitcnt lgkmcnt(1)
	v_mfma_f32_16x16x32_bf16 v[12:15], v[12:15], v[48:51], v[40:43]
	s_waitcnt lgkmcnt(0)
	v_mfma_f32_16x16x32_bf16 v[24:27], v[4:7], v[48:51], v[24:27]
	ds_read_b128 v[4:7], v179 offset:25600
	s_waitcnt lgkmcnt(0)
	v_mfma_f32_16x16x32_bf16 v[28:31], v[4:7], v[48:51], v[28:31]
	ds_read_b128 v[4:7], v179 offset:27648
	s_waitcnt lgkmcnt(0)
	v_mfma_f32_16x16x32_bf16 v[32:35], v[4:7], v[48:51], v[32:35]
	ds_read_b128 v[4:7], v179 offset:29696
	s_waitcnt lgkmcnt(0)
	v_mfma_f32_16x16x32_bf16 v[4:7], v[4:7], v[48:51], v[36:39]
	v_lshlrev_b32_e32 v152, 4, v205
	v_mov_b32_e32 v153, v3
	s_nop 0
	v_lshl_add_u64 v[36:37], s[6:7], 0, v[152:153]
	s_mov_b32 s0, 0xa00000
	v_add_co_u32_e32 v36, vcc, s0, v36
	v_lshlrev_b32_e32 v162, 2, v205
	s_nop 0
	v_addc_co_u32_e32 v37, vcc, 0, v37, vcc
	global_load_dwordx4 v[68:71], v[36:37], off
	global_load_dwordx4 v[72:75], v[36:37], off offset:64
	global_load_dwordx4 v[76:79], v[36:37], off offset:128
	global_load_dwordx4 v[80:83], v[36:37], off offset:192
	global_load_dwordx4 v[84:87], v[36:37], off offset:256
	global_load_dwordx4 v[124:127], v[36:37], off offset:320
	global_load_dwordx4 v[128:131], v[36:37], off offset:384
	global_load_dwordx4 v[132:135], v[36:37], off offset:448
	global_load_dwordx4 v[64:67], v[36:37], off offset:512
	global_load_dwordx4 v[60:63], v[36:37], off offset:576
	global_load_dwordx4 v[56:59], v[36:37], off offset:640
	global_load_dwordx4 v[52:55], v[36:37], off offset:704
	global_load_dwordx4 v[48:51], v[36:37], off offset:768
	global_load_dwordx4 v[44:47], v[36:37], off offset:832
	global_load_dwordx4 v[40:43], v[36:37], off offset:896
	s_nop 0
	global_load_dwordx4 v[36:39], v[36:37], off offset:960
	s_waitcnt vmcnt(15)
	v_pk_add_f32 v[94:95], v[94:95], v[70:71]
	v_pk_add_f32 v[92:93], v[92:93], v[68:69]
	s_waitcnt vmcnt(14)
	v_pk_add_f32 v[98:99], v[98:99], v[74:75]
	v_pk_add_f32 v[96:97], v[96:97], v[72:73]
	s_waitcnt vmcnt(13)
	v_pk_add_f32 v[102:103], v[102:103], v[78:79]
	v_pk_add_f32 v[100:101], v[100:101], v[76:77]
	s_waitcnt vmcnt(12)
	v_pk_add_f32 v[82:83], v[106:107], v[82:83]
	v_pk_add_f32 v[80:81], v[104:105], v[80:81]
	s_waitcnt vmcnt(11)
	v_pk_add_f32 v[88:89], v[110:111], v[86:87]
	v_pk_add_f32 v[90:91], v[108:109], v[84:85]
	s_waitcnt vmcnt(10)
	v_pk_add_f32 v[84:85], v[114:115], v[126:127]
	v_pk_add_f32 v[86:87], v[112:113], v[124:125]
	s_waitcnt vmcnt(9)
	v_pk_add_f32 v[72:73], v[118:119], v[130:131]
	v_pk_add_f32 v[74:75], v[116:117], v[128:129]
	s_waitcnt vmcnt(8)
	v_pk_add_f32 v[68:69], v[122:123], v[134:135]
	v_pk_add_f32 v[70:71], v[120:121], v[132:133]
	v_mul_f32_e32 v2, 0x3d372713, v92
	v_mul_f32_e32 v76, 0x3d372713, v93
	v_mul_f32_e32 v2, v92, v2
	v_mul_f32_e32 v76, v93, v76
	v_mul_f32_e32 v77, 0x3d372713, v94
	v_fma_f32 v2, v92, v2, v92
	v_fma_f32 v76, v93, v76, v93
	v_mul_f32_e32 v77, v94, v77
	v_mul_f32_e32 v2, 0x3f4c422a, v2
	v_mul_f32_e32 v76, 0x3f4c422a, v76
	v_fma_f32 v77, v94, v77, v94
	v_mul_f32_e32 v2, 0xc038aa3b, v2
	v_mul_f32_e32 v76, 0xc038aa3b, v76
	v_mul_f32_e32 v77, 0x3f4c422a, v77
	v_exp_f32_e32 v2, v2
	v_exp_f32_e32 v76, v76
	v_mul_f32_e32 v77, 0xc038aa3b, v77
	v_exp_f32_e32 v77, v77
	v_add_f32_e32 v2, 1.0, v2
	v_add_f32_e32 v76, 1.0, v76
	v_rcp_f32_e32 v2, v2
	v_rcp_f32_e32 v76, v76
	v_add_f32_e32 v77, 1.0, v77
	v_rcp_f32_e32 v77, v77
	v_mul_f32_e32 v78, 0x3d372713, v95
	v_mul_f32_e32 v2, v92, v2
	v_mul_f32_e32 v76, v93, v76
	v_mul_f32_e32 v79, 0x3d372713, v96
	v_mul_f32_e32 v92, 0x3d372713, v97
	v_mul_f32_e32 v93, 0x3d372713, v98
	v_mul_f32_e32 v78, v95, v78
	v_mul_f32_e32 v77, v94, v77
	v_mul_f32_e32 v79, v96, v79
	v_mul_f32_e32 v92, v97, v92
	v_mul_f32_e32 v93, v98, v93
	v_mul_f32_e32 v94, 0x3d372713, v99
	v_fma_f32 v78, v95, v78, v95
	v_fma_f32 v79, v96, v79, v96
	v_fma_f32 v92, v97, v92, v97
	v_fma_f32 v93, v98, v93, v98
	v_mul_f32_e32 v94, v99, v94
	v_mul_f32_e32 v78, 0x3f4c422a, v78
	v_mul_f32_e32 v79, 0x3f4c422a, v79
	v_mul_f32_e32 v92, 0x3f4c422a, v92
	v_mul_f32_e32 v93, 0x3f4c422a, v93
	v_fma_f32 v94, v99, v94, v99
	v_mul_f32_e32 v78, 0xc038aa3b, v78
	v_mul_f32_e32 v79, 0xc038aa3b, v79
	v_mul_f32_e32 v92, 0xc038aa3b, v92
	v_mul_f32_e32 v93, 0xc038aa3b, v93
	v_mul_f32_e32 v94, 0x3f4c422a, v94
	v_exp_f32_e32 v78, v78
	v_exp_f32_e32 v79, v79
	v_exp_f32_e32 v92, v92
	v_exp_f32_e32 v93, v93
	v_mul_f32_e32 v94, 0xc038aa3b, v94
	v_exp_f32_e32 v94, v94
	v_add_f32_e32 v78, 1.0, v78
	v_add_f32_e32 v79, 1.0, v79
	v_add_f32_e32 v92, 1.0, v92
	v_add_f32_e32 v93, 1.0, v93
	v_rcp_f32_e32 v78, v78
	v_rcp_f32_e32 v79, v79
	v_rcp_f32_e32 v92, v92
	v_rcp_f32_e32 v93, v93
	v_add_f32_e32 v94, 1.0, v94
	v_rcp_f32_e32 v94, v94
	v_mul_f32_e32 v78, v95, v78
	v_mul_f32_e32 v79, v96, v79
	v_mul_f32_e32 v92, v97, v92
	v_mul_f32_e32 v93, v98, v93
	v_mul_f32_e32 v94, v99, v94
	v_cvt_pk_bf16_f32 v76, v2, v76
	v_mul_f32_e32 v2, 0x3d372713, v100
	v_cvt_pk_bf16_f32 v77, v77, v78
	v_cvt_pk_bf16_f32 v78, v79, v92
	v_cvt_pk_bf16_f32 v79, v93, v94
	v_mul_f32_e32 v92, 0x3d372713, v101
	v_mul_f32_e32 v93, 0x3d372713, v102
	v_mul_f32_e32 v2, v100, v2
	v_mul_f32_e32 v92, v101, v92
	v_mul_f32_e32 v93, v102, v93
	v_mul_f32_e32 v94, 0x3d372713, v103
	v_mul_f32_e32 v95, 0x3d372713, v80
	v_mul_f32_e32 v96, 0x3d372713, v81
	v_fma_f32 v2, v100, v2, v100
	v_fma_f32 v92, v101, v92, v101
	v_fma_f32 v93, v102, v93, v102
	v_mul_f32_e32 v94, v103, v94
	v_mul_f32_e32 v95, v80, v95
	v_mul_f32_e32 v96, v81, v96
	v_mul_f32_e32 v2, 0x3f4c422a, v2
	v_mul_f32_e32 v92, 0x3f4c422a, v92
	v_mul_f32_e32 v93, 0x3f4c422a, v93
	v_fma_f32 v94, v103, v94, v103
	v_fma_f32 v95, v80, v95, v80
	v_fma_f32 v96, v81, v96, v81
	v_mul_f32_e32 v2, 0xc038aa3b, v2
	v_mul_f32_e32 v92, 0xc038aa3b, v92
	v_mul_f32_e32 v93, 0xc038aa3b, v93
	v_mul_f32_e32 v94, 0x3f4c422a, v94
	v_mul_f32_e32 v95, 0x3f4c422a, v95
	v_mul_f32_e32 v96, 0x3f4c422a, v96
	v_exp_f32_e32 v2, v2
	v_exp_f32_e32 v92, v92
	v_exp_f32_e32 v93, v93
	v_mul_f32_e32 v94, 0xc038aa3b, v94
	v_mul_f32_e32 v95, 0xc038aa3b, v95
	v_mul_f32_e32 v96, 0xc038aa3b, v96
	v_exp_f32_e32 v94, v94
	v_exp_f32_e32 v95, v95
	v_exp_f32_e32 v96, v96
	v_add_f32_e32 v2, 1.0, v2
	v_add_f32_e32 v92, 1.0, v92
	v_add_f32_e32 v93, 1.0, v93
	v_rcp_f32_e32 v2, v2
	v_rcp_f32_e32 v92, v92
	v_rcp_f32_e32 v93, v93
	v_add_f32_e32 v94, 1.0, v94
	v_add_f32_e32 v95, 1.0, v95
	v_add_f32_e32 v96, 1.0, v96
	v_rcp_f32_e32 v94, v94
	v_rcp_f32_e32 v95, v95
	v_rcp_f32_e32 v96, v96
	v_mul_f32_e32 v2, v100, v2
	v_mul_f32_e32 v92, v101, v92
	v_mul_f32_e32 v93, v102, v93
	v_mul_f32_e32 v94, v103, v94
	v_mul_f32_e32 v95, v80, v95
	v_mul_f32_e32 v96, v81, v96
	v_cvt_pk_bf16_f32 v80, v2, v92
	v_mul_f32_e32 v2, 0x3d372713, v90
	v_cvt_pk_bf16_f32 v81, v93, v94
	v_mul_f32_e32 v92, 0x3d372713, v91
	v_mul_f32_e32 v93, 0x3d372713, v88
	v_mul_f32_e32 v2, v90, v2
	v_mul_f32_e32 v92, v91, v92
	v_mul_f32_e32 v93, v88, v93
	v_fma_f32 v2, v90, v2, v90
	v_fma_f32 v92, v91, v92, v91
	v_fma_f32 v93, v88, v93, v88
	v_mul_f32_e32 v2, 0x3f4c422a, v2
	v_mul_f32_e32 v92, 0x3f4c422a, v92
	v_mul_f32_e32 v93, 0x3f4c422a, v93
	v_mul_f32_e32 v2, 0xc038aa3b, v2
	v_mul_f32_e32 v92, 0xc038aa3b, v92
	v_mul_f32_e32 v93, 0xc038aa3b, v93
	v_exp_f32_e32 v2, v2
	v_exp_f32_e32 v92, v92
	v_exp_f32_e32 v93, v93
	v_mul_f32_e32 v94, 0x3d372713, v89
	v_add_f32_e32 v2, 1.0, v2
	v_add_f32_e32 v92, 1.0, v92
	v_add_f32_e32 v93, 1.0, v93
	v_rcp_f32_e32 v2, v2
	v_rcp_f32_e32 v92, v92
	v_rcp_f32_e32 v93, v93
	v_mul_f32_e32 v94, v89, v94
	v_fma_f32 v94, v89, v94, v89
	v_mul_f32_e32 v94, 0x3f4c422a, v94
	v_mul_f32_e32 v94, 0xc038aa3b, v94
	v_exp_f32_e32 v94, v94
	v_mul_f32_e32 v2, v90, v2
	v_mul_f32_e32 v90, v91, v92
	v_mul_f32_e32 v88, v88, v93
	v_mul_f32_e32 v92, 0x3d372713, v86
	v_mul_f32_e32 v93, 0x3d372713, v87
	v_mul_f32_e32 v92, v86, v92
	v_mul_f32_e32 v93, v87, v93
	v_fma_f32 v92, v86, v92, v86
	v_fma_f32 v93, v87, v93, v87
	v_mul_f32_e32 v92, 0x3f4c422a, v92
	v_mul_f32_e32 v93, 0x3f4c422a, v93
	v_add_f32_e32 v91, 1.0, v94
	v_mul_f32_e32 v92, 0xc038aa3b, v92
	v_mul_f32_e32 v93, 0xc038aa3b, v93
	v_rcp_f32_e32 v91, v91
	v_exp_f32_e32 v92, v92
	v_exp_f32_e32 v93, v93
	v_mul_f32_e32 v98, 0x3d372713, v83
	v_mul_f32_e32 v97, 0x3d372713, v82
	v_mul_f32_e32 v98, v83, v98
	v_mul_f32_e32 v89, v89, v91
	v_add_f32_e32 v91, 1.0, v92
	v_add_f32_e32 v92, 1.0, v93
	v_mul_f32_e32 v93, 0x3d372713, v84
	v_mul_f32_e32 v94, 0x3d372713, v85
	v_mul_f32_e32 v97, v82, v97
	v_fma_f32 v98, v83, v98, v83
	v_mul_f32_e32 v93, v84, v93
	v_mul_f32_e32 v94, v85, v94
	v_fma_f32 v97, v82, v97, v82
	v_mul_f32_e32 v98, 0x3f4c422a, v98
	v_fma_f32 v93, v84, v93, v84
	v_fma_f32 v94, v85, v94, v85
	v_mul_f32_e32 v97, 0x3f4c422a, v97
	v_mul_f32_e32 v98, 0xc038aa3b, v98
	v_mul_f32_e32 v93, 0x3f4c422a, v93
	v_mul_f32_e32 v94, 0x3f4c422a, v94
	v_mul_f32_e32 v97, 0xc038aa3b, v97
	v_exp_f32_e32 v98, v98
	v_mul_f32_e32 v93, 0xc038aa3b, v93
	v_mul_f32_e32 v94, 0xc038aa3b, v94
	v_exp_f32_e32 v97, v97
	v_exp_f32_e32 v93, v93
	v_exp_f32_e32 v94, v94
	v_add_f32_e32 v98, 1.0, v98
	v_add_f32_e32 v97, 1.0, v97
	v_rcp_f32_e32 v98, v98
	v_add_f32_e32 v93, 1.0, v93
	v_add_f32_e32 v94, 1.0, v94
	v_rcp_f32_e32 v97, v97
	v_rcp_f32_e32 v91, v91
	v_rcp_f32_e32 v92, v92
	v_rcp_f32_e32 v93, v93
	v_rcp_f32_e32 v94, v94
	v_mul_f32_e32 v83, v83, v98
	v_mul_f32_e32 v97, v82, v97
	v_cvt_pk_bf16_f32 v82, v95, v96
	v_cvt_pk_bf16_f32 v83, v97, v83
	v_mul_f32_e32 v86, v86, v91
	v_mul_f32_e32 v87, v87, v92
	v_mul_f32_e32 v91, v84, v93
	v_mul_f32_e32 v92, v85, v94
	v_cvt_pk_bf16_f32 v84, v2, v90
	v_mul_f32_e32 v2, 0x3d372713, v74
	v_cvt_pk_bf16_f32 v85, v88, v89
	v_mul_f32_e32 v88, 0x3d372713, v75
	v_mul_f32_e32 v89, 0x3d372713, v72
	v_mul_f32_e32 v2, v74, v2
	v_mul_f32_e32 v88, v75, v88
	v_mul_f32_e32 v89, v72, v89
	v_fma_f32 v2, v74, v2, v74
	v_fma_f32 v88, v75, v88, v75
	v_fma_f32 v89, v72, v89, v72
	v_mul_f32_e32 v2, 0x3f4c422a, v2
	v_mul_f32_e32 v88, 0x3f4c422a, v88
	v_mul_f32_e32 v89, 0x3f4c422a, v89
	v_mul_f32_e32 v2, 0xc038aa3b, v2
	v_mul_f32_e32 v88, 0xc038aa3b, v88
	v_mul_f32_e32 v89, 0xc038aa3b, v89
	v_exp_f32_e32 v2, v2
	v_exp_f32_e32 v88, v88
	v_exp_f32_e32 v89, v89
	v_mul_f32_e32 v90, 0x3d372713, v73
	v_add_f32_e32 v2, 1.0, v2
	v_add_f32_e32 v88, 1.0, v88
	v_add_f32_e32 v89, 1.0, v89
	v_rcp_f32_e32 v2, v2
	v_rcp_f32_e32 v88, v88
	v_rcp_f32_e32 v89, v89
	v_mul_f32_e32 v90, v73, v90
	v_fma_f32 v90, v73, v90, v73
	v_mul_f32_e32 v90, 0x3f4c422a, v90
	v_mul_f32_e32 v90, 0xc038aa3b, v90
	v_exp_f32_e32 v90, v90
	v_mul_f32_e32 v2, v74, v2
	v_mul_f32_e32 v74, v75, v88
	v_mul_f32_e32 v72, v72, v89
	v_mul_f32_e32 v88, 0x3d372713, v70
	v_mul_f32_e32 v89, 0x3d372713, v71
	v_mul_f32_e32 v88, v70, v88
	v_mul_f32_e32 v89, v71, v89
	v_fma_f32 v88, v70, v88, v70
	v_fma_f32 v89, v71, v89, v71
	v_mul_f32_e32 v88, 0x3f4c422a, v88
	v_mul_f32_e32 v89, 0x3f4c422a, v89
	v_add_f32_e32 v75, 1.0, v90
	v_mul_f32_e32 v88, 0xc038aa3b, v88
	v_mul_f32_e32 v89, 0xc038aa3b, v89
	v_rcp_f32_e32 v75, v75
	v_exp_f32_e32 v88, v88
	v_exp_f32_e32 v89, v89
	v_mul_f32_e32 v90, 0x3d372713, v69
	v_mul_f32_e32 v73, v73, v75
	v_add_f32_e32 v75, 1.0, v88
	v_add_f32_e32 v88, 1.0, v89
	v_mul_f32_e32 v89, 0x3d372713, v68
	v_mul_f32_e32 v89, v68, v89
	v_mul_f32_e32 v90, v69, v90
	v_fma_f32 v89, v68, v89, v68
	v_fma_f32 v90, v69, v90, v69
	v_mul_f32_e32 v89, 0x3f4c422a, v89
	v_mul_f32_e32 v90, 0x3f4c422a, v90
	v_mul_f32_e32 v89, 0xc038aa3b, v89
	v_mul_f32_e32 v90, 0xc038aa3b, v90
	v_exp_f32_e32 v89, v89
	v_exp_f32_e32 v90, v90
	v_rcp_f32_e32 v75, v75
	v_rcp_f32_e32 v88, v88
	v_add_f32_e32 v89, 1.0, v89
	v_add_f32_e32 v90, 1.0, v90
	v_rcp_f32_e32 v89, v89
	v_rcp_f32_e32 v90, v90
	v_readlane_b32 s8, v254, 0
	v_readlane_b32 s9, v254, 1
	s_mov_b64 s[0:1], s[8:9]
	v_cvt_pk_bf16_f32 v86, v86, v87
	v_cvt_pk_bf16_f32 v87, v91, v92
	v_mul_f32_e32 v70, v70, v75
	v_mul_f32_e32 v71, v71, v88
	v_mul_f32_e32 v68, v68, v89
	v_mul_f32_e32 v69, v69, v90
	v_cvt_pk_bf16_f32 v88, v2, v74
	v_cvt_pk_bf16_f32 v89, v72, v73
	v_cvt_pk_bf16_f32 v90, v70, v71
	v_cvt_pk_bf16_f32 v91, v68, v69
	s_load_dwordx2 s[0:1], s[0:1], 0xa8
	v_mov_b32_e32 v179, v3
	v_lshlrev_b32_e32 v2, 10, v205
	v_or_b32_e32 v96, 0x1000, v2
	v_mov_b32_e32 v97, v3
	s_waitcnt lgkmcnt(0)
	v_lshl_add_u64 v[158:159], s[0:1], 0, v[178:179]
	v_or_b32_e32 v98, 0x1100, v2
	v_mov_b32_e32 v99, v3
	v_or_b32_e32 v100, 0x1200, v2
	v_mov_b32_e32 v101, v3
	v_or_b32_e32 v102, 0x1300, v2
	v_mov_b32_e32 v103, v3
	v_or_b32_e32 v104, 0x2000, v2
	v_mov_b32_e32 v105, v3
	v_or_b32_e32 v106, 0x2100, v2
	v_mov_b32_e32 v107, v3
	v_or_b32_e32 v110, 0x2300, v2
	v_mov_b32_e32 v111, v3
	v_or_b32_e32 v112, 0x3000, v2
	v_mov_b32_e32 v113, v3
	v_or_b32_e32 v114, 0x3100, v2
	v_mov_b32_e32 v115, v3
	v_or_b32_e32 v116, 0x3200, v2
	v_mov_b32_e32 v117, v3
	v_or_b32_e32 v118, 0x3300, v2
	v_mov_b32_e32 v119, v3
	v_or_b32_e32 v120, 0x4000, v2
	v_mov_b32_e32 v121, v3
	v_or_b32_e32 v122, 0x4100, v2
	v_mov_b32_e32 v123, v3
	v_or_b32_e32 v124, 0x4200, v2
	v_mov_b32_e32 v125, v3
	v_or_b32_e32 v126, 0x4300, v2
	v_mov_b32_e32 v127, v3
	v_lshl_add_u64 v[156:157], v[158:159], 0, v[2:3]
	v_lshl_add_u64 v[68:69], v[158:159], 0, v[96:97]
	v_lshl_add_u64 v[70:71], v[158:159], 0, v[98:99]
	v_lshl_add_u64 v[72:73], v[158:159], 0, v[100:101]
	v_lshl_add_u64 v[74:75], v[158:159], 0, v[102:103]
	v_lshl_add_u64 v[92:93], v[158:159], 0, v[104:105]
	v_lshl_add_u64 v[94:95], v[158:159], 0, v[106:107]
	v_or_b32_e32 v108, 0x2200, v2
	v_mov_b32_e32 v109, v3
	v_lshl_add_u64 v[160:161], v[158:159], 0, v[110:111]
	v_lshl_add_u64 v[164:165], v[158:159], 0, v[112:113]
	v_lshl_add_u64 v[166:167], v[158:159], 0, v[114:115]
	v_lshl_add_u64 v[168:169], v[158:159], 0, v[116:117]
	v_lshl_add_u64 v[170:171], v[158:159], 0, v[118:119]
	v_lshl_add_u64 v[172:173], v[158:159], 0, v[120:121]
	v_lshl_add_u64 v[174:175], v[158:159], 0, v[122:123]
	v_lshl_add_u64 v[182:183], v[158:159], 0, v[124:125]
	v_lshl_add_u64 v[184:185], v[158:159], 0, v[126:127]
	v_or_b32_e32 v128, 0x5000, v2
	v_mov_b32_e32 v129, v3
	v_or_b32_e32 v130, 0x5100, v2
	v_mov_b32_e32 v131, v3
	v_or_b32_e32 v132, 0x5200, v2
	v_mov_b32_e32 v133, v3
	v_or_b32_e32 v134, 0x5300, v2
	v_mov_b32_e32 v135, v3
	v_or_b32_e32 v136, 0x6000, v2
	v_mov_b32_e32 v137, v3
	v_or_b32_e32 v138, 0x6100, v2
	v_mov_b32_e32 v139, v3
	v_or_b32_e32 v140, 0x6200, v2
	v_mov_b32_e32 v141, v3
	v_or_b32_e32 v142, 0x6300, v2
	v_mov_b32_e32 v143, v3
	v_or_b32_e32 v144, 0x7000, v2
	v_mov_b32_e32 v145, v3
	v_or_b32_e32 v146, 0x7100, v2
	v_mov_b32_e32 v147, v3
	v_or_b32_e32 v148, 0x7200, v2
	v_mov_b32_e32 v149, v3
	v_or_b32_e32 v150, 0x7300, v2
	v_mov_b32_e32 v151, v3
	v_lshl_add_u64 v[154:155], v[158:159], 0, v[108:109]
	v_lshl_add_u64 v[186:187], v[158:159], 0, v[128:129]
	v_lshl_add_u64 v[188:189], v[158:159], 0, v[130:131]
	v_lshl_add_u64 v[190:191], v[158:159], 0, v[132:133]
	v_lshl_add_u64 v[192:193], v[158:159], 0, v[134:135]
	v_lshl_add_u64 v[194:195], v[158:159], 0, v[136:137]
	v_lshl_add_u64 v[196:197], v[158:159], 0, v[138:139]
	v_lshl_add_u64 v[198:199], v[158:159], 0, v[140:141]
	v_lshl_add_u64 v[202:203], v[158:159], 0, v[142:143]
	v_lshl_add_u64 v[208:209], v[158:159], 0, v[144:145]
	v_lshl_add_u64 v[210:211], v[158:159], 0, v[146:147]
	v_lshl_add_u64 v[212:213], v[158:159], 0, v[148:149]
	v_lshl_add_u64 v[214:215], v[158:159], 0, v[150:151]
	global_load_dword v153, v[156:157], off offset:256
	global_load_dword v163, v[156:157], off offset:768
	s_nop 0
	global_load_dword v70, v[70:71], off
	s_nop 0
	global_load_dword v71, v[74:75], off
	s_nop 0
	global_load_dword v72, v[72:73], off
	s_nop 0
	global_load_dword v73, v[68:69], off
	s_nop 0
	global_load_dword v69, v[156:157], off offset:512
	global_load_dword v68, v[156:157], off
	global_load_dword v74, v[94:95], off
	global_load_dword v75, v[160:161], off
	s_nop 0
	global_load_dword v94, v[166:167], off
	global_load_dword v95, v[170:171], off
	global_load_dword v160, v[168:169], off
	global_load_dword v161, v[164:165], off
	s_nop 0
	global_load_dword v164, v[154:155], off
	s_nop 0
	global_load_dword v92, v[92:93], off
	s_nop 0
	global_load_dword v93, v[174:175], off
	global_load_dword v165, v[184:185], off
	global_load_dword v166, v[188:189], off
	global_load_dword v167, v[192:193], off
	global_load_dword v168, v[190:191], off
	global_load_dword v169, v[186:187], off
	global_load_dword v170, v[182:183], off
	global_load_dword v171, v[172:173], off
	s_nop 0
	global_load_dword v172, v[196:197], off
	global_load_dword v173, v[202:203], off
	global_load_dword v174, v[210:211], off
	global_load_dword v175, v[214:215], off
	global_load_dword v182, v[212:213], off
	global_load_dword v183, v[208:209], off
	global_load_dword v184, v[198:199], off
	global_load_dword v185, v[194:195], off
	v_ashrrev_i32_e32 v181, 31, v180
	v_lshlrev_b64 v[154:155], 10, v[180:181]
	s_waitcnt vmcnt(24)
	v_cvt_pk_bf16_f32 v68, v68, v153
	v_cvt_pk_bf16_f32 v69, v69, v163
	v_cvt_pk_bf16_f32 v70, v73, v70
	v_cvt_pk_bf16_f32 v71, v72, v71
	s_waitcnt vmcnt(16)
	v_cvt_pk_bf16_f32 v72, v92, v74
	v_cvt_pk_bf16_f32 v73, v164, v75
	v_cvt_pk_bf16_f32 v74, v161, v94
	v_cvt_pk_bf16_f32 v75, v160, v95
	v_mfma_f32_16x16x32_bf16 v[68:71], v[68:71], v[76:79], 0
	v_mfma_f32_16x16x32_bf16 v[68:71], v[72:75], v[80:83], v[68:71]
	s_waitcnt vmcnt(8)
	v_cvt_pk_bf16_f32 v72, v171, v93
	v_cvt_pk_bf16_f32 v73, v170, v165
	v_cvt_pk_bf16_f32 v74, v169, v166
	v_cvt_pk_bf16_f32 v75, v168, v167
	s_nop 0
	v_mfma_f32_16x16x32_bf16 v[68:71], v[72:75], v[84:87], v[68:71]
	s_waitcnt vmcnt(0)
	v_cvt_pk_bf16_f32 v72, v185, v172
	v_cvt_pk_bf16_f32 v73, v184, v173
	v_cvt_pk_bf16_f32 v74, v183, v174
	v_cvt_pk_bf16_f32 v75, v182, v175
	s_nop 0
	v_mfma_f32_16x16x32_bf16 v[92:95], v[72:75], v[88:91], v[68:71]
	s_nop 4
	v_lshl_add_u64 v[68:69], v[158:159], 0, 64
	v_lshl_add_u64 v[70:71], v[68:69], 0, v[96:97]
	v_lshl_add_u64 v[72:73], v[68:69], 0, v[98:99]
	v_lshl_add_u64 v[74:75], v[68:69], 0, v[100:101]
	v_lshl_add_u64 v[160:161], v[68:69], 0, v[102:103]
	v_lshl_add_u64 v[164:165], v[68:69], 0, v[104:105]
	v_lshl_add_u64 v[166:167], v[68:69], 0, v[106:107]
	v_lshl_add_u64 v[168:169], v[68:69], 0, v[108:109]
	v_lshl_add_u64 v[170:171], v[68:69], 0, v[110:111]
	v_lshl_add_u64 v[172:173], v[68:69], 0, v[112:113]
	v_lshl_add_u64 v[174:175], v[68:69], 0, v[114:115]
	v_lshl_add_u64 v[180:181], v[68:69], 0, v[116:117]
	v_lshl_add_u64 v[182:183], v[68:69], 0, v[118:119]
	v_lshl_add_u64 v[184:185], v[68:69], 0, v[120:121]
	v_lshl_add_u64 v[186:187], v[68:69], 0, v[122:123]
	v_lshl_add_u64 v[188:189], v[68:69], 0, v[124:125]
	v_lshl_add_u64 v[190:191], v[68:69], 0, v[126:127]
	v_lshl_add_u64 v[192:193], v[68:69], 0, v[128:129]
	v_lshl_add_u64 v[194:195], v[68:69], 0, v[130:131]
	v_lshl_add_u64 v[196:197], v[68:69], 0, v[132:133]
	v_lshl_add_u64 v[198:199], v[68:69], 0, v[134:135]
	v_lshl_add_u64 v[202:203], v[68:69], 0, v[136:137]
	v_lshl_add_u64 v[208:209], v[68:69], 0, v[138:139]
	v_lshl_add_u64 v[210:211], v[68:69], 0, v[140:141]
	v_lshl_add_u64 v[212:213], v[68:69], 0, v[142:143]
	v_lshl_add_u64 v[214:215], v[68:69], 0, v[144:145]
	v_lshl_add_u64 v[216:217], v[68:69], 0, v[146:147]
	v_lshl_add_u64 v[218:219], v[68:69], 0, v[148:149]
	v_lshl_add_u64 v[68:69], v[68:69], 0, v[150:151]
	global_load_dword v153, v[156:157], off offset:320
	global_load_dword v163, v[156:157], off offset:832
	s_nop 0
	global_load_dword v72, v[72:73], off
	s_nop 0
	global_load_dword v73, v[160:161], off
	s_nop 0
	global_load_dword v74, v[74:75], off
	s_nop 0
	global_load_dword v70, v[70:71], off
	s_nop 0
	global_load_dword v71, v[156:157], off offset:576
	global_load_dword v75, v[156:157], off offset:64
	global_load_dword v160, v[166:167], off
	global_load_dword v161, v[170:171], off
	s_nop 0
	global_load_dword v166, v[174:175], off
	global_load_dword v167, v[182:183], off
	global_load_dword v170, v[180:181], off
	global_load_dword v171, v[172:173], off
	s_nop 0
	global_load_dword v168, v[168:169], off
	s_nop 0
	global_load_dword v164, v[164:165], off
	s_nop 0
	global_load_dword v165, v[186:187], off
	global_load_dword v169, v[190:191], off
	global_load_dword v172, v[194:195], off
	global_load_dword v173, v[198:199], off
	global_load_dword v174, v[196:197], off
	global_load_dword v175, v[192:193], off
	global_load_dword v180, v[188:189], off
	global_load_dword v181, v[184:185], off
	global_load_dword v182, v[208:209], off
	global_load_dword v183, v[212:213], off
	s_nop 0
	global_load_dword v184, v[216:217], off
	global_load_dword v185, v[68:69], off
	global_load_dword v186, v[218:219], off
	global_load_dword v187, v[214:215], off
	global_load_dword v188, v[210:211], off
	global_load_dword v189, v[202:203], off
	s_waitcnt vmcnt(24)
	v_cvt_pk_bf16_f32 v68, v75, v153
	v_cvt_pk_bf16_f32 v69, v71, v163
	v_cvt_pk_bf16_f32 v70, v70, v72
	v_cvt_pk_bf16_f32 v71, v74, v73
	s_waitcnt vmcnt(16)
	v_cvt_pk_bf16_f32 v72, v164, v160
	v_cvt_pk_bf16_f32 v73, v168, v161
	v_cvt_pk_bf16_f32 v74, v171, v166
	v_cvt_pk_bf16_f32 v75, v170, v167
	v_mfma_f32_16x16x32_bf16 v[68:71], v[68:71], v[76:79], 0
	v_mfma_f32_16x16x32_bf16 v[68:71], v[72:75], v[80:83], v[68:71]
	s_waitcnt vmcnt(8)
	v_cvt_pk_bf16_f32 v72, v181, v165
	v_cvt_pk_bf16_f32 v73, v180, v169
	v_cvt_pk_bf16_f32 v74, v175, v172
	v_cvt_pk_bf16_f32 v75, v174, v173
	s_nop 0
	v_mfma_f32_16x16x32_bf16 v[68:71], v[72:75], v[84:87], v[68:71]
	s_waitcnt vmcnt(0)
	v_cvt_pk_bf16_f32 v72, v189, v182
	v_cvt_pk_bf16_f32 v73, v188, v183
	v_cvt_pk_bf16_f32 v74, v187, v184
	v_cvt_pk_bf16_f32 v75, v186, v185
	s_nop 0
	v_mfma_f32_16x16x32_bf16 v[68:71], v[72:75], v[88:91], v[68:71]
	s_mov_b64 s[0:1], 0x80
	v_lshl_add_u64 v[72:73], v[158:159], 0, s[0:1]
	v_lshl_add_u64 v[74:75], v[72:73], 0, v[96:97]
	v_lshl_add_u64 v[160:161], v[72:73], 0, v[98:99]
	v_lshl_add_u64 v[164:165], v[72:73], 0, v[100:101]
	v_lshl_add_u64 v[166:167], v[72:73], 0, v[102:103]
	v_lshl_add_u64 v[168:169], v[72:73], 0, v[104:105]
	v_lshl_add_u64 v[170:171], v[72:73], 0, v[106:107]
	v_lshl_add_u64 v[172:173], v[72:73], 0, v[108:109]
	v_lshl_add_u64 v[174:175], v[72:73], 0, v[110:111]
	v_lshl_add_u64 v[180:181], v[72:73], 0, v[112:113]
	v_lshl_add_u64 v[182:183], v[72:73], 0, v[114:115]
	v_lshl_add_u64 v[184:185], v[72:73], 0, v[116:117]
	v_lshl_add_u64 v[186:187], v[72:73], 0, v[118:119]
	v_lshl_add_u64 v[188:189], v[72:73], 0, v[120:121]
	v_lshl_add_u64 v[190:191], v[72:73], 0, v[122:123]
	v_lshl_add_u64 v[192:193], v[72:73], 0, v[124:125]
	v_lshl_add_u64 v[194:195], v[72:73], 0, v[126:127]
	v_lshl_add_u64 v[196:197], v[72:73], 0, v[128:129]
	v_lshl_add_u64 v[198:199], v[72:73], 0, v[130:131]
	v_lshl_add_u64 v[202:203], v[72:73], 0, v[132:133]
	v_lshl_add_u64 v[208:209], v[72:73], 0, v[134:135]
	v_lshl_add_u64 v[210:211], v[72:73], 0, v[136:137]
	v_lshl_add_u64 v[212:213], v[72:73], 0, v[138:139]
	v_lshl_add_u64 v[214:215], v[72:73], 0, v[140:141]
	v_lshl_add_u64 v[216:217], v[72:73], 0, v[142:143]
	v_lshl_add_u64 v[218:219], v[72:73], 0, v[144:145]
	v_lshl_add_u64 v[220:221], v[72:73], 0, v[146:147]
	v_lshl_add_u64 v[222:223], v[72:73], 0, v[148:149]
	v_lshl_add_u64 v[72:73], v[72:73], 0, v[150:151]
	global_load_dword v153, v[156:157], off offset:384
	global_load_dword v163, v[156:157], off offset:896
	s_nop 0
	global_load_dword v160, v[160:161], off
	s_nop 0
	global_load_dword v161, v[166:167], off
	s_nop 0
	global_load_dword v164, v[164:165], off
	s_nop 0
	global_load_dword v74, v[74:75], off
	s_nop 0
	global_load_dword v75, v[156:157], off offset:640
	global_load_dword v165, v[156:157], off offset:128
	global_load_dword v166, v[170:171], off
	global_load_dword v167, v[174:175], off
	s_nop 0
	global_load_dword v170, v[182:183], off
	global_load_dword v171, v[186:187], off
	global_load_dword v174, v[184:185], off
	global_load_dword v175, v[180:181], off
	s_nop 0
	global_load_dword v172, v[172:173], off
	s_nop 0
	global_load_dword v168, v[168:169], off
	s_nop 0
	global_load_dword v169, v[190:191], off
	global_load_dword v173, v[194:195], off
	global_load_dword v180, v[198:199], off
	global_load_dword v181, v[208:209], off
	global_load_dword v182, v[202:203], off
	global_load_dword v183, v[196:197], off
	global_load_dword v184, v[192:193], off
	global_load_dword v185, v[188:189], off
	global_load_dword v186, v[212:213], off
	global_load_dword v187, v[216:217], off
	s_nop 0
	global_load_dword v188, v[220:221], off
	global_load_dword v189, v[72:73], off
	global_load_dword v190, v[222:223], off
	global_load_dword v191, v[218:219], off
	global_load_dword v192, v[214:215], off
	global_load_dword v193, v[210:211], off
	s_waitcnt vmcnt(24)
	v_cvt_pk_bf16_f32 v72, v165, v153
	v_cvt_pk_bf16_f32 v73, v75, v163
	v_cvt_pk_bf16_f32 v74, v74, v160
	v_cvt_pk_bf16_f32 v75, v164, v161
	s_waitcnt vmcnt(16)
	v_cvt_pk_bf16_f32 v164, v168, v166
	v_cvt_pk_bf16_f32 v165, v172, v167
	v_cvt_pk_bf16_f32 v166, v175, v170
	v_cvt_pk_bf16_f32 v167, v174, v171
	v_mfma_f32_16x16x32_bf16 v[72:75], v[72:75], v[76:79], 0
	v_mfma_f32_16x16x32_bf16 v[72:75], v[164:167], v[80:83], v[72:75]
	s_waitcnt vmcnt(8)
	v_cvt_pk_bf16_f32 v164, v185, v169
	v_cvt_pk_bf16_f32 v165, v184, v173
	v_cvt_pk_bf16_f32 v166, v183, v180
	v_cvt_pk_bf16_f32 v167, v182, v181
	s_nop 0
	v_mfma_f32_16x16x32_bf16 v[72:75], v[164:167], v[84:87], v[72:75]
	s_waitcnt vmcnt(0)
	v_cvt_pk_bf16_f32 v164, v193, v186
	v_cvt_pk_bf16_f32 v165, v192, v187
	v_cvt_pk_bf16_f32 v166, v191, v188
	v_cvt_pk_bf16_f32 v167, v190, v189
	s_nop 0
	v_mfma_f32_16x16x32_bf16 v[72:75], v[164:167], v[88:91], v[72:75]
	s_mov_b64 s[0:1], 0xc0
	v_lshl_add_u64 v[158:159], v[158:159], 0, s[0:1]
	v_lshl_add_u64 v[160:161], v[158:159], 0, v[96:97]
	v_lshl_add_u64 v[164:165], v[158:159], 0, v[98:99]
	v_lshl_add_u64 v[166:167], v[158:159], 0, v[100:101]
	v_lshl_add_u64 v[168:169], v[158:159], 0, v[102:103]
	v_lshl_add_u64 v[170:171], v[158:159], 0, v[104:105]
	v_lshl_add_u64 v[172:173], v[158:159], 0, v[106:107]
	v_lshl_add_u64 v[174:175], v[158:159], 0, v[108:109]
	v_lshl_add_u64 v[180:181], v[158:159], 0, v[110:111]
	v_lshl_add_u64 v[182:183], v[158:159], 0, v[112:113]
	v_lshl_add_u64 v[184:185], v[158:159], 0, v[114:115]
	v_lshl_add_u64 v[186:187], v[158:159], 0, v[116:117]
	v_lshl_add_u64 v[188:189], v[158:159], 0, v[118:119]
	v_lshl_add_u64 v[190:191], v[158:159], 0, v[120:121]
	v_lshl_add_u64 v[192:193], v[158:159], 0, v[122:123]
	v_lshl_add_u64 v[194:195], v[158:159], 0, v[124:125]
	v_lshl_add_u64 v[196:197], v[158:159], 0, v[126:127]
	v_lshl_add_u64 v[198:199], v[158:159], 0, v[128:129]
	v_lshl_add_u64 v[202:203], v[158:159], 0, v[130:131]
	v_lshl_add_u64 v[208:209], v[158:159], 0, v[132:133]
	v_lshl_add_u64 v[210:211], v[158:159], 0, v[134:135]
	v_lshl_add_u64 v[212:213], v[158:159], 0, v[136:137]
	v_lshl_add_u64 v[214:215], v[158:159], 0, v[138:139]
	v_lshl_add_u64 v[216:217], v[158:159], 0, v[140:141]
	v_lshl_add_u64 v[218:219], v[158:159], 0, v[142:143]
	v_lshl_add_u64 v[220:221], v[158:159], 0, v[144:145]
	v_lshl_add_u64 v[222:223], v[158:159], 0, v[146:147]
	v_lshl_add_u64 v[224:225], v[158:159], 0, v[148:149]
	v_lshl_add_u64 v[158:159], v[158:159], 0, v[150:151]
	global_load_dword v153, v[156:157], off offset:448
	global_load_dword v163, v[156:157], off offset:960
	s_nop 0
	global_load_dword v164, v[164:165], off
	s_nop 0
	global_load_dword v165, v[168:169], off
	s_nop 0
	global_load_dword v166, v[166:167], off
	s_nop 0
	global_load_dword v160, v[160:161], off
	s_nop 0
	global_load_dword v161, v[156:157], off offset:704
	s_nop 0
	global_load_dword v156, v[156:157], off offset:192
	s_nop 0
	global_load_dword v167, v[172:173], off
	global_load_dword v168, v[180:181], off
	global_load_dword v169, v[184:185], off
	s_nop 0
	global_load_dword v172, v[188:189], off
	global_load_dword v173, v[186:187], off
	global_load_dword v180, v[182:183], off
	s_nop 0
	global_load_dword v174, v[174:175], off
	s_nop 0
	global_load_dword v170, v[170:171], off
	s_nop 0
	global_load_dword v171, v[192:193], off
	global_load_dword v175, v[196:197], off
	global_load_dword v181, v[202:203], off
	global_load_dword v182, v[210:211], off
	global_load_dword v183, v[208:209], off
	global_load_dword v184, v[198:199], off
	global_load_dword v185, v[194:195], off
	global_load_dword v186, v[190:191], off
	global_load_dword v187, v[214:215], off
	global_load_dword v188, v[218:219], off
	global_load_dword v189, v[222:223], off
	s_nop 0
	global_load_dword v190, v[158:159], off
	global_load_dword v191, v[224:225], off
	global_load_dword v192, v[220:221], off
	global_load_dword v193, v[216:217], off
	global_load_dword v194, v[212:213], off
	s_waitcnt vmcnt(24)
	v_cvt_pk_bf16_f32 v156, v156, v153
	v_cvt_pk_bf16_f32 v157, v161, v163
	v_cvt_pk_bf16_f32 v158, v160, v164
	v_cvt_pk_bf16_f32 v159, v166, v165
	s_nop 0
	v_mfma_f32_16x16x32_bf16 v[76:79], v[156:159], v[76:79], 0
	s_waitcnt vmcnt(16)
	v_cvt_pk_bf16_f32 v156, v170, v167
	v_cvt_pk_bf16_f32 v157, v174, v168
	v_cvt_pk_bf16_f32 v158, v180, v169
	v_cvt_pk_bf16_f32 v159, v173, v172
	s_nop 0
	v_mfma_f32_16x16x32_bf16 v[76:79], v[156:159], v[80:83], v[76:79]
	s_waitcnt vmcnt(8)
	v_cvt_pk_bf16_f32 v80, v186, v171
	v_cvt_pk_bf16_f32 v81, v185, v175
	v_cvt_pk_bf16_f32 v82, v184, v181
	v_cvt_pk_bf16_f32 v83, v183, v182
	s_nop 0
	v_mfma_f32_16x16x32_bf16 v[76:79], v[80:83], v[84:87], v[76:79]
	s_waitcnt vmcnt(0)
	v_cvt_pk_bf16_f32 v80, v194, v187
	v_cvt_pk_bf16_f32 v81, v193, v188
	v_cvt_pk_bf16_f32 v82, v192, v189
	v_cvt_pk_bf16_f32 v83, v191, v190
	s_nop 0
	v_mfma_f32_16x16x32_bf16 v[76:79], v[80:83], v[88:91], v[76:79]
	v_mul_f32_e64 v80, v94, v94
	v_mul_f32_e64 v81, v95, v95
	v_pk_mul_f32 v[82:83], v[92:93], v[92:93]
	s_mov_b32 s0, 0x800000
	v_pk_mov_b32 v[84:85], v[82:83], v[80:81] op_sel:[1,0]
	v_mov_b32_e32 v83, v81
	v_pk_add_f32 v[80:81], v[84:85], v[82:83]
	v_pk_mul_f32 v[82:83], v[70:71], v[70:71]
	v_pk_mul_f32 v[84:85], v[68:69], v[68:69]
	v_pk_add_f32 v[80:81], v[80:81], v[80:81] op_sel:[0,1] op_sel_hi:[1,0]
	v_pk_mov_b32 v[86:87], v[84:85], v[82:83] op_sel:[1,0]
	v_mov_b32_e32 v85, v83
	v_pk_add_f32 v[82:83], v[86:87], v[84:85]
	v_mul_f32_e32 v84, v76, v76
	v_mul_f32_e32 v85, v77, v77
	v_pk_add_f32 v[82:83], v[82:83], v[82:83] op_sel:[0,1] op_sel_hi:[1,0]
	v_mov_b32_e32 v81, v84
	v_mov_b32_e32 v83, v85
	v_pk_add_f32 v[80:81], v[80:81], v[82:83]
	v_mul_f32_e32 v82, v73, v73
	v_mul_f32_e32 v84, v75, v75
	v_mul_f32_e32 v86, v78, v78
	v_mul_f32_e32 v87, v79, v79
	v_pk_fma_f32 v[82:83], v[72:73], v[72:73], v[82:83] op_sel_hi:[1,1,0]
	v_pk_fma_f32 v[84:85], v[74:75], v[74:75], v[84:85] op_sel_hi:[1,1,0]
	v_mov_b32_e32 v83, v86
	v_mov_b32_e32 v85, v87
	v_pk_add_f32 v[82:83], v[82:83], v[84:85]
	s_nop 0
	v_pk_add_f32 v[80:81], v[80:81], v[82:83]
	v_and_b32_e32 v82, 64, v229
	v_add_f32_e32 v80, v80, v81
	v_xor_b32_e32 v81, 16, v229
	v_add_u32_e32 v82, 64, v82
	v_cmp_lt_i32_e32 vcc, v81, v82
	s_nop 1
	v_cndmask_b32_e32 v81, v229, v81, vcc
	v_lshlrev_b32_e32 v81, 2, v81
	ds_bpermute_b32 v81, v81, v80
	s_waitcnt lgkmcnt(0)
	v_add_f32_e32 v80, v80, v81
	v_xor_b32_e32 v81, 32, v229
	v_cmp_lt_i32_e32 vcc, v81, v82
	s_nop 1
	v_cndmask_b32_e32 v81, v229, v81, vcc
	v_lshlrev_b32_e32 v153, 2, v81
	ds_bpermute_b32 v81, v153, v80
	s_waitcnt lgkmcnt(0)
	v_add_f32_e32 v80, v80, v81
	v_fmamk_f32 v80, v80, 0x3c800000, v226
	v_cmp_gt_f32_e32 vcc, s0, v80
	v_mul_f32_e32 v81, 0x4b800000, v80
	s_mov_b64 s[0:1], s[8:9]
	v_cndmask_b32_e32 v80, v80, v81, vcc
	v_rsq_f32_e32 v80, v80
	s_load_dwordx2 s[0:1], s[0:1], 0x90
	v_mul_f32_e32 v81, 0x45800000, v80
	v_cndmask_b32_e32 v156, v80, v81, vcc
	s_waitcnt lgkmcnt(0)
	global_load_dwordx4 v[80:83], v152, s[0:1]
	s_mov_b64 s[0:1], s[8:9]
	s_load_dwordx2 s[0:1], s[0:1], 0x90
	v_pk_mul_f32 v[84:85], v[92:93], v[156:157] op_sel_hi:[1,0]
	v_pk_mul_f32 v[86:87], v[94:95], v[156:157] op_sel_hi:[1,0]
	v_lshl_add_u64 v[94:95], s[6:7], 0, v[154:155]
	v_lshlrev_b32_e32 v92, 2, v162
	s_waitcnt vmcnt(0)
	v_pk_mul_f32 v[90:91], v[82:83], v[86:87]
	v_pk_mul_f32 v[88:89], v[80:81], v[84:85]
	s_waitcnt lgkmcnt(0)
	global_load_dwordx4 v[80:83], v152, s[0:1] offset:64
	s_mov_b64 s[0:1], s[8:9]
	s_load_dwordx2 s[0:1], s[0:1], 0x90
	ds_bpermute_b32 v160, v153, v88
	ds_bpermute_b32 v161, v153, v89
	ds_bpermute_b32 v158, v153, v90
	ds_bpermute_b32 v159, v153, v91
	s_waitcnt lgkmcnt(0)
	global_load_dwordx4 v[84:87], v152, s[0:1] offset:128
	v_lshlrev_b32_e32 v152, 2, v176
	s_and_saveexec_b64 s[0:1], s[4:5]
	s_cbranch_execz .LBB0_567
	v_lshlrev_b32_e32 v154, 12, v1
	v_mov_b32_e32 v155, v3
	v_and_b32_e32 v93, 8, v206
	v_lshl_add_u64 v[154:155], s[6:7], 0, v[154:155]
	v_lshlrev_b32_e32 v164, 2, v93
	v_mov_b32_e32 v165, v3
	v_lshl_add_u64 v[154:155], v[154:155], 0, v[164:165]
	s_mov_b64 s[10:11], 0x900fc0
	v_lshl_add_u64 v[168:169], v[154:155], 0, s[10:11]
	v_add_co_u32_e32 v154, vcc, 0x900000, v154
	v_mov_b32_e32 v157, v156
	s_nop 0
	v_addc_co_u32_e32 v155, vcc, 0, v155, vcc
	global_load_dwordx4 v[164:167], v[154:155], off offset:4032
	s_nop 0
	global_load_dwordx4 v[168:171], v[168:169], off offset:16
	s_load_dwordx2 s[8:9], s[8:9], 0x90
	v_cmp_gt_u32_e32 vcc, 2, v205
	v_pk_mul_f32 v[72:73], v[72:73], v[156:157]
	v_pk_mul_f32 v[68:69], v[68:69], v[156:157]
	s_waitcnt vmcnt(2)
	v_pk_mul_f32 v[72:73], v[84:85], v[72:73]
	v_pk_mul_f32 v[68:69], v[80:81], v[68:69]
	v_lshlrev_b32_e32 v80, 9, v177
	v_lshlrev_b32_e32 v81, 7, v204
	v_or3_b32 v80, v80, v81, v1
	v_ashrrev_i32_e32 v81, 31, v80
	v_lshlrev_b64 v[80:81], 7, v[80:81]
	v_lshl_add_u64 v[80:81], s[6:7], 0, v[80:81]
	s_waitcnt vmcnt(1)
	v_mov_b32_e32 v154, v165
	v_mov_b32_e32 v155, v167
	v_pk_mul_f32 v[154:155], v[154:155], v[160:161]
	s_waitcnt vmcnt(0)
	v_mov_b32_e32 v160, v169
	v_mov_b32_e32 v161, v171
	v_pk_mul_f32 v[158:159], v[160:161], v[158:159]
	v_xor_b32_e32 v93, 0x80000000, v154
	v_xor_b32_e32 v153, 0x80000000, v155
	v_xor_b32_e32 v160, 0x80000000, v158
	v_xor_b32_e32 v161, 0x80000000, v159
	v_cndmask_b32_e32 v155, v155, v153, vcc
	v_cndmask_b32_e32 v154, v154, v93, vcc
	v_mov_b32_e32 v165, v166
	v_cndmask_b32_e32 v159, v159, v161, vcc
	v_cndmask_b32_e32 v158, v158, v160, vcc
	v_pk_fma_f32 v[88:89], v[88:89], v[164:165], v[154:155]
	v_mov_b32_e32 v169, v170
	v_mov_b32_e32 v154, v156
	v_mov_b32_e32 v155, v156
	v_pk_fma_f32 v[90:91], v[90:91], v[168:169], v[158:159]
	v_pk_mul_f32 v[158:159], v[78:79], v[154:155]
	v_pk_mul_f32 v[160:161], v[76:77], v[156:157]
	s_waitcnt lgkmcnt(0)
	global_load_dwordx4 v[76:79], v92, s[8:9] offset:192
	v_pk_mul_f32 v[70:71], v[70:71], v[154:155]
	v_mov_b32_e32 v153, v3
	v_mov_b32_e32 v93, v3
	v_pk_mul_f32 v[70:71], v[82:83], v[70:71]
	v_lshl_add_u64 v[82:83], v[94:95], 0, v[152:153]
	v_lshl_add_u64 v[82:83], v[82:83], 0, v[92:93]
	s_mov_b64 s[8:9], 0x2a900000
	v_lshl_add_u64 v[84:85], v[82:83], 0, s[8:9]
	s_mov_b32 s8, 0x2a900000
	v_add_co_u32_e32 v82, vcc, s8, v82
	v_pk_mul_f32 v[74:75], v[74:75], v[154:155]
	s_nop 0
	v_addc_co_u32_e32 v83, vcc, 0, v83, vcc
	v_pk_mul_f32 v[74:75], v[86:87], v[74:75]
	s_mov_b64 s[8:9], 0x2b500000
	v_bfe_u32 v86, v91, 16, 1
	v_add3_u32 v86, v91, v86, s96
	s_waitcnt vmcnt(0)
	v_pk_mul_f32 v[78:79], v[158:159], v[78:79]
	v_pk_mul_f32 v[76:77], v[160:161], v[76:77]
	global_store_dwordx4 v[82:83], v[88:91], off
	global_store_dwordx4 v[84:85], v[68:71], off offset:64
	global_store_dwordx4 v[84:85], v[72:75], off offset:128
	global_store_dwordx4 v[84:85], v[76:79], off offset:192
	v_bfe_u32 v84, v88, 16, 1
	v_add3_u32 v84, v88, v84, s96
	v_bfe_u32 v85, v89, 16, 1
	v_lshlrev_b32_e32 v82, 1, v162
	v_mov_b32_e32 v83, v3
	v_lshrrev_b32_e32 v84, 16, v84
	v_add3_u32 v85, v89, v85, s96
	v_lshl_add_u64 v[82:83], v[80:81], 0, v[82:83]
	v_and_or_b32 v84, v85, s97, v84
	v_bfe_u32 v85, v90, 16, 1
	v_lshl_add_u64 v[80:81], v[82:83], 0, s[8:9]
	v_add3_u32 v85, v90, v85, s96
	s_mov_b32 s8, 0x2b500000
	v_lshrrev_b32_e32 v85, 16, v85
	v_add_co_u32_e32 v82, vcc, s8, v82
	v_and_or_b32 v85, v86, s97, v85
	s_nop 0
	v_addc_co_u32_e32 v83, vcc, 0, v83, vcc
	global_store_dwordx2 v[82:83], v[84:85], off
	v_bfe_u32 v82, v68, 16, 1
	v_add3_u32 v68, v68, v82, s96
	v_bfe_u32 v82, v69, 16, 1
	v_lshrrev_b32_e32 v68, 16, v68
	v_add3_u32 v69, v69, v82, s96
	v_and_or_b32 v68, v69, s97, v68
	v_bfe_u32 v69, v70, 16, 1
	v_add3_u32 v69, v70, v69, s96
	v_bfe_u32 v70, v71, 16, 1
	v_lshrrev_b32_e32 v69, 16, v69
	v_add3_u32 v70, v71, v70, s96
	v_and_or_b32 v69, v70, s97, v69
	global_store_dwordx2 v[80:81], v[68:69], off offset:32
	v_bfe_u32 v68, v72, 16, 1
	v_add3_u32 v68, v72, v68, s96
	v_bfe_u32 v69, v73, 16, 1
	v_lshrrev_b32_e32 v68, 16, v68
	v_add3_u32 v69, v73, v69, s96
	v_and_or_b32 v68, v69, s97, v68
	v_bfe_u32 v69, v74, 16, 1
	v_add3_u32 v69, v74, v69, s96
	v_bfe_u32 v70, v75, 16, 1
	v_lshrrev_b32_e32 v69, 16, v69
	v_add3_u32 v70, v75, v70, s96
	v_and_or_b32 v69, v70, s97, v69
	global_store_dwordx2 v[80:81], v[68:69], off offset:64
	v_bfe_u32 v68, v76, 16, 1
	v_add3_u32 v68, v76, v68, s96
	v_bfe_u32 v69, v77, 16, 1
	v_lshrrev_b32_e32 v68, 16, v68
	v_add3_u32 v69, v77, v69, s96
	v_and_or_b32 v68, v69, s97, v68
	v_bfe_u32 v69, v78, 16, 1
	v_add3_u32 v69, v78, v69, s96
	v_bfe_u32 v70, v79, 16, 1
	v_lshrrev_b32_e32 v69, 16, v69
	v_add3_u32 v70, v79, v70, s96
	v_and_or_b32 v69, v70, s97, v69
	global_store_dwordx2 v[80:81], v[68:69], off offset:96
